# sc1 write-through on EpiResid and EpiWin output stores so the grid barrier's L2 writeback has nothing left to flush
# baseline (speedup 1.0000x reference)
;     __device__ __forceinline__ void operator()(const f32x4 (&acc)[2][2][4][2], const pg8::Unit& u, int wr, int wc, int fr_, int fq_, int tid) {
;     ...
;         for (int g = 0; g < 8; ++g) {
;             const int ai = g >> 2, m = g & 3;
;             if (g < 7) ER_LD(nxt, g + 1);
;             const size_t off = base + (size_t)(ai * 128 + m * 16) * DM; float s = 0.f;
; #pragma unroll
;             for (int bj = 0; bj < 2; ++bj) {
;                 const f32x4 n0 = cur[2 * bj] + acc[ai][bj][m][0] * alpha, n1 = cur[2 * bj + 1] + acc[ai][bj][m][1] * alpha;
;                 const u32x4 w = pack8bf(n0, n1);
;                 *(u32x4*)(xb + off + bj * 128) = w;
;                 float q[8]; unpack8(w, q);
;                 s += ((q[0] * q[0] + q[1] * q[1]) + (q[2] * q[2] + q[3] * q[3])) + ((q[4] * q[4] + q[5] * q[5]) + (q[6] * q[6] + q[7] * q[7]));
;             }
;             s += __shfl_xor(s, 16); s += __shfl_xor(s, 32);
;             if (fq == 0) ssq[(size_t)(row0 + ai * 128 + m * 16) * 32 + u.pn * 4 + wc] = s;
.LBB0_257:
	s_waitcnt vmcnt(0)
	v_pk_fma_f32 v[128:129], v[128:129], 0.5, v[160:161] op_sel_hi:[1,0,1]
	v_pk_fma_f32 v[126:127], v[126:127], 0.5, v[158:159] op_sel_hi:[1,0,1]
	v_pk_fma_f32 v[156:157], v[124:125], 0.5, v[156:157] op_sel_hi:[1,0,1]
	v_pk_fma_f32 v[124:125], v[122:123], 0.5, v[154:155] op_sel_hi:[1,0,1]
	v_cvt_pk_bf16_f32 v122, v126, v127
	v_cvt_pk_bf16_f32 v123, v128, v129
	v_pk_fma_f32 v[118:119], v[118:119], 0.5, v[150:151] op_sel_hi:[1,0,1]
	v_cvt_pk_bf16_f32 v124, v124, v125
	v_cvt_pk_bf16_f32 v125, v156, v157
	global_store_dwordx4 v[184:185], v[122:125], off sc1
	v_lshlrev_b32_e32 v126, 16, v122
	v_lshlrev_b32_e32 v127, 16, v123
	v_and_b32_e32 v122, 0xffff0000, v122
	v_and_b32_e32 v123, 0xffff0000, v123
	v_mul_f32_e32 v122, v122, v122
	v_mul_f32_e32 v123, v123, v123
	v_lshlrev_b32_e32 v128, 16, v124
	v_and_b32_e32 v124, 0xffff0000, v124
	v_lshlrev_b32_e32 v129, 16, v125
	v_and_b32_e32 v125, 0xffff0000, v125
	v_fmac_f32_e32 v122, v126, v126
	v_fmac_f32_e32 v123, v127, v127
	v_add_f32_e32 v122, v122, v123
	v_mul_f32_e32 v123, v124, v124
	v_mul_f32_e32 v124, v125, v125
	v_fmac_f32_e32 v123, v128, v128
	v_fmac_f32_e32 v124, v129, v129
	v_add_f32_e32 v123, v123, v124
	v_pk_fma_f32 v[114:115], v[114:115], 0.5, v[146:147] op_sel_hi:[1,0,1]
	v_add_f32_e32 v124, v122, v123
	v_pk_fma_f32 v[120:121], v[120:121], 0.5, v[152:153] op_sel_hi:[1,0,1]
	v_pk_fma_f32 v[122:123], v[116:117], 0.5, v[148:149] op_sel_hi:[1,0,1]
	v_cvt_pk_bf16_f32 v116, v118, v119
	v_cvt_pk_bf16_f32 v117, v120, v121
	v_cvt_pk_bf16_f32 v118, v114, v115
	v_cmp_lt_i32_e32 vcc, v203, v198
	v_and_b32_e32 v115, 0xffff0000, v116
	v_lshlrev_b32_e32 v114, 16, v116
	v_and_b32_e32 v121, 0xffff0000, v117
	v_mul_f32_e32 v115, v115, v115
	v_lshlrev_b32_e32 v120, 16, v117
	v_fmac_f32_e32 v115, v114, v114
	v_mul_f32_e32 v114, v121, v121
	v_cvt_pk_bf16_f32 v119, v122, v123
	v_and_b32_e32 v123, 0xffff0000, v118
	v_and_b32_e32 v126, 0xffff0000, v119
	v_fmac_f32_e32 v114, v120, v120
	v_lshlrev_b32_e32 v122, 16, v118
	v_lshlrev_b32_e32 v125, 16, v119
	v_add_f32_e32 v114, v115, v114
	v_mul_f32_e32 v115, v123, v123
	v_mul_f32_e32 v120, v126, v126
	v_fmac_f32_e32 v115, v122, v122
	v_fmac_f32_e32 v120, v125, v125
	v_add_f32_e32 v115, v115, v120
	v_add_f32_e32 v114, v114, v115
	v_cndmask_b32_e32 v115, v195, v203, vcc
	v_add_f32_e32 v114, v124, v114
	v_lshlrev_b32_e32 v148, 2, v115
	ds_bpermute_b32 v115, v148, v114
	v_cmp_lt_i32_e32 vcc, v204, v198
	s_lshl_b32 s24, s51, 2
	global_store_dwordx4 v[184:185], v[116:119], off offset:256 sc1
	v_cmp_eq_u32_e64 s[6:7], 0, v218
	s_waitcnt lgkmcnt(0)
	v_add_f32_e32 v114, v114, v115
	v_cndmask_b32_e32 v115, v195, v204, vcc
	v_lshlrev_b32_e32 v149, 2, v115
	ds_bpermute_b32 v115, v149, v114
	v_lshlrev_b64 v[116:117], 7, v[188:189]
	s_ashr_i32 s25, s24, 31
	v_lshl_add_u64 v[146:147], s[14:15], 0, v[116:117]
	s_and_saveexec_b64 s[26:27], s[6:7]
	s_cbranch_execz .LBB0_259
	v_lshl_add_u64 v[116:117], s[24:25], 2, v[146:147]
	s_lshl_b32 s96, s41, 2
	v_lshl_add_u64 v[116:117], v[116:117], 0, s[96:97]
	s_waitcnt lgkmcnt(0)
	v_add_f32_e32 v114, v114, v115
	global_store_dword v[116:117], v114, off sc1

;     __device__ __forceinline__ void operator()(const f32x4 (&acc)[2][2][4][2], const pg8::Unit& u, int wr, int wc, int fr_, int fq_, int tid) {
;     ...
;         for (int g = 0; g < 8; ++g) {
;             const int ai = g >> 2, m = g & 3;
;             if (g < 7) ER_LD(nxt, g + 1);
;             const size_t off = base + (size_t)(ai * 128 + m * 16) * DM; float s = 0.f;
; #pragma unroll
;             for (int bj = 0; bj < 2; ++bj) {
;                 const f32x4 n0 = cur[2 * bj] + acc[ai][bj][m][0] * alpha, n1 = cur[2 * bj + 1] + acc[ai][bj][m][1] * alpha;
;                 const u32x4 w = pack8bf(n0, n1);
;                 *(u32x4*)(xb + off + bj * 128) = w;
;                 float q[8]; unpack8(w, q);
;                 s += ((q[0] * q[0] + q[1] * q[1]) + (q[2] * q[2] + q[3] * q[3])) + ((q[4] * q[4] + q[5] * q[5]) + (q[6] * q[6] + q[7] * q[7]));
;             }
;             s += __shfl_xor(s, 16); s += __shfl_xor(s, 32);
;             if (fq == 0) ssq[(size_t)(row0 + ai * 128 + m * 16) * 32 + u.pn * 4 + wc] = s;
.LBB0_262:
	v_pk_fma_f32 v[110:111], v[110:111], 0.5, v[142:143] op_sel_hi:[1,0,1]
	v_pk_fma_f32 v[140:141], v[108:109], 0.5, v[140:141] op_sel_hi:[1,0,1]
	v_pk_fma_f32 v[108:109], v[106:107], 0.5, v[138:139] op_sel_hi:[1,0,1]
	v_cvt_pk_bf16_f32 v106, v110, v111
	v_add_co_u32_e32 v110, vcc, s86, v184
	v_pk_fma_f32 v[112:113], v[112:113], 0.5, v[144:145] op_sel_hi:[1,0,1]
	s_nop 0
	v_addc_co_u32_e32 v111, vcc, 0, v185, vcc
	v_cvt_pk_bf16_f32 v107, v112, v113
	v_cvt_pk_bf16_f32 v108, v108, v109
	v_cvt_pk_bf16_f32 v109, v140, v141
	global_store_dwordx4 v[110:111], v[106:109], off sc1
	v_lshlrev_b32_e32 v112, 16, v106
	v_lshlrev_b32_e32 v113, 16, v107
	v_and_b32_e32 v106, 0xffff0000, v106
	v_and_b32_e32 v107, 0xffff0000, v107
	v_mul_f32_e32 v106, v106, v106
	v_mul_f32_e32 v107, v107, v107
	v_lshlrev_b32_e32 v138, 16, v108
	v_and_b32_e32 v108, 0xffff0000, v108
	v_lshlrev_b32_e32 v139, 16, v109
	v_and_b32_e32 v109, 0xffff0000, v109
	v_fmac_f32_e32 v106, v112, v112
	v_fmac_f32_e32 v107, v113, v113
	v_add_f32_e32 v106, v106, v107
	v_mul_f32_e32 v107, v108, v108
	v_mul_f32_e32 v108, v109, v109
	v_fmac_f32_e32 v107, v138, v138
	v_fmac_f32_e32 v108, v139, v139
	v_add_f32_e32 v107, v107, v108
	v_pk_fma_f32 v[102:103], v[102:103], 0.5, v[134:135] op_sel_hi:[1,0,1]
	v_pk_fma_f32 v[98:99], v[98:99], 0.5, v[130:131] op_sel_hi:[1,0,1]
	v_add_f32_e32 v108, v106, v107
	v_pk_fma_f32 v[104:105], v[104:105], 0.5, v[136:137] op_sel_hi:[1,0,1]
	v_pk_fma_f32 v[106:107], v[100:101], 0.5, v[132:133] op_sel_hi:[1,0,1]
	v_cvt_pk_bf16_f32 v100, v102, v103
	v_cvt_pk_bf16_f32 v101, v104, v105
	v_cvt_pk_bf16_f32 v102, v98, v99
	s_nop 0
	v_and_b32_e32 v99, 0xffff0000, v100
	v_lshlrev_b32_e32 v98, 16, v100
	v_and_b32_e32 v105, 0xffff0000, v101
	v_mul_f32_e32 v99, v99, v99
	v_lshlrev_b32_e32 v104, 16, v101
	v_fmac_f32_e32 v99, v98, v98
	v_mul_f32_e32 v98, v105, v105
	v_cvt_pk_bf16_f32 v103, v106, v107
	v_and_b32_e32 v107, 0xffff0000, v102
	v_and_b32_e32 v112, 0xffff0000, v103
	v_fmac_f32_e32 v98, v104, v104
	v_lshlrev_b32_e32 v106, 16, v102
	v_lshlrev_b32_e32 v109, 16, v103
	v_add_f32_e32 v98, v99, v98
	v_mul_f32_e32 v99, v107, v107
	v_mul_f32_e32 v104, v112, v112
	v_fmac_f32_e32 v99, v106, v106
	v_fmac_f32_e32 v104, v109, v109
	v_add_f32_e32 v99, v99, v104
	v_add_f32_e32 v98, v98, v99
	v_add_f32_e32 v98, v108, v98
	ds_bpermute_b32 v99, v148, v98
	global_store_dwordx4 v[110:111], v[100:103], off offset:256 sc1
	s_waitcnt lgkmcnt(0)
	v_add_f32_e32 v98, v98, v99
	ds_bpermute_b32 v99, v149, v98
	s_and_saveexec_b64 s[26:27], s[6:7]
	s_cbranch_execz .LBB0_264
	s_waitcnt lgkmcnt(0)
	v_add_f32_e32 v100, v98, v99
	v_lshl_add_u64 v[98:99], s[24:25], 2, v[146:147]
	s_lshl_b32 s96, s41, 2
	v_lshl_add_u64 v[98:99], v[98:99], 0, s[96:97]
	global_store_dword v[98:99], v100, off offset:2048 sc1

;     __device__ __forceinline__ void operator()(const f32x4 (&acc)[2][2][4][2], const pg8::Unit& u, int wr, int wc, int fr_, int fq_, int tid) {
;     ...
;         for (int g = 0; g < 8; ++g) {
;             const int ai = g >> 2, m = g & 3;
;             if (g < 7) ER_LD(nxt, g + 1);
;             const size_t off = base + (size_t)(ai * 128 + m * 16) * DM; float s = 0.f;
; #pragma unroll
;             for (int bj = 0; bj < 2; ++bj) {
;                 const f32x4 n0 = cur[2 * bj] + acc[ai][bj][m][0] * alpha, n1 = cur[2 * bj + 1] + acc[ai][bj][m][1] * alpha;
;                 const u32x4 w = pack8bf(n0, n1);
;                 *(u32x4*)(xb + off + bj * 128) = w;
;                 float q[8]; unpack8(w, q);
;                 s += ((q[0] * q[0] + q[1] * q[1]) + (q[2] * q[2] + q[3] * q[3])) + ((q[4] * q[4] + q[5] * q[5]) + (q[6] * q[6] + q[7] * q[7]));
;             }
;             s += __shfl_xor(s, 16); s += __shfl_xor(s, 32);
;             if (fq == 0) ssq[(size_t)(row0 + ai * 128 + m * 16) * 32 + u.pn * 4 + wc] = s;
.LBB0_267:
	s_waitcnt vmcnt(3)
	v_pk_fma_f32 v[94:95], v[94:95], 0.5, v[126:127] op_sel_hi:[1,0,1]
	v_pk_fma_f32 v[124:125], v[92:93], 0.5, v[124:125] op_sel_hi:[1,0,1]
	v_pk_fma_f32 v[92:93], v[90:91], 0.5, v[122:123] op_sel_hi:[1,0,1]
	v_cvt_pk_bf16_f32 v90, v94, v95
	v_add_co_u32_e32 v94, vcc, s89, v184
	v_pk_fma_f32 v[96:97], v[96:97], 0.5, v[128:129] op_sel_hi:[1,0,1]
	s_nop 0
	v_addc_co_u32_e32 v95, vcc, 0, v185, vcc
	v_cvt_pk_bf16_f32 v91, v96, v97
	v_cvt_pk_bf16_f32 v92, v92, v93
	v_cvt_pk_bf16_f32 v93, v124, v125
	global_store_dwordx4 v[94:95], v[90:93], off sc1
	v_lshlrev_b32_e32 v96, 16, v90
	v_lshlrev_b32_e32 v97, 16, v91
	v_and_b32_e32 v90, 0xffff0000, v90
	v_and_b32_e32 v91, 0xffff0000, v91
	v_mul_f32_e32 v90, v90, v90
	v_mul_f32_e32 v91, v91, v91
	v_lshlrev_b32_e32 v122, 16, v92
	v_and_b32_e32 v92, 0xffff0000, v92
	v_lshlrev_b32_e32 v123, 16, v93
	v_and_b32_e32 v93, 0xffff0000, v93
	v_fmac_f32_e32 v90, v96, v96
	v_fmac_f32_e32 v91, v97, v97
	v_add_f32_e32 v90, v90, v91
	v_mul_f32_e32 v91, v92, v92
	v_mul_f32_e32 v92, v93, v93
	v_fmac_f32_e32 v91, v122, v122
	v_fmac_f32_e32 v92, v123, v123
	v_add_f32_e32 v91, v91, v92
	v_pk_fma_f32 v[86:87], v[86:87], 0.5, v[118:119] op_sel_hi:[1,0,1]
	s_waitcnt vmcnt(3)
	v_pk_fma_f32 v[82:83], v[82:83], 0.5, v[114:115] op_sel_hi:[1,0,1]
	v_add_f32_e32 v92, v90, v91
	v_pk_fma_f32 v[88:89], v[88:89], 0.5, v[120:121] op_sel_hi:[1,0,1]
	v_pk_fma_f32 v[90:91], v[84:85], 0.5, v[116:117] op_sel_hi:[1,0,1]
	v_cvt_pk_bf16_f32 v84, v86, v87
	v_cvt_pk_bf16_f32 v85, v88, v89
	v_cvt_pk_bf16_f32 v86, v82, v83
	s_nop 0
	v_and_b32_e32 v83, 0xffff0000, v84
	v_lshlrev_b32_e32 v82, 16, v84
	v_and_b32_e32 v89, 0xffff0000, v85
	v_mul_f32_e32 v83, v83, v83
	v_lshlrev_b32_e32 v88, 16, v85
	v_fmac_f32_e32 v83, v82, v82
	v_mul_f32_e32 v82, v89, v89
	v_cvt_pk_bf16_f32 v87, v90, v91
	v_and_b32_e32 v91, 0xffff0000, v86
	v_and_b32_e32 v96, 0xffff0000, v87
	v_fmac_f32_e32 v82, v88, v88
	v_lshlrev_b32_e32 v90, 16, v86
	v_lshlrev_b32_e32 v93, 16, v87
	v_add_f32_e32 v82, v83, v82
	v_mul_f32_e32 v83, v91, v91
	v_mul_f32_e32 v88, v96, v96
	v_fmac_f32_e32 v83, v90, v90
	v_fmac_f32_e32 v88, v93, v93
	v_add_f32_e32 v83, v83, v88
	v_add_f32_e32 v82, v82, v83
	v_add_f32_e32 v82, v92, v82
	ds_bpermute_b32 v83, v148, v82
	global_store_dwordx4 v[94:95], v[84:87], off offset:256 sc1
	s_waitcnt lgkmcnt(0)
	v_add_f32_e32 v82, v82, v83
	ds_bpermute_b32 v83, v149, v82
	s_and_saveexec_b64 s[26:27], s[6:7]
	s_cbranch_execz .LBB0_269
	s_waitcnt lgkmcnt(0)
	v_add_f32_e32 v84, v82, v83
	v_lshl_add_u64 v[82:83], s[24:25], 2, v[146:147]
	s_lshl_b32 s96, s41, 2
	v_lshl_add_u64 v[82:83], v[82:83], 0, s[96:97]
	v_add_co_u32_e32 v82, vcc, 0x1000, v82
	s_nop 1
	v_addc_co_u32_e32 v83, vcc, 0, v83, vcc
	global_store_dword v[82:83], v84, off sc1

;     __device__ __forceinline__ void operator()(const f32x4 (&acc)[2][2][4][2], const pg8::Unit& u, int wr, int wc, int fr_, int fq_, int tid) {
;     ...
;         for (int g = 0; g < 8; ++g) {
;             const int ai = g >> 2, m = g & 3;
;             if (g < 7) ER_LD(nxt, g + 1);
;             const size_t off = base + (size_t)(ai * 128 + m * 16) * DM; float s = 0.f;
; #pragma unroll
;             for (int bj = 0; bj < 2; ++bj) {
;                 const f32x4 n0 = cur[2 * bj] + acc[ai][bj][m][0] * alpha, n1 = cur[2 * bj + 1] + acc[ai][bj][m][1] * alpha;
;                 const u32x4 w = pack8bf(n0, n1);
;                 *(u32x4*)(xb + off + bj * 128) = w;
;                 float q[8]; unpack8(w, q);
;                 s += ((q[0] * q[0] + q[1] * q[1]) + (q[2] * q[2] + q[3] * q[3])) + ((q[4] * q[4] + q[5] * q[5]) + (q[6] * q[6] + q[7] * q[7]));
;             }
;             s += __shfl_xor(s, 16); s += __shfl_xor(s, 32);
;             if (fq == 0) ssq[(size_t)(row0 + ai * 128 + m * 16) * 32 + u.pn * 4 + wc] = s;
.LBB0_272:
	s_waitcnt vmcnt(3)
	v_pk_fma_f32 v[78:79], v[78:79], 0.5, v[110:111] op_sel_hi:[1,0,1]
	v_pk_fma_f32 v[108:109], v[76:77], 0.5, v[108:109] op_sel_hi:[1,0,1]
	v_pk_fma_f32 v[76:77], v[74:75], 0.5, v[106:107] op_sel_hi:[1,0,1]
	v_cvt_pk_bf16_f32 v74, v78, v79
	v_add_co_u32_e32 v78, vcc, s90, v184
	v_pk_fma_f32 v[80:81], v[80:81], 0.5, v[112:113] op_sel_hi:[1,0,1]
	s_nop 0
	v_addc_co_u32_e32 v79, vcc, 0, v185, vcc
	v_cvt_pk_bf16_f32 v75, v80, v81
	v_cvt_pk_bf16_f32 v76, v76, v77
	v_cvt_pk_bf16_f32 v77, v108, v109
	global_store_dwordx4 v[78:79], v[74:77], off sc1
	v_lshlrev_b32_e32 v80, 16, v74
	v_lshlrev_b32_e32 v81, 16, v75
	v_and_b32_e32 v74, 0xffff0000, v74
	v_and_b32_e32 v75, 0xffff0000, v75
	v_mul_f32_e32 v74, v74, v74
	v_mul_f32_e32 v75, v75, v75
	v_lshlrev_b32_e32 v106, 16, v76
	v_and_b32_e32 v76, 0xffff0000, v76
	v_lshlrev_b32_e32 v107, 16, v77
	v_and_b32_e32 v77, 0xffff0000, v77
	v_fmac_f32_e32 v74, v80, v80
	v_fmac_f32_e32 v75, v81, v81
	v_add_f32_e32 v74, v74, v75
	v_mul_f32_e32 v75, v76, v76
	v_mul_f32_e32 v76, v77, v77
	v_fmac_f32_e32 v75, v106, v106
	v_fmac_f32_e32 v76, v107, v107
	v_add_f32_e32 v75, v75, v76
	v_pk_fma_f32 v[70:71], v[70:71], 0.5, v[102:103] op_sel_hi:[1,0,1]
	s_waitcnt vmcnt(3)
	v_pk_fma_f32 v[66:67], v[66:67], 0.5, v[98:99] op_sel_hi:[1,0,1]
	v_add_f32_e32 v76, v74, v75
	v_pk_fma_f32 v[72:73], v[72:73], 0.5, v[104:105] op_sel_hi:[1,0,1]
	v_pk_fma_f32 v[74:75], v[68:69], 0.5, v[100:101] op_sel_hi:[1,0,1]
	v_cvt_pk_bf16_f32 v68, v70, v71
	v_cvt_pk_bf16_f32 v69, v72, v73
	v_cvt_pk_bf16_f32 v70, v66, v67
	s_nop 0
	v_and_b32_e32 v67, 0xffff0000, v68
	v_lshlrev_b32_e32 v66, 16, v68
	v_and_b32_e32 v73, 0xffff0000, v69
	v_mul_f32_e32 v67, v67, v67
	v_lshlrev_b32_e32 v72, 16, v69
	v_fmac_f32_e32 v67, v66, v66
	v_mul_f32_e32 v66, v73, v73
	v_cvt_pk_bf16_f32 v71, v74, v75
	v_and_b32_e32 v75, 0xffff0000, v70
	v_and_b32_e32 v80, 0xffff0000, v71
	v_fmac_f32_e32 v66, v72, v72
	v_lshlrev_b32_e32 v74, 16, v70
	v_lshlrev_b32_e32 v77, 16, v71
	v_add_f32_e32 v66, v67, v66
	v_mul_f32_e32 v67, v75, v75
	v_mul_f32_e32 v72, v80, v80
	v_fmac_f32_e32 v67, v74, v74
	v_fmac_f32_e32 v72, v77, v77
	v_add_f32_e32 v67, v67, v72
	v_add_f32_e32 v66, v66, v67
	v_add_f32_e32 v66, v76, v66
	ds_bpermute_b32 v67, v148, v66
	global_store_dwordx4 v[78:79], v[68:71], off offset:256 sc1
	s_waitcnt lgkmcnt(0)
	v_add_f32_e32 v66, v66, v67
	ds_bpermute_b32 v67, v149, v66
	s_and_saveexec_b64 s[26:27], s[6:7]
	s_cbranch_execz .LBB0_274
	s_waitcnt lgkmcnt(0)
	v_add_f32_e32 v68, v66, v67
	v_lshl_add_u64 v[66:67], s[24:25], 2, v[146:147]
	s_lshl_b32 s96, s41, 2
	v_lshl_add_u64 v[66:67], v[66:67], 0, s[96:97]
	v_add_co_u32_e32 v66, vcc, 0x1000, v66
	s_nop 1
	v_addc_co_u32_e32 v67, vcc, 0, v67, vcc
	global_store_dword v[66:67], v68, off offset:2048 sc1

;     __device__ __forceinline__ void operator()(const f32x4 (&acc)[2][2][4][2], const pg8::Unit& u, int wr, int wc, int fr_, int fq_, int tid) {
;     ...
;         for (int g = 0; g < 8; ++g) {
;             const int ai = g >> 2, m = g & 3;
;             if (g < 7) ER_LD(nxt, g + 1);
;             const size_t off = base + (size_t)(ai * 128 + m * 16) * DM; float s = 0.f;
; #pragma unroll
;             for (int bj = 0; bj < 2; ++bj) {
;                 const f32x4 n0 = cur[2 * bj] + acc[ai][bj][m][0] * alpha, n1 = cur[2 * bj + 1] + acc[ai][bj][m][1] * alpha;
;                 const u32x4 w = pack8bf(n0, n1);
;                 *(u32x4*)(xb + off + bj * 128) = w;
;                 float q[8]; unpack8(w, q);
;                 s += ((q[0] * q[0] + q[1] * q[1]) + (q[2] * q[2] + q[3] * q[3])) + ((q[4] * q[4] + q[5] * q[5]) + (q[6] * q[6] + q[7] * q[7]));
;             }
;             s += __shfl_xor(s, 16); s += __shfl_xor(s, 32);
;             if (fq == 0) ssq[(size_t)(row0 + ai * 128 + m * 16) * 32 + u.pn * 4 + wc] = s;
.LBB0_277:
	s_waitcnt vmcnt(3)
	v_pk_fma_f32 v[62:63], v[62:63], 0.5, v[94:95] op_sel_hi:[1,0,1]
	v_pk_fma_f32 v[92:93], v[60:61], 0.5, v[92:93] op_sel_hi:[1,0,1]
	v_pk_fma_f32 v[60:61], v[58:59], 0.5, v[90:91] op_sel_hi:[1,0,1]
	v_cvt_pk_bf16_f32 v58, v62, v63
	v_add_co_u32_e32 v62, vcc, s91, v184
	v_pk_fma_f32 v[64:65], v[64:65], 0.5, v[96:97] op_sel_hi:[1,0,1]
	s_nop 0
	v_addc_co_u32_e32 v63, vcc, 0, v185, vcc
	v_cvt_pk_bf16_f32 v59, v64, v65
	v_cvt_pk_bf16_f32 v60, v60, v61
	v_cvt_pk_bf16_f32 v61, v92, v93
	global_store_dwordx4 v[62:63], v[58:61], off sc1
	v_lshlrev_b32_e32 v64, 16, v58
	v_lshlrev_b32_e32 v65, 16, v59
	v_and_b32_e32 v58, 0xffff0000, v58
	v_and_b32_e32 v59, 0xffff0000, v59
	v_mul_f32_e32 v58, v58, v58
	v_mul_f32_e32 v59, v59, v59
	v_lshlrev_b32_e32 v90, 16, v60
	v_and_b32_e32 v60, 0xffff0000, v60
	v_lshlrev_b32_e32 v91, 16, v61
	v_and_b32_e32 v61, 0xffff0000, v61
	v_fmac_f32_e32 v58, v64, v64
	v_fmac_f32_e32 v59, v65, v65
	v_add_f32_e32 v58, v58, v59
	v_mul_f32_e32 v59, v60, v60
	v_mul_f32_e32 v60, v61, v61
	v_fmac_f32_e32 v59, v90, v90
	v_fmac_f32_e32 v60, v91, v91
	v_add_f32_e32 v59, v59, v60
	v_pk_fma_f32 v[54:55], v[54:55], 0.5, v[86:87] op_sel_hi:[1,0,1]
	s_waitcnt vmcnt(3)
	v_pk_fma_f32 v[50:51], v[50:51], 0.5, v[82:83] op_sel_hi:[1,0,1]
	v_add_f32_e32 v60, v58, v59
	v_pk_fma_f32 v[56:57], v[56:57], 0.5, v[88:89] op_sel_hi:[1,0,1]
	v_pk_fma_f32 v[58:59], v[52:53], 0.5, v[84:85] op_sel_hi:[1,0,1]
	v_cvt_pk_bf16_f32 v52, v54, v55
	v_cvt_pk_bf16_f32 v53, v56, v57
	v_cvt_pk_bf16_f32 v54, v50, v51
	s_nop 0
	v_and_b32_e32 v51, 0xffff0000, v52
	v_lshlrev_b32_e32 v50, 16, v52
	v_and_b32_e32 v57, 0xffff0000, v53
	v_mul_f32_e32 v51, v51, v51
	v_lshlrev_b32_e32 v56, 16, v53
	v_fmac_f32_e32 v51, v50, v50
	v_mul_f32_e32 v50, v57, v57
	v_cvt_pk_bf16_f32 v55, v58, v59
	v_and_b32_e32 v59, 0xffff0000, v54
	v_and_b32_e32 v64, 0xffff0000, v55
	v_fmac_f32_e32 v50, v56, v56
	v_lshlrev_b32_e32 v58, 16, v54
	v_lshlrev_b32_e32 v61, 16, v55
	v_add_f32_e32 v50, v51, v50
	v_mul_f32_e32 v51, v59, v59
	v_mul_f32_e32 v56, v64, v64
	v_fmac_f32_e32 v51, v58, v58
	v_fmac_f32_e32 v56, v61, v61
	v_add_f32_e32 v51, v51, v56
	v_add_f32_e32 v50, v50, v51
	v_add_f32_e32 v50, v60, v50
	ds_bpermute_b32 v51, v148, v50
	global_store_dwordx4 v[62:63], v[52:55], off offset:256 sc1
	s_waitcnt lgkmcnt(0)
	v_add_f32_e32 v50, v50, v51
	ds_bpermute_b32 v51, v149, v50
	s_and_saveexec_b64 s[26:27], s[6:7]
	s_cbranch_execz .LBB0_279
	s_waitcnt lgkmcnt(0)
	v_add_f32_e32 v52, v50, v51
	v_lshl_add_u64 v[50:51], s[24:25], 2, v[146:147]
	s_lshl_b32 s96, s41, 2
	v_lshl_add_u64 v[50:51], v[50:51], 0, s[96:97]
	v_add_co_u32_e32 v50, vcc, 0x4000, v50
	s_nop 1
	v_addc_co_u32_e32 v51, vcc, 0, v51, vcc
	global_store_dword v[50:51], v52, off sc1

;     __device__ __forceinline__ void operator()(const f32x4 (&acc)[2][2][4][2], const pg8::Unit& u, int wr, int wc, int fr_, int fq_, int tid) {
;     ...
;         for (int g = 0; g < 8; ++g) {
;             const int ai = g >> 2, m = g & 3;
;             if (g < 7) ER_LD(nxt, g + 1);
;             const size_t off = base + (size_t)(ai * 128 + m * 16) * DM; float s = 0.f;
; #pragma unroll
;             for (int bj = 0; bj < 2; ++bj) {
;                 const f32x4 n0 = cur[2 * bj] + acc[ai][bj][m][0] * alpha, n1 = cur[2 * bj + 1] + acc[ai][bj][m][1] * alpha;
;                 const u32x4 w = pack8bf(n0, n1);
;                 *(u32x4*)(xb + off + bj * 128) = w;
;                 float q[8]; unpack8(w, q);
;                 s += ((q[0] * q[0] + q[1] * q[1]) + (q[2] * q[2] + q[3] * q[3])) + ((q[4] * q[4] + q[5] * q[5]) + (q[6] * q[6] + q[7] * q[7]));
;             }
;             s += __shfl_xor(s, 16); s += __shfl_xor(s, 32);
;             if (fq == 0) ssq[(size_t)(row0 + ai * 128 + m * 16) * 32 + u.pn * 4 + wc] = s;
.LBB0_282:
	s_waitcnt vmcnt(3)
	v_pk_fma_f32 v[46:47], v[46:47], 0.5, v[78:79] op_sel_hi:[1,0,1]
	v_pk_fma_f32 v[76:77], v[44:45], 0.5, v[76:77] op_sel_hi:[1,0,1]
	v_pk_fma_f32 v[44:45], v[42:43], 0.5, v[74:75] op_sel_hi:[1,0,1]
	v_cvt_pk_bf16_f32 v42, v46, v47
	v_add_co_u32_e32 v46, vcc, s92, v184
	v_pk_fma_f32 v[48:49], v[48:49], 0.5, v[80:81] op_sel_hi:[1,0,1]
	s_nop 0
	v_addc_co_u32_e32 v47, vcc, 0, v185, vcc
	v_cvt_pk_bf16_f32 v43, v48, v49
	v_cvt_pk_bf16_f32 v44, v44, v45
	v_cvt_pk_bf16_f32 v45, v76, v77
	global_store_dwordx4 v[46:47], v[42:45], off sc1
	v_lshlrev_b32_e32 v48, 16, v42
	v_lshlrev_b32_e32 v49, 16, v43
	v_and_b32_e32 v42, 0xffff0000, v42
	v_and_b32_e32 v43, 0xffff0000, v43
	v_mul_f32_e32 v42, v42, v42
	v_mul_f32_e32 v43, v43, v43
	v_lshlrev_b32_e32 v74, 16, v44
	v_and_b32_e32 v44, 0xffff0000, v44
	v_lshlrev_b32_e32 v75, 16, v45
	v_and_b32_e32 v45, 0xffff0000, v45
	v_fmac_f32_e32 v42, v48, v48
	v_fmac_f32_e32 v43, v49, v49
	v_add_f32_e32 v42, v42, v43
	v_mul_f32_e32 v43, v44, v44
	v_mul_f32_e32 v44, v45, v45
	v_fmac_f32_e32 v43, v74, v74
	v_fmac_f32_e32 v44, v75, v75
	v_add_f32_e32 v43, v43, v44
	v_pk_fma_f32 v[38:39], v[38:39], 0.5, v[70:71] op_sel_hi:[1,0,1]
	s_waitcnt vmcnt(3)
	v_pk_fma_f32 v[34:35], v[34:35], 0.5, v[66:67] op_sel_hi:[1,0,1]
	v_add_f32_e32 v44, v42, v43
	v_pk_fma_f32 v[40:41], v[40:41], 0.5, v[72:73] op_sel_hi:[1,0,1]
	v_pk_fma_f32 v[42:43], v[36:37], 0.5, v[68:69] op_sel_hi:[1,0,1]
	v_cvt_pk_bf16_f32 v36, v38, v39
	v_cvt_pk_bf16_f32 v37, v40, v41
	v_cvt_pk_bf16_f32 v38, v34, v35
	s_nop 0
	v_and_b32_e32 v35, 0xffff0000, v36
	v_lshlrev_b32_e32 v34, 16, v36
	v_and_b32_e32 v41, 0xffff0000, v37
	v_mul_f32_e32 v35, v35, v35
	v_lshlrev_b32_e32 v40, 16, v37
	v_fmac_f32_e32 v35, v34, v34
	v_mul_f32_e32 v34, v41, v41
	v_cvt_pk_bf16_f32 v39, v42, v43
	v_and_b32_e32 v43, 0xffff0000, v38
	v_and_b32_e32 v48, 0xffff0000, v39
	v_fmac_f32_e32 v34, v40, v40
	v_lshlrev_b32_e32 v42, 16, v38
	v_lshlrev_b32_e32 v45, 16, v39
	v_add_f32_e32 v34, v35, v34
	v_mul_f32_e32 v35, v43, v43
	v_mul_f32_e32 v40, v48, v48
	v_fmac_f32_e32 v35, v42, v42
	v_fmac_f32_e32 v40, v45, v45
	v_add_f32_e32 v35, v35, v40
	v_add_f32_e32 v34, v34, v35
	v_add_f32_e32 v34, v44, v34
	ds_bpermute_b32 v35, v148, v34
	global_store_dwordx4 v[46:47], v[36:39], off offset:256 sc1
	s_waitcnt lgkmcnt(0)
	v_add_f32_e32 v34, v34, v35
	ds_bpermute_b32 v35, v149, v34
	s_and_saveexec_b64 s[26:27], s[6:7]
	s_cbranch_execz .LBB0_284
	s_waitcnt lgkmcnt(0)
	v_add_f32_e32 v36, v34, v35
	v_lshl_add_u64 v[34:35], s[24:25], 2, v[146:147]
	s_lshl_b32 s96, s41, 2
	v_lshl_add_u64 v[34:35], v[34:35], 0, s[96:97]
	v_add_co_u32_e32 v34, vcc, 0x4000, v34
	s_nop 1
	v_addc_co_u32_e32 v35, vcc, 0, v35, vcc
	global_store_dword v[34:35], v36, off offset:2048 sc1

;     __device__ __forceinline__ void operator()(const f32x4 (&acc)[2][2][4][2], const pg8::Unit& u, int wr, int wc, int fr_, int fq_, int tid) {
;     ...
;         for (int g = 0; g < 8; ++g) {
;             const int ai = g >> 2, m = g & 3;
;             if (g < 7) ER_LD(nxt, g + 1);
;             const size_t off = base + (size_t)(ai * 128 + m * 16) * DM; float s = 0.f;
; #pragma unroll
;             for (int bj = 0; bj < 2; ++bj) {
;                 const f32x4 n0 = cur[2 * bj] + acc[ai][bj][m][0] * alpha, n1 = cur[2 * bj + 1] + acc[ai][bj][m][1] * alpha;
;                 const u32x4 w = pack8bf(n0, n1);
;                 *(u32x4*)(xb + off + bj * 128) = w;
;                 float q[8]; unpack8(w, q);
;                 s += ((q[0] * q[0] + q[1] * q[1]) + (q[2] * q[2] + q[3] * q[3])) + ((q[4] * q[4] + q[5] * q[5]) + (q[6] * q[6] + q[7] * q[7]));
;             }
;             s += __shfl_xor(s, 16); s += __shfl_xor(s, 32);
;             if (fq == 0) ssq[(size_t)(row0 + ai * 128 + m * 16) * 32 + u.pn * 4 + wc] = s;
.LBB0_287:
	s_waitcnt vmcnt(3)
	v_pk_fma_f32 v[30:31], v[30:31], 0.5, v[62:63] op_sel_hi:[1,0,1]
	v_pk_fma_f32 v[60:61], v[28:29], 0.5, v[60:61] op_sel_hi:[1,0,1]
	v_pk_fma_f32 v[28:29], v[26:27], 0.5, v[58:59] op_sel_hi:[1,0,1]
	v_cvt_pk_bf16_f32 v26, v30, v31
	v_add_co_u32_e32 v30, vcc, s59, v184
	v_pk_fma_f32 v[32:33], v[32:33], 0.5, v[64:65] op_sel_hi:[1,0,1]
	s_nop 0
	v_addc_co_u32_e32 v31, vcc, 0, v185, vcc
	v_cvt_pk_bf16_f32 v27, v32, v33
	v_cvt_pk_bf16_f32 v28, v28, v29
	v_cvt_pk_bf16_f32 v29, v60, v61
	global_store_dwordx4 v[30:31], v[26:29], off sc1
	v_lshlrev_b32_e32 v32, 16, v26
	v_lshlrev_b32_e32 v33, 16, v27
	v_and_b32_e32 v26, 0xffff0000, v26
	v_and_b32_e32 v27, 0xffff0000, v27
	v_mul_f32_e32 v26, v26, v26
	v_mul_f32_e32 v27, v27, v27
	v_lshlrev_b32_e32 v58, 16, v28
	v_and_b32_e32 v28, 0xffff0000, v28
	v_lshlrev_b32_e32 v59, 16, v29
	v_and_b32_e32 v29, 0xffff0000, v29
	v_fmac_f32_e32 v26, v32, v32
	v_fmac_f32_e32 v27, v33, v33
	v_add_f32_e32 v26, v26, v27
	v_mul_f32_e32 v27, v28, v28
	v_mul_f32_e32 v28, v29, v29
	v_fmac_f32_e32 v27, v58, v58
	v_fmac_f32_e32 v28, v59, v59
	v_add_f32_e32 v27, v27, v28
	v_pk_fma_f32 v[22:23], v[22:23], 0.5, v[54:55] op_sel_hi:[1,0,1]
	s_waitcnt vmcnt(3)
	v_pk_fma_f32 v[18:19], v[18:19], 0.5, v[50:51] op_sel_hi:[1,0,1]
	v_add_f32_e32 v28, v26, v27
	v_pk_fma_f32 v[24:25], v[24:25], 0.5, v[56:57] op_sel_hi:[1,0,1]
	v_pk_fma_f32 v[26:27], v[20:21], 0.5, v[52:53] op_sel_hi:[1,0,1]
	v_cvt_pk_bf16_f32 v20, v22, v23
	v_cvt_pk_bf16_f32 v21, v24, v25
	v_cvt_pk_bf16_f32 v22, v18, v19
	s_nop 0
	v_and_b32_e32 v19, 0xffff0000, v20
	v_lshlrev_b32_e32 v18, 16, v20
	v_and_b32_e32 v25, 0xffff0000, v21
	v_mul_f32_e32 v19, v19, v19
	v_lshlrev_b32_e32 v24, 16, v21
	v_fmac_f32_e32 v19, v18, v18
	v_mul_f32_e32 v18, v25, v25
	v_cvt_pk_bf16_f32 v23, v26, v27
	v_and_b32_e32 v27, 0xffff0000, v22
	v_and_b32_e32 v32, 0xffff0000, v23
	v_fmac_f32_e32 v18, v24, v24
	v_lshlrev_b32_e32 v26, 16, v22
	v_lshlrev_b32_e32 v29, 16, v23
	v_add_f32_e32 v18, v19, v18
	v_mul_f32_e32 v19, v27, v27
	v_mul_f32_e32 v24, v32, v32
	v_fmac_f32_e32 v19, v26, v26
	v_fmac_f32_e32 v24, v29, v29
	v_add_f32_e32 v19, v19, v24
	v_add_f32_e32 v18, v18, v19
	v_add_f32_e32 v18, v28, v18
	ds_bpermute_b32 v19, v148, v18
	global_store_dwordx4 v[30:31], v[20:23], off offset:256 sc1
	s_waitcnt lgkmcnt(0)
	v_add_f32_e32 v18, v18, v19
	ds_bpermute_b32 v19, v149, v18
	s_and_saveexec_b64 s[8:9], s[6:7]
	s_cbranch_execz .LBB0_289
	s_waitcnt lgkmcnt(0)
	v_add_f32_e32 v20, v18, v19
	v_lshl_add_u64 v[18:19], s[24:25], 2, v[146:147]
	s_lshl_b32 s96, s41, 2
	v_lshl_add_u64 v[18:19], v[18:19], 0, s[96:97]
	v_add_co_u32_e32 v18, vcc, 0x5000, v18
	s_nop 1
	v_addc_co_u32_e32 v19, vcc, 0, v19, vcc
	global_store_dword v[18:19], v20, off sc1
.LBB0_289:
	s_or_b64 exec, exec, s[8:9]
	s_waitcnt vmcnt(3)
	v_pk_fma_f32 v[14:15], v[14:15], 0.5, v[46:47] op_sel_hi:[1,0,1]
	s_waitcnt lgkmcnt(0)
	v_pk_fma_f32 v[18:19], v[12:13], 0.5, v[44:45] op_sel_hi:[1,0,1]
	v_pk_fma_f32 v[12:13], v[10:11], 0.5, v[42:43] op_sel_hi:[1,0,1]
	v_cvt_pk_bf16_f32 v10, v14, v15
	v_add_co_u32_e32 v14, vcc, s60, v184
	v_pk_fma_f32 v[16:17], v[16:17], 0.5, v[48:49] op_sel_hi:[1,0,1]
	s_nop 0
	v_addc_co_u32_e32 v15, vcc, 0, v185, vcc
	v_cvt_pk_bf16_f32 v11, v16, v17
	v_cvt_pk_bf16_f32 v12, v12, v13
	v_cvt_pk_bf16_f32 v13, v18, v19
	global_store_dwordx4 v[14:15], v[10:13], off sc1
	v_lshlrev_b32_e32 v16, 16, v10
	v_lshlrev_b32_e32 v17, 16, v11
	v_and_b32_e32 v10, 0xffff0000, v10
	v_and_b32_e32 v11, 0xffff0000, v11
	v_mul_f32_e32 v10, v10, v10
	v_mul_f32_e32 v11, v11, v11
	v_lshlrev_b32_e32 v18, 16, v12
	v_and_b32_e32 v12, 0xffff0000, v12
	v_lshlrev_b32_e32 v19, 16, v13
	v_and_b32_e32 v13, 0xffff0000, v13
	v_fmac_f32_e32 v10, v16, v16
	v_fmac_f32_e32 v11, v17, v17
	v_add_f32_e32 v10, v10, v11
	v_mul_f32_e32 v11, v12, v12
	v_mul_f32_e32 v12, v13, v13
	v_fmac_f32_e32 v11, v18, v18
	v_fmac_f32_e32 v12, v19, v19
	v_add_f32_e32 v11, v11, v12
	v_pk_fma_f32 v[6:7], v[6:7], 0.5, v[38:39] op_sel_hi:[1,0,1]
	s_waitcnt vmcnt(3)
	v_pk_fma_f32 v[2:3], v[2:3], 0.5, v[34:35] op_sel_hi:[1,0,1]
	v_add_f32_e32 v12, v10, v11
	v_pk_fma_f32 v[8:9], v[8:9], 0.5, v[40:41] op_sel_hi:[1,0,1]
	v_pk_fma_f32 v[10:11], v[4:5], 0.5, v[36:37] op_sel_hi:[1,0,1]
	v_cvt_pk_bf16_f32 v4, v6, v7
	v_cvt_pk_bf16_f32 v5, v8, v9
	v_cvt_pk_bf16_f32 v6, v2, v3
	s_nop 0
	v_and_b32_e32 v3, 0xffff0000, v4
	v_lshlrev_b32_e32 v2, 16, v4
	v_and_b32_e32 v9, 0xffff0000, v5
	v_mul_f32_e32 v3, v3, v3
	v_lshlrev_b32_e32 v8, 16, v5
	v_fmac_f32_e32 v3, v2, v2
	v_mul_f32_e32 v2, v9, v9
	v_cvt_pk_bf16_f32 v7, v10, v11
	v_and_b32_e32 v11, 0xffff0000, v6
	v_and_b32_e32 v16, 0xffff0000, v7
	v_fmac_f32_e32 v2, v8, v8
	v_lshlrev_b32_e32 v10, 16, v6
	v_lshlrev_b32_e32 v13, 16, v7
	v_add_f32_e32 v2, v3, v2
	v_mul_f32_e32 v3, v11, v11
	v_mul_f32_e32 v8, v16, v16
	v_fmac_f32_e32 v3, v10, v10
	v_fmac_f32_e32 v8, v13, v13
	v_add_f32_e32 v3, v3, v8
	v_add_f32_e32 v2, v2, v3
	v_add_f32_e32 v2, v12, v2
	ds_bpermute_b32 v3, v148, v2
	global_store_dwordx4 v[14:15], v[4:7], off offset:256 sc1
	s_waitcnt lgkmcnt(0)
	v_add_f32_e32 v2, v2, v3
	ds_bpermute_b32 v3, v149, v2
	s_and_saveexec_b64 s[8:9], s[6:7]
	s_cbranch_execz .LBB0_291
	s_waitcnt lgkmcnt(0)
	v_add_f32_e32 v4, v2, v3
	v_lshl_add_u64 v[2:3], s[24:25], 2, v[146:147]
	s_lshl_b32 s96, s41, 2
	v_lshl_add_u64 v[2:3], v[2:3], 0, s[96:97]
	v_add_co_u32_e32 v2, vcc, 0x5000, v2
	s_nop 1
	v_addc_co_u32_e32 v3, vcc, 0, v3, vcc
	global_store_dword v[2:3], v4, off offset:2048 sc1

; __device__ __forceinline__ float silu_f(float x) { return x * __builtin_amdgcn_rcpf(1.0f + __builtin_amdgcn_exp2f(-1.4426950408889634f * x)); }
; __device__ __forceinline__ float gelu_tanh_f(float x) { const float u = (2.0f * 1.4426950408889634f * 0.7978845608028654f) * (x + 0.044715f * x * x * x); return x * __builtin_amdgcn_rcpf(1.0f + __builtin_amdgcn_exp2f(-u)); }
;     __device__ __forceinline__ void operator()(const f32x4 (&acc)[2][2][4][2], const pg8::Unit& u, int wr, int wc, int fr_, int fq_, int tid) {
;     ...
;             for (int ai = 0; ai < 2; ++ai)
; #pragma unroll
;                 for (int m = 0; m < 4; ++m) {
;                     const int s = s0 + ai * 128 + m * 16; const float rs = rsl[rl0 + ai * 128 + m * 16];
; #pragma unroll
;                     for (int bj = 0; bj < 2; ++bj) { const int head = 2 * (idx & 1) + bj;
;                         f32x4 v0 = acc[ai][bj][m][0] * rs, v1 = acc[ai][bj][m][1] * rs;
;                         if (kind == 1) {
; #pragma unroll
;                             for (int i = 0; i < 4; ++i) { v0[i] = silu_f(v0[i]); v1[i] = silu_f(v1[i]); } }
;                         if (kind >= 2) {
; #pragma unroll
;                             for (int i = 0; i < 4; ++i) { v0[i] = gelu_tanh_f(v0[i]); v1[i] = gelu_tanh_f(v1[i]); } }
;                         *(u32x4*)(base + ((size_t)(b * RETH + head) * SEQ + s) * HD + wc * 32 + 8 * fq) = pack8bf(v0, v1); }
.LBB0_382:
	s_lshl_b32 s8, s38, 1
	s_add_i32 s96, s0, 2
	s_and_b32 s8, s8, 2
	s_lshl_b32 s9, s29, 2
	s_lshl_b64 s[0:1], s[96:97], 24
	s_or_b32 s40, s9, s8
	s_add_u32 s0, s71, s0
	v_lshlrev_b32_e32 v130, 3, v176
	s_addc_u32 s1, s72, s1
	v_ashrrev_i32_e32 v131, 31, v130
	v_ashrrev_i32_e32 v155, 31, v154
	v_lshl_add_u64 v[130:131], v[130:131], 1, s[0:1]
	v_lshlrev_b64 v[134:135], 8, v[154:155]
	s_ashr_i32 s41, s40, 31
	v_lshl_add_u64 v[134:135], v[130:131], 0, v[134:135]
	s_lshl_b64 s[0:1], s[40:41], 20
	v_mov_b32_e32 v133, v132
	v_cvt_pk_bf16_f32 v180, v140, v141
	v_cvt_pk_bf16_f32 v181, v136, v137
	v_cvt_pk_bf16_f32 v182, v156, v157
	v_cvt_pk_bf16_f32 v183, v138, v139
	v_lshl_add_u64 v[136:137], v[134:135], 0, s[0:1]
	v_mov_b32_e32 v138, v132
	v_mov_b32_e32 v139, v132
	v_cndmask_b32_e64 v156, 0, 1, s[10:11]
	global_store_dwordx4 v[136:137], v[180:183], off sc1
	v_pk_mul_f32 v[136:137], v[120:121], v[138:139]
	v_pk_mul_f32 v[140:141], v[118:119], v[132:133]
	v_pk_mul_f32 v[138:139], v[116:117], v[138:139]
	v_cmp_ne_u32_e64 s[8:9], 1, v156
	s_andn2_b64 vcc, exec, s[10:11]
	v_pk_mul_f32 v[132:133], v[114:115], v[132:133]
	s_cbranch_vccnz .LBB0_384
	v_mul_f32_e32 v179, 0xbfb8aa3b, v133
	v_exp_f32_e32 v179, v179
	v_mul_f32_e32 v157, 0xbfb8aa3b, v132
	v_exp_f32_e32 v157, v157
	v_mul_f32_e32 v156, 0xbfb8aa3b, v140
	v_add_f32_e32 v179, 1.0, v179
	v_rcp_f32_e32 v181, v179
	v_mul_f32_e32 v179, 0xbfb8aa3b, v136
	v_add_f32_e32 v157, 1.0, v157
	v_exp_f32_e32 v179, v179
	v_rcp_f32_e32 v180, v157
	v_mul_f32_e32 v157, 0xbfb8aa3b, v141
	v_exp_f32_e32 v156, v156
	v_exp_f32_e32 v157, v157
	v_add_f32_e32 v179, 1.0, v179
	v_rcp_f32_e32 v182, v179
	v_mul_f32_e32 v179, 0xbfb8aa3b, v138
	v_add_f32_e32 v156, 1.0, v156
	v_add_f32_e32 v157, 1.0, v157
	v_exp_f32_e32 v179, v179
	v_rcp_f32_e32 v156, v156
	v_rcp_f32_e32 v157, v157
	v_pk_mul_f32 v[132:133], v[132:133], v[180:181]
	v_add_f32_e32 v179, 1.0, v179
	v_rcp_f32_e32 v184, v179
	v_mul_f32_e32 v179, 0xbfb8aa3b, v137
	v_pk_mul_f32 v[140:141], v[140:141], v[156:157]
	v_mul_f32_e32 v156, 0xbfb8aa3b, v139
	v_exp_f32_e32 v179, v179
	v_exp_f32_e32 v156, v156
	v_add_f32_e32 v179, 1.0, v179
	v_add_f32_e32 v156, 1.0, v156
	v_rcp_f32_e32 v183, v179
	v_rcp_f32_e32 v185, v156
	v_pk_mul_f32 v[136:137], v[136:137], v[182:183]
	v_pk_mul_f32 v[138:139], v[138:139], v[184:185]

; __device__ __forceinline__ float silu_f(float x) { return x * __builtin_amdgcn_rcpf(1.0f + __builtin_amdgcn_exp2f(-1.4426950408889634f * x)); }
; __device__ __forceinline__ float gelu_tanh_f(float x) { const float u = (2.0f * 1.4426950408889634f * 0.7978845608028654f) * (x + 0.044715f * x * x * x); return x * __builtin_amdgcn_rcpf(1.0f + __builtin_amdgcn_exp2f(-u)); }
;     __device__ __forceinline__ void operator()(const f32x4 (&acc)[2][2][4][2], const pg8::Unit& u, int wr, int wc, int fr_, int fq_, int tid) {
;     ...
;             for (int ai = 0; ai < 2; ++ai)
; #pragma unroll
;                 for (int m = 0; m < 4; ++m) {
;                     const int s = s0 + ai * 128 + m * 16; const float rs = rsl[rl0 + ai * 128 + m * 16];
; #pragma unroll
;                     for (int bj = 0; bj < 2; ++bj) { const int head = 2 * (idx & 1) + bj;
;                         f32x4 v0 = acc[ai][bj][m][0] * rs, v1 = acc[ai][bj][m][1] * rs;
;                         if (kind == 1) {
; #pragma unroll
;                             for (int i = 0; i < 4; ++i) { v0[i] = silu_f(v0[i]); v1[i] = silu_f(v1[i]); } }
;                         if (kind >= 2) {
; #pragma unroll
;                             for (int i = 0; i < 4; ++i) { v0[i] = gelu_tanh_f(v0[i]); v1[i] = gelu_tanh_f(v1[i]); } }
;                         *(u32x4*)(base + ((size_t)(b * RETH + head) * SEQ + s) * HD + wc * 32 + 8 * fq) = pack8bf(v0, v1); }
.LBB0_386:
	v_cvt_pk_bf16_f32 v180, v140, v141
	v_cvt_pk_bf16_f32 v181, v136, v137
	v_cvt_pk_bf16_f32 v182, v132, v133
	s_nop 0
	v_cvt_pk_bf16_f32 v183, v138, v139
	ds_read_b32 v132, v158 offset:64
	s_or_b32 s40, s40, 1
	s_ashr_i32 s41, s40, 31
	s_lshl_b64 s[42:43], s[40:41], 20
	v_lshl_add_u64 v[134:135], v[134:135], 0, s[42:43]
	s_waitcnt lgkmcnt(0)
	v_pk_mul_f32 v[136:137], v[112:113], v[132:133] op_sel_hi:[1,0]
	v_pk_mul_f32 v[140:141], v[110:111], v[132:133] op_sel_hi:[1,0]
	v_pk_mul_f32 v[138:139], v[108:109], v[132:133] op_sel_hi:[1,0]
	s_and_b64 vcc, exec, s[8:9]
	v_pk_mul_f32 v[156:157], v[106:107], v[132:133] op_sel_hi:[1,0]
	global_store_dwordx4 v[134:135], v[180:183], off sc1
	s_cbranch_vccnz .LBB0_388
	v_mul_f32_e32 v133, 0xbfb8aa3b, v140
	v_exp_f32_e32 v133, v133
	s_nop 0
	v_add_f32_e32 v133, 1.0, v133
	v_rcp_f32_e32 v134, v133
	v_mul_f32_e32 v133, 0xbfb8aa3b, v156
	v_exp_f32_e32 v133, v133
	s_nop 0
	v_add_f32_e32 v133, 1.0, v133
	v_rcp_f32_e32 v180, v133
	v_mul_f32_e32 v133, 0xbfb8aa3b, v141
	v_exp_f32_e32 v133, v133
	s_nop 0
	v_add_f32_e32 v133, 1.0, v133
	v_rcp_f32_e32 v135, v133
	v_mul_f32_e32 v133, 0xbfb8aa3b, v157
	v_exp_f32_e32 v133, v133
	v_pk_mul_f32 v[140:141], v[140:141], v[134:135]
	v_add_f32_e32 v133, 1.0, v133
	v_rcp_f32_e32 v181, v133
	v_mul_f32_e32 v133, 0xbfb8aa3b, v136
	v_exp_f32_e32 v133, v133
	v_pk_mul_f32 v[156:157], v[156:157], v[180:181]
	v_add_f32_e32 v133, 1.0, v133
	v_rcp_f32_e32 v182, v133
	v_mul_f32_e32 v133, 0xbfb8aa3b, v138
	v_exp_f32_e32 v133, v133
	s_nop 0
	v_add_f32_e32 v133, 1.0, v133
	v_rcp_f32_e32 v184, v133
	v_mul_f32_e32 v133, 0xbfb8aa3b, v137
	v_exp_f32_e32 v133, v133
	s_nop 0
	v_add_f32_e32 v133, 1.0, v133
	v_rcp_f32_e32 v183, v133
	v_mul_f32_e32 v133, 0xbfb8aa3b, v139
	v_exp_f32_e32 v133, v133
	v_pk_mul_f32 v[136:137], v[136:137], v[182:183]
	v_add_f32_e32 v133, 1.0, v133
	v_rcp_f32_e32 v185, v133
	s_nop 0
	v_pk_mul_f32 v[138:139], v[138:139], v[184:185]

; __device__ __forceinline__ float silu_f(float x) { return x * __builtin_amdgcn_rcpf(1.0f + __builtin_amdgcn_exp2f(-1.4426950408889634f * x)); }
; __device__ __forceinline__ float gelu_tanh_f(float x) { const float u = (2.0f * 1.4426950408889634f * 0.7978845608028654f) * (x + 0.044715f * x * x * x); return x * __builtin_amdgcn_rcpf(1.0f + __builtin_amdgcn_exp2f(-u)); }
;     __device__ __forceinline__ void operator()(const f32x4 (&acc)[2][2][4][2], const pg8::Unit& u, int wr, int wc, int fr_, int fq_, int tid) {
;     ...
;             for (int ai = 0; ai < 2; ++ai)
; #pragma unroll
;                 for (int m = 0; m < 4; ++m) {
;                     const int s = s0 + ai * 128 + m * 16; const float rs = rsl[rl0 + ai * 128 + m * 16];
; #pragma unroll
;                     for (int bj = 0; bj < 2; ++bj) { const int head = 2 * (idx & 1) + bj;
;                         f32x4 v0 = acc[ai][bj][m][0] * rs, v1 = acc[ai][bj][m][1] * rs;
;                         if (kind == 1) {
; #pragma unroll
;                             for (int i = 0; i < 4; ++i) { v0[i] = silu_f(v0[i]); v1[i] = silu_f(v1[i]); } }
;                         if (kind >= 2) {
; #pragma unroll
;                             for (int i = 0; i < 4; ++i) { v0[i] = gelu_tanh_f(v0[i]); v1[i] = gelu_tanh_f(v1[i]); } }
;                         *(u32x4*)(base + ((size_t)(b * RETH + head) * SEQ + s) * HD + wc * 32 + 8 * fq) = pack8bf(v0, v1); }
.LBB0_390:
	v_lshlrev_b64 v[134:135], 8, v[154:155]
	v_lshl_add_u64 v[134:135], v[130:131], 0, v[134:135]
	s_mov_b64 s[40:41], 0x1000
	v_lshl_add_u64 v[134:135], v[134:135], 0, s[40:41]
	v_mov_b32_e32 v133, v132
	v_cvt_pk_bf16_f32 v180, v140, v141
	v_cvt_pk_bf16_f32 v181, v136, v137
	v_cvt_pk_bf16_f32 v182, v156, v157
	v_cvt_pk_bf16_f32 v183, v138, v139
	v_lshl_add_u64 v[136:137], v[134:135], 0, s[0:1]
	v_mov_b32_e32 v138, v132
	v_mov_b32_e32 v139, v132
	global_store_dwordx4 v[136:137], v[180:183], off sc1
	v_pk_mul_f32 v[136:137], v[104:105], v[138:139]
	v_pk_mul_f32 v[140:141], v[102:103], v[132:133]
	v_pk_mul_f32 v[138:139], v[100:101], v[138:139]
	s_and_b64 vcc, exec, s[8:9]
	v_pk_mul_f32 v[132:133], v[98:99], v[132:133]
	s_cbranch_vccnz .LBB0_392
	v_mul_f32_e32 v179, 0xbfb8aa3b, v133
	v_exp_f32_e32 v179, v179
	v_mul_f32_e32 v157, 0xbfb8aa3b, v132
	v_exp_f32_e32 v157, v157
	v_mul_f32_e32 v156, 0xbfb8aa3b, v140
	v_add_f32_e32 v179, 1.0, v179
	v_rcp_f32_e32 v181, v179
	v_mul_f32_e32 v179, 0xbfb8aa3b, v136
	v_add_f32_e32 v157, 1.0, v157
	v_exp_f32_e32 v179, v179
	v_rcp_f32_e32 v180, v157
	v_mul_f32_e32 v157, 0xbfb8aa3b, v141
	v_exp_f32_e32 v156, v156
	v_exp_f32_e32 v157, v157
	v_add_f32_e32 v179, 1.0, v179
	v_rcp_f32_e32 v182, v179
	v_mul_f32_e32 v179, 0xbfb8aa3b, v138
	v_add_f32_e32 v156, 1.0, v156
	v_add_f32_e32 v157, 1.0, v157
	v_exp_f32_e32 v179, v179
	v_rcp_f32_e32 v156, v156
	v_rcp_f32_e32 v157, v157
	v_pk_mul_f32 v[132:133], v[132:133], v[180:181]
	v_add_f32_e32 v179, 1.0, v179
	v_rcp_f32_e32 v184, v179
	v_mul_f32_e32 v179, 0xbfb8aa3b, v137
	v_pk_mul_f32 v[140:141], v[140:141], v[156:157]
	v_mul_f32_e32 v156, 0xbfb8aa3b, v139
	v_exp_f32_e32 v179, v179
	v_exp_f32_e32 v156, v156
	v_add_f32_e32 v179, 1.0, v179
	v_add_f32_e32 v156, 1.0, v156
	v_rcp_f32_e32 v183, v179
	v_rcp_f32_e32 v185, v156
	v_pk_mul_f32 v[136:137], v[136:137], v[182:183]
	v_pk_mul_f32 v[138:139], v[138:139], v[184:185]

; __device__ __forceinline__ float silu_f(float x) { return x * __builtin_amdgcn_rcpf(1.0f + __builtin_amdgcn_exp2f(-1.4426950408889634f * x)); }
; __device__ __forceinline__ float gelu_tanh_f(float x) { const float u = (2.0f * 1.4426950408889634f * 0.7978845608028654f) * (x + 0.044715f * x * x * x); return x * __builtin_amdgcn_rcpf(1.0f + __builtin_amdgcn_exp2f(-u)); }
;     __device__ __forceinline__ void operator()(const f32x4 (&acc)[2][2][4][2], const pg8::Unit& u, int wr, int wc, int fr_, int fq_, int tid) {
;     ...
;             for (int ai = 0; ai < 2; ++ai)
; #pragma unroll
;                 for (int m = 0; m < 4; ++m) {
;                     const int s = s0 + ai * 128 + m * 16; const float rs = rsl[rl0 + ai * 128 + m * 16];
; #pragma unroll
;                     for (int bj = 0; bj < 2; ++bj) { const int head = 2 * (idx & 1) + bj;
;                         f32x4 v0 = acc[ai][bj][m][0] * rs, v1 = acc[ai][bj][m][1] * rs;
;                         if (kind == 1) {
; #pragma unroll
;                             for (int i = 0; i < 4; ++i) { v0[i] = silu_f(v0[i]); v1[i] = silu_f(v1[i]); } }
;                         if (kind >= 2) {
; #pragma unroll
;                             for (int i = 0; i < 4; ++i) { v0[i] = gelu_tanh_f(v0[i]); v1[i] = gelu_tanh_f(v1[i]); } }
;                         *(u32x4*)(base + ((size_t)(b * RETH + head) * SEQ + s) * HD + wc * 32 + 8 * fq) = pack8bf(v0, v1); }
.LBB0_394:
	v_cvt_pk_bf16_f32 v180, v140, v141
	v_cvt_pk_bf16_f32 v181, v136, v137
	v_cvt_pk_bf16_f32 v182, v132, v133
	s_nop 0
	v_cvt_pk_bf16_f32 v183, v138, v139
	ds_read_b32 v132, v158 offset:128
	v_lshl_add_u64 v[134:135], v[134:135], 0, s[42:43]
	s_and_b64 vcc, exec, s[8:9]
	global_store_dwordx4 v[134:135], v[180:183], off sc1
	s_waitcnt lgkmcnt(0)
	v_pk_mul_f32 v[136:137], v[96:97], v[132:133] op_sel_hi:[1,0]
	v_pk_mul_f32 v[140:141], v[94:95], v[132:133] op_sel_hi:[1,0]
	v_pk_mul_f32 v[138:139], v[92:93], v[132:133] op_sel_hi:[1,0]
	v_pk_mul_f32 v[156:157], v[90:91], v[132:133] op_sel_hi:[1,0]
	s_cbranch_vccnz .LBB0_396
	v_mul_f32_e32 v133, 0xbfb8aa3b, v140
	v_exp_f32_e32 v133, v133
	s_nop 0
	v_add_f32_e32 v133, 1.0, v133
	v_rcp_f32_e32 v134, v133
	v_mul_f32_e32 v133, 0xbfb8aa3b, v156
	v_exp_f32_e32 v133, v133
	s_nop 0
	v_add_f32_e32 v133, 1.0, v133
	v_rcp_f32_e32 v180, v133
	v_mul_f32_e32 v133, 0xbfb8aa3b, v141
	v_exp_f32_e32 v133, v133
	s_nop 0
	v_add_f32_e32 v133, 1.0, v133
	v_rcp_f32_e32 v135, v133
	v_mul_f32_e32 v133, 0xbfb8aa3b, v157
	v_exp_f32_e32 v133, v133
	v_pk_mul_f32 v[140:141], v[140:141], v[134:135]
	v_add_f32_e32 v133, 1.0, v133
	v_rcp_f32_e32 v181, v133
	v_mul_f32_e32 v133, 0xbfb8aa3b, v136
	v_exp_f32_e32 v133, v133
	v_pk_mul_f32 v[156:157], v[156:157], v[180:181]
	v_add_f32_e32 v133, 1.0, v133
	v_rcp_f32_e32 v182, v133
	v_mul_f32_e32 v133, 0xbfb8aa3b, v138
	v_exp_f32_e32 v133, v133
	s_nop 0
	v_add_f32_e32 v133, 1.0, v133
	v_rcp_f32_e32 v184, v133
	v_mul_f32_e32 v133, 0xbfb8aa3b, v137
	v_exp_f32_e32 v133, v133
	s_nop 0
	v_add_f32_e32 v133, 1.0, v133
	v_rcp_f32_e32 v183, v133
	v_mul_f32_e32 v133, 0xbfb8aa3b, v139
	v_exp_f32_e32 v133, v133
	v_pk_mul_f32 v[136:137], v[136:137], v[182:183]
	v_add_f32_e32 v133, 1.0, v133
	v_rcp_f32_e32 v185, v133
	s_nop 0
	v_pk_mul_f32 v[138:139], v[138:139], v[184:185]

; __device__ __forceinline__ float silu_f(float x) { return x * __builtin_amdgcn_rcpf(1.0f + __builtin_amdgcn_exp2f(-1.4426950408889634f * x)); }
; __device__ __forceinline__ float gelu_tanh_f(float x) { const float u = (2.0f * 1.4426950408889634f * 0.7978845608028654f) * (x + 0.044715f * x * x * x); return x * __builtin_amdgcn_rcpf(1.0f + __builtin_amdgcn_exp2f(-u)); }
;     __device__ __forceinline__ void operator()(const f32x4 (&acc)[2][2][4][2], const pg8::Unit& u, int wr, int wc, int fr_, int fq_, int tid) {
;     ...
;             for (int ai = 0; ai < 2; ++ai)
; #pragma unroll
;                 for (int m = 0; m < 4; ++m) {
;                     const int s = s0 + ai * 128 + m * 16; const float rs = rsl[rl0 + ai * 128 + m * 16];
; #pragma unroll
;                     for (int bj = 0; bj < 2; ++bj) { const int head = 2 * (idx & 1) + bj;
;                         f32x4 v0 = acc[ai][bj][m][0] * rs, v1 = acc[ai][bj][m][1] * rs;
;                         if (kind == 1) {
; #pragma unroll
;                             for (int i = 0; i < 4; ++i) { v0[i] = silu_f(v0[i]); v1[i] = silu_f(v1[i]); } }
;                         if (kind >= 2) {
; #pragma unroll
;                             for (int i = 0; i < 4; ++i) { v0[i] = gelu_tanh_f(v0[i]); v1[i] = gelu_tanh_f(v1[i]); } }
;                         *(u32x4*)(base + ((size_t)(b * RETH + head) * SEQ + s) * HD + wc * 32 + 8 * fq) = pack8bf(v0, v1); }
.LBB0_398:
	v_lshlrev_b64 v[134:135], 8, v[154:155]
	v_lshl_add_u64 v[134:135], v[130:131], 0, v[134:135]
	s_mov_b64 s[40:41], 0x2000
	v_lshl_add_u64 v[134:135], v[134:135], 0, s[40:41]
	v_mov_b32_e32 v133, v132
	v_cvt_pk_bf16_f32 v180, v140, v141
	v_cvt_pk_bf16_f32 v181, v136, v137
	v_cvt_pk_bf16_f32 v182, v156, v157
	v_cvt_pk_bf16_f32 v183, v138, v139
	v_lshl_add_u64 v[136:137], v[134:135], 0, s[0:1]
	v_mov_b32_e32 v138, v132
	v_mov_b32_e32 v139, v132
	global_store_dwordx4 v[136:137], v[180:183], off sc1
	v_pk_mul_f32 v[136:137], v[88:89], v[138:139]
	v_pk_mul_f32 v[140:141], v[86:87], v[132:133]
	v_pk_mul_f32 v[138:139], v[84:85], v[138:139]
	s_and_b64 vcc, exec, s[8:9]
	v_pk_mul_f32 v[132:133], v[82:83], v[132:133]
	s_cbranch_vccnz .LBB0_400
	v_mul_f32_e32 v179, 0xbfb8aa3b, v133
	v_exp_f32_e32 v179, v179
	v_mul_f32_e32 v157, 0xbfb8aa3b, v132
	v_exp_f32_e32 v157, v157
	v_mul_f32_e32 v156, 0xbfb8aa3b, v140
	v_add_f32_e32 v179, 1.0, v179
	v_rcp_f32_e32 v181, v179
	v_mul_f32_e32 v179, 0xbfb8aa3b, v136
	v_add_f32_e32 v157, 1.0, v157
	v_exp_f32_e32 v179, v179
	v_rcp_f32_e32 v180, v157
	v_mul_f32_e32 v157, 0xbfb8aa3b, v141
	v_exp_f32_e32 v156, v156
	v_exp_f32_e32 v157, v157
	v_add_f32_e32 v179, 1.0, v179
	v_rcp_f32_e32 v182, v179
	v_mul_f32_e32 v179, 0xbfb8aa3b, v138
	v_add_f32_e32 v156, 1.0, v156
	v_add_f32_e32 v157, 1.0, v157
	v_exp_f32_e32 v179, v179
	v_rcp_f32_e32 v156, v156
	v_rcp_f32_e32 v157, v157
	v_pk_mul_f32 v[132:133], v[132:133], v[180:181]
	v_add_f32_e32 v179, 1.0, v179
	v_rcp_f32_e32 v184, v179
	v_mul_f32_e32 v179, 0xbfb8aa3b, v137
	v_pk_mul_f32 v[140:141], v[140:141], v[156:157]
	v_mul_f32_e32 v156, 0xbfb8aa3b, v139
	v_exp_f32_e32 v179, v179
	v_exp_f32_e32 v156, v156
	v_add_f32_e32 v179, 1.0, v179
	v_add_f32_e32 v156, 1.0, v156
	v_rcp_f32_e32 v183, v179
	v_rcp_f32_e32 v185, v156
	v_pk_mul_f32 v[136:137], v[136:137], v[182:183]
	v_pk_mul_f32 v[138:139], v[138:139], v[184:185]

; __device__ __forceinline__ float silu_f(float x) { return x * __builtin_amdgcn_rcpf(1.0f + __builtin_amdgcn_exp2f(-1.4426950408889634f * x)); }
; __device__ __forceinline__ float gelu_tanh_f(float x) { const float u = (2.0f * 1.4426950408889634f * 0.7978845608028654f) * (x + 0.044715f * x * x * x); return x * __builtin_amdgcn_rcpf(1.0f + __builtin_amdgcn_exp2f(-u)); }
;     __device__ __forceinline__ void operator()(const f32x4 (&acc)[2][2][4][2], const pg8::Unit& u, int wr, int wc, int fr_, int fq_, int tid) {
;     ...
;             for (int ai = 0; ai < 2; ++ai)
; #pragma unroll
;                 for (int m = 0; m < 4; ++m) {
;                     const int s = s0 + ai * 128 + m * 16; const float rs = rsl[rl0 + ai * 128 + m * 16];
; #pragma unroll
;                     for (int bj = 0; bj < 2; ++bj) { const int head = 2 * (idx & 1) + bj;
;                         f32x4 v0 = acc[ai][bj][m][0] * rs, v1 = acc[ai][bj][m][1] * rs;
;                         if (kind == 1) {
; #pragma unroll
;                             for (int i = 0; i < 4; ++i) { v0[i] = silu_f(v0[i]); v1[i] = silu_f(v1[i]); } }
;                         if (kind >= 2) {
; #pragma unroll
;                             for (int i = 0; i < 4; ++i) { v0[i] = gelu_tanh_f(v0[i]); v1[i] = gelu_tanh_f(v1[i]); } }
;                         *(u32x4*)(base + ((size_t)(b * RETH + head) * SEQ + s) * HD + wc * 32 + 8 * fq) = pack8bf(v0, v1); }
.LBB0_402:
	v_cvt_pk_bf16_f32 v180, v140, v141
	v_cvt_pk_bf16_f32 v181, v136, v137
	v_cvt_pk_bf16_f32 v182, v132, v133
	s_nop 0
	v_cvt_pk_bf16_f32 v183, v138, v139
	ds_read_b32 v132, v158 offset:192
	v_lshl_add_u64 v[134:135], v[134:135], 0, s[42:43]
	s_and_b64 vcc, exec, s[8:9]
	global_store_dwordx4 v[134:135], v[180:183], off sc1
	s_waitcnt lgkmcnt(0)
	v_pk_mul_f32 v[136:137], v[80:81], v[132:133] op_sel_hi:[1,0]
	v_pk_mul_f32 v[140:141], v[78:79], v[132:133] op_sel_hi:[1,0]
	v_pk_mul_f32 v[138:139], v[76:77], v[132:133] op_sel_hi:[1,0]
	v_pk_mul_f32 v[156:157], v[74:75], v[132:133] op_sel_hi:[1,0]
	s_cbranch_vccnz .LBB0_404
	v_mul_f32_e32 v133, 0xbfb8aa3b, v140
	v_exp_f32_e32 v133, v133
	s_nop 0
	v_add_f32_e32 v133, 1.0, v133
	v_rcp_f32_e32 v134, v133
	v_mul_f32_e32 v133, 0xbfb8aa3b, v156
	v_exp_f32_e32 v133, v133
	s_nop 0
	v_add_f32_e32 v133, 1.0, v133
	v_rcp_f32_e32 v180, v133
	v_mul_f32_e32 v133, 0xbfb8aa3b, v141
	v_exp_f32_e32 v133, v133
	s_nop 0
	v_add_f32_e32 v133, 1.0, v133
	v_rcp_f32_e32 v135, v133
	v_mul_f32_e32 v133, 0xbfb8aa3b, v157
	v_exp_f32_e32 v133, v133
	v_pk_mul_f32 v[140:141], v[140:141], v[134:135]
	v_add_f32_e32 v133, 1.0, v133
	v_rcp_f32_e32 v181, v133
	v_mul_f32_e32 v133, 0xbfb8aa3b, v136
	v_exp_f32_e32 v133, v133
	v_pk_mul_f32 v[156:157], v[156:157], v[180:181]
	v_add_f32_e32 v133, 1.0, v133
	v_rcp_f32_e32 v182, v133
	v_mul_f32_e32 v133, 0xbfb8aa3b, v138
	v_exp_f32_e32 v133, v133
	s_nop 0
	v_add_f32_e32 v133, 1.0, v133
	v_rcp_f32_e32 v184, v133
	v_mul_f32_e32 v133, 0xbfb8aa3b, v137
	v_exp_f32_e32 v133, v133
	s_nop 0
	v_add_f32_e32 v133, 1.0, v133
	v_rcp_f32_e32 v183, v133
	v_mul_f32_e32 v133, 0xbfb8aa3b, v139
	v_exp_f32_e32 v133, v133
	v_pk_mul_f32 v[136:137], v[136:137], v[182:183]
	v_add_f32_e32 v133, 1.0, v133
	v_rcp_f32_e32 v185, v133
	s_nop 0
	v_pk_mul_f32 v[138:139], v[138:139], v[184:185]

; __device__ __forceinline__ float silu_f(float x) { return x * __builtin_amdgcn_rcpf(1.0f + __builtin_amdgcn_exp2f(-1.4426950408889634f * x)); }
; __device__ __forceinline__ float gelu_tanh_f(float x) { const float u = (2.0f * 1.4426950408889634f * 0.7978845608028654f) * (x + 0.044715f * x * x * x); return x * __builtin_amdgcn_rcpf(1.0f + __builtin_amdgcn_exp2f(-u)); }
;     __device__ __forceinline__ void operator()(const f32x4 (&acc)[2][2][4][2], const pg8::Unit& u, int wr, int wc, int fr_, int fq_, int tid) {
;     ...
;             for (int ai = 0; ai < 2; ++ai)
; #pragma unroll
;                 for (int m = 0; m < 4; ++m) {
;                     const int s = s0 + ai * 128 + m * 16; const float rs = rsl[rl0 + ai * 128 + m * 16];
; #pragma unroll
;                     for (int bj = 0; bj < 2; ++bj) { const int head = 2 * (idx & 1) + bj;
;                         f32x4 v0 = acc[ai][bj][m][0] * rs, v1 = acc[ai][bj][m][1] * rs;
;                         if (kind == 1) {
; #pragma unroll
;                             for (int i = 0; i < 4; ++i) { v0[i] = silu_f(v0[i]); v1[i] = silu_f(v1[i]); } }
;                         if (kind >= 2) {
; #pragma unroll
;                             for (int i = 0; i < 4; ++i) { v0[i] = gelu_tanh_f(v0[i]); v1[i] = gelu_tanh_f(v1[i]); } }
;                         *(u32x4*)(base + ((size_t)(b * RETH + head) * SEQ + s) * HD + wc * 32 + 8 * fq) = pack8bf(v0, v1); }
.LBB0_406:
	v_lshlrev_b64 v[134:135], 8, v[154:155]
	v_lshl_add_u64 v[134:135], v[130:131], 0, v[134:135]
	s_mov_b64 s[40:41], 0x3000
	v_lshl_add_u64 v[134:135], v[134:135], 0, s[40:41]
	v_mov_b32_e32 v133, v132
	v_cvt_pk_bf16_f32 v180, v140, v141
	v_cvt_pk_bf16_f32 v181, v136, v137
	v_cvt_pk_bf16_f32 v182, v156, v157
	v_cvt_pk_bf16_f32 v183, v138, v139
	v_lshl_add_u64 v[136:137], v[134:135], 0, s[0:1]
	v_mov_b32_e32 v138, v132
	v_mov_b32_e32 v139, v132
	global_store_dwordx4 v[136:137], v[180:183], off sc1
	v_pk_mul_f32 v[136:137], v[72:73], v[138:139]
	v_pk_mul_f32 v[140:141], v[70:71], v[132:133]
	v_pk_mul_f32 v[138:139], v[68:69], v[138:139]
	s_and_b64 vcc, exec, s[8:9]
	v_pk_mul_f32 v[132:133], v[66:67], v[132:133]
	s_cbranch_vccnz .LBB0_408
	v_mul_f32_e32 v179, 0xbfb8aa3b, v133
	v_exp_f32_e32 v179, v179
	v_mul_f32_e32 v157, 0xbfb8aa3b, v132
	v_exp_f32_e32 v157, v157
	v_mul_f32_e32 v156, 0xbfb8aa3b, v140
	v_add_f32_e32 v179, 1.0, v179
	v_rcp_f32_e32 v181, v179
	v_mul_f32_e32 v179, 0xbfb8aa3b, v136
	v_add_f32_e32 v157, 1.0, v157
	v_exp_f32_e32 v179, v179
	v_rcp_f32_e32 v180, v157
	v_mul_f32_e32 v157, 0xbfb8aa3b, v141
	v_exp_f32_e32 v156, v156
	v_exp_f32_e32 v157, v157
	v_add_f32_e32 v179, 1.0, v179
	v_rcp_f32_e32 v182, v179
	v_mul_f32_e32 v179, 0xbfb8aa3b, v138
	v_add_f32_e32 v156, 1.0, v156
	v_add_f32_e32 v157, 1.0, v157
	v_exp_f32_e32 v179, v179
	v_rcp_f32_e32 v156, v156
	v_rcp_f32_e32 v157, v157
	v_pk_mul_f32 v[132:133], v[132:133], v[180:181]
	v_add_f32_e32 v179, 1.0, v179
	v_rcp_f32_e32 v184, v179
	v_mul_f32_e32 v179, 0xbfb8aa3b, v137
	v_pk_mul_f32 v[140:141], v[140:141], v[156:157]
	v_mul_f32_e32 v156, 0xbfb8aa3b, v139
	v_exp_f32_e32 v179, v179
	v_exp_f32_e32 v156, v156
	v_add_f32_e32 v179, 1.0, v179
	v_add_f32_e32 v156, 1.0, v156
	v_rcp_f32_e32 v183, v179
	v_rcp_f32_e32 v185, v156
	v_pk_mul_f32 v[136:137], v[136:137], v[182:183]
	v_pk_mul_f32 v[138:139], v[138:139], v[184:185]

; __device__ __forceinline__ float silu_f(float x) { return x * __builtin_amdgcn_rcpf(1.0f + __builtin_amdgcn_exp2f(-1.4426950408889634f * x)); }
; __device__ __forceinline__ float gelu_tanh_f(float x) { const float u = (2.0f * 1.4426950408889634f * 0.7978845608028654f) * (x + 0.044715f * x * x * x); return x * __builtin_amdgcn_rcpf(1.0f + __builtin_amdgcn_exp2f(-u)); }
;     __device__ __forceinline__ void operator()(const f32x4 (&acc)[2][2][4][2], const pg8::Unit& u, int wr, int wc, int fr_, int fq_, int tid) {
;     ...
;             for (int ai = 0; ai < 2; ++ai)
; #pragma unroll
;                 for (int m = 0; m < 4; ++m) {
;                     const int s = s0 + ai * 128 + m * 16; const float rs = rsl[rl0 + ai * 128 + m * 16];
; #pragma unroll
;                     for (int bj = 0; bj < 2; ++bj) { const int head = 2 * (idx & 1) + bj;
;                         f32x4 v0 = acc[ai][bj][m][0] * rs, v1 = acc[ai][bj][m][1] * rs;
;                         if (kind == 1) {
; #pragma unroll
;                             for (int i = 0; i < 4; ++i) { v0[i] = silu_f(v0[i]); v1[i] = silu_f(v1[i]); } }
;                         if (kind >= 2) {
; #pragma unroll
;                             for (int i = 0; i < 4; ++i) { v0[i] = gelu_tanh_f(v0[i]); v1[i] = gelu_tanh_f(v1[i]); } }
;                         *(u32x4*)(base + ((size_t)(b * RETH + head) * SEQ + s) * HD + wc * 32 + 8 * fq) = pack8bf(v0, v1); }
.LBB0_410:
	v_cvt_pk_bf16_f32 v180, v140, v141
	v_cvt_pk_bf16_f32 v181, v136, v137
	v_cvt_pk_bf16_f32 v182, v132, v133
	s_nop 0
	v_cvt_pk_bf16_f32 v183, v138, v139
	ds_read_b32 v132, v158 offset:512
	v_lshl_add_u64 v[134:135], v[134:135], 0, s[42:43]
	s_and_b64 vcc, exec, s[8:9]
	global_store_dwordx4 v[134:135], v[180:183], off sc1
	s_waitcnt lgkmcnt(0)
	v_pk_mul_f32 v[136:137], v[64:65], v[132:133] op_sel_hi:[1,0]
	v_pk_mul_f32 v[140:141], v[62:63], v[132:133] op_sel_hi:[1,0]
	v_pk_mul_f32 v[138:139], v[60:61], v[132:133] op_sel_hi:[1,0]
	v_pk_mul_f32 v[156:157], v[58:59], v[132:133] op_sel_hi:[1,0]
	s_cbranch_vccnz .LBB0_412
	v_mul_f32_e32 v133, 0xbfb8aa3b, v140
	v_exp_f32_e32 v133, v133
	s_nop 0
	v_add_f32_e32 v133, 1.0, v133
	v_rcp_f32_e32 v134, v133
	v_mul_f32_e32 v133, 0xbfb8aa3b, v156
	v_exp_f32_e32 v133, v133
	s_nop 0
	v_add_f32_e32 v133, 1.0, v133
	v_rcp_f32_e32 v180, v133
	v_mul_f32_e32 v133, 0xbfb8aa3b, v141
	v_exp_f32_e32 v133, v133
	s_nop 0
	v_add_f32_e32 v133, 1.0, v133
	v_rcp_f32_e32 v135, v133
	v_mul_f32_e32 v133, 0xbfb8aa3b, v157
	v_exp_f32_e32 v133, v133
	v_pk_mul_f32 v[140:141], v[140:141], v[134:135]
	v_add_f32_e32 v133, 1.0, v133
	v_rcp_f32_e32 v181, v133
	v_mul_f32_e32 v133, 0xbfb8aa3b, v136
	v_exp_f32_e32 v133, v133
	v_pk_mul_f32 v[156:157], v[156:157], v[180:181]
	v_add_f32_e32 v133, 1.0, v133
	v_rcp_f32_e32 v182, v133
	v_mul_f32_e32 v133, 0xbfb8aa3b, v138
	v_exp_f32_e32 v133, v133
	s_nop 0
	v_add_f32_e32 v133, 1.0, v133
	v_rcp_f32_e32 v184, v133
	v_mul_f32_e32 v133, 0xbfb8aa3b, v137
	v_exp_f32_e32 v133, v133
	s_nop 0
	v_add_f32_e32 v133, 1.0, v133
	v_rcp_f32_e32 v183, v133
	v_mul_f32_e32 v133, 0xbfb8aa3b, v139
	v_exp_f32_e32 v133, v133
	v_pk_mul_f32 v[136:137], v[136:137], v[182:183]
	v_add_f32_e32 v133, 1.0, v133
	v_rcp_f32_e32 v185, v133
	s_nop 0
	v_pk_mul_f32 v[138:139], v[138:139], v[184:185]

; __device__ __forceinline__ float silu_f(float x) { return x * __builtin_amdgcn_rcpf(1.0f + __builtin_amdgcn_exp2f(-1.4426950408889634f * x)); }
; __device__ __forceinline__ float gelu_tanh_f(float x) { const float u = (2.0f * 1.4426950408889634f * 0.7978845608028654f) * (x + 0.044715f * x * x * x); return x * __builtin_amdgcn_rcpf(1.0f + __builtin_amdgcn_exp2f(-u)); }
;     __device__ __forceinline__ void operator()(const f32x4 (&acc)[2][2][4][2], const pg8::Unit& u, int wr, int wc, int fr_, int fq_, int tid) {
;     ...
;             for (int ai = 0; ai < 2; ++ai)
; #pragma unroll
;                 for (int m = 0; m < 4; ++m) {
;                     const int s = s0 + ai * 128 + m * 16; const float rs = rsl[rl0 + ai * 128 + m * 16];
; #pragma unroll
;                     for (int bj = 0; bj < 2; ++bj) { const int head = 2 * (idx & 1) + bj;
;                         f32x4 v0 = acc[ai][bj][m][0] * rs, v1 = acc[ai][bj][m][1] * rs;
;                         if (kind == 1) {
; #pragma unroll
;                             for (int i = 0; i < 4; ++i) { v0[i] = silu_f(v0[i]); v1[i] = silu_f(v1[i]); } }
;                         if (kind >= 2) {
; #pragma unroll
;                             for (int i = 0; i < 4; ++i) { v0[i] = gelu_tanh_f(v0[i]); v1[i] = gelu_tanh_f(v1[i]); } }
;                         *(u32x4*)(base + ((size_t)(b * RETH + head) * SEQ + s) * HD + wc * 32 + 8 * fq) = pack8bf(v0, v1); }
.LBB0_414:
	v_lshlrev_b64 v[134:135], 8, v[154:155]
	v_lshl_add_u64 v[134:135], v[130:131], 0, v[134:135]
	s_mov_b64 s[40:41], 0x8000
	v_lshl_add_u64 v[134:135], v[134:135], 0, s[40:41]
	v_mov_b32_e32 v133, v132
	v_cvt_pk_bf16_f32 v180, v140, v141
	v_cvt_pk_bf16_f32 v181, v136, v137
	v_cvt_pk_bf16_f32 v182, v156, v157
	v_cvt_pk_bf16_f32 v183, v138, v139
	v_lshl_add_u64 v[136:137], v[134:135], 0, s[0:1]
	v_mov_b32_e32 v138, v132
	v_mov_b32_e32 v139, v132
	global_store_dwordx4 v[136:137], v[180:183], off sc1
	v_pk_mul_f32 v[136:137], v[56:57], v[138:139]
	v_pk_mul_f32 v[140:141], v[54:55], v[132:133]
	v_pk_mul_f32 v[138:139], v[52:53], v[138:139]
	s_and_b64 vcc, exec, s[8:9]
	v_pk_mul_f32 v[132:133], v[50:51], v[132:133]
	s_cbranch_vccnz .LBB0_416
	v_mul_f32_e32 v179, 0xbfb8aa3b, v133
	v_exp_f32_e32 v179, v179
	v_mul_f32_e32 v157, 0xbfb8aa3b, v132
	v_exp_f32_e32 v157, v157
	v_mul_f32_e32 v156, 0xbfb8aa3b, v140
	v_add_f32_e32 v179, 1.0, v179
	v_rcp_f32_e32 v181, v179
	v_mul_f32_e32 v179, 0xbfb8aa3b, v136
	v_add_f32_e32 v157, 1.0, v157
	v_exp_f32_e32 v179, v179
	v_rcp_f32_e32 v180, v157
	v_mul_f32_e32 v157, 0xbfb8aa3b, v141
	v_exp_f32_e32 v156, v156
	v_exp_f32_e32 v157, v157
	v_add_f32_e32 v179, 1.0, v179
	v_rcp_f32_e32 v182, v179
	v_mul_f32_e32 v179, 0xbfb8aa3b, v138
	v_add_f32_e32 v156, 1.0, v156
	v_add_f32_e32 v157, 1.0, v157
	v_exp_f32_e32 v179, v179
	v_rcp_f32_e32 v156, v156
	v_rcp_f32_e32 v157, v157
	v_pk_mul_f32 v[132:133], v[132:133], v[180:181]
	v_add_f32_e32 v179, 1.0, v179
	v_rcp_f32_e32 v184, v179
	v_mul_f32_e32 v179, 0xbfb8aa3b, v137
	v_pk_mul_f32 v[140:141], v[140:141], v[156:157]
	v_mul_f32_e32 v156, 0xbfb8aa3b, v139
	v_exp_f32_e32 v179, v179
	v_exp_f32_e32 v156, v156
	v_add_f32_e32 v179, 1.0, v179
	v_add_f32_e32 v156, 1.0, v156
	v_rcp_f32_e32 v183, v179
	v_rcp_f32_e32 v185, v156
	v_pk_mul_f32 v[136:137], v[136:137], v[182:183]
	v_pk_mul_f32 v[138:139], v[138:139], v[184:185]

; __device__ __forceinline__ float silu_f(float x) { return x * __builtin_amdgcn_rcpf(1.0f + __builtin_amdgcn_exp2f(-1.4426950408889634f * x)); }
; __device__ __forceinline__ float gelu_tanh_f(float x) { const float u = (2.0f * 1.4426950408889634f * 0.7978845608028654f) * (x + 0.044715f * x * x * x); return x * __builtin_amdgcn_rcpf(1.0f + __builtin_amdgcn_exp2f(-u)); }
;     __device__ __forceinline__ void operator()(const f32x4 (&acc)[2][2][4][2], const pg8::Unit& u, int wr, int wc, int fr_, int fq_, int tid) {
;     ...
;             for (int ai = 0; ai < 2; ++ai)
; #pragma unroll
;                 for (int m = 0; m < 4; ++m) {
;                     const int s = s0 + ai * 128 + m * 16; const float rs = rsl[rl0 + ai * 128 + m * 16];
; #pragma unroll
;                     for (int bj = 0; bj < 2; ++bj) { const int head = 2 * (idx & 1) + bj;
;                         f32x4 v0 = acc[ai][bj][m][0] * rs, v1 = acc[ai][bj][m][1] * rs;
;                         if (kind == 1) {
; #pragma unroll
;                             for (int i = 0; i < 4; ++i) { v0[i] = silu_f(v0[i]); v1[i] = silu_f(v1[i]); } }
;                         if (kind >= 2) {
; #pragma unroll
;                             for (int i = 0; i < 4; ++i) { v0[i] = gelu_tanh_f(v0[i]); v1[i] = gelu_tanh_f(v1[i]); } }
;                         *(u32x4*)(base + ((size_t)(b * RETH + head) * SEQ + s) * HD + wc * 32 + 8 * fq) = pack8bf(v0, v1); }
.LBB0_418:
	v_cvt_pk_bf16_f32 v180, v140, v141
	v_cvt_pk_bf16_f32 v181, v136, v137
	v_cvt_pk_bf16_f32 v182, v132, v133
	s_nop 0
	v_cvt_pk_bf16_f32 v183, v138, v139
	ds_read_b32 v132, v158 offset:576
	v_lshl_add_u64 v[134:135], v[134:135], 0, s[42:43]
	s_and_b64 vcc, exec, s[8:9]
	global_store_dwordx4 v[134:135], v[180:183], off sc1
	s_waitcnt lgkmcnt(0)
	v_pk_mul_f32 v[136:137], v[48:49], v[132:133] op_sel_hi:[1,0]
	v_pk_mul_f32 v[140:141], v[46:47], v[132:133] op_sel_hi:[1,0]
	v_pk_mul_f32 v[138:139], v[44:45], v[132:133] op_sel_hi:[1,0]
	v_pk_mul_f32 v[156:157], v[42:43], v[132:133] op_sel_hi:[1,0]
	s_cbranch_vccnz .LBB0_420
	v_mul_f32_e32 v133, 0xbfb8aa3b, v140
	v_exp_f32_e32 v133, v133
	s_nop 0
	v_add_f32_e32 v133, 1.0, v133
	v_rcp_f32_e32 v134, v133
	v_mul_f32_e32 v133, 0xbfb8aa3b, v156
	v_exp_f32_e32 v133, v133
	s_nop 0
	v_add_f32_e32 v133, 1.0, v133
	v_rcp_f32_e32 v180, v133
	v_mul_f32_e32 v133, 0xbfb8aa3b, v141
	v_exp_f32_e32 v133, v133
	s_nop 0
	v_add_f32_e32 v133, 1.0, v133
	v_rcp_f32_e32 v135, v133
	v_mul_f32_e32 v133, 0xbfb8aa3b, v157
	v_exp_f32_e32 v133, v133
	v_pk_mul_f32 v[140:141], v[140:141], v[134:135]
	v_add_f32_e32 v133, 1.0, v133
	v_rcp_f32_e32 v181, v133
	v_mul_f32_e32 v133, 0xbfb8aa3b, v136
	v_exp_f32_e32 v133, v133
	v_pk_mul_f32 v[156:157], v[156:157], v[180:181]
	v_add_f32_e32 v133, 1.0, v133
	v_rcp_f32_e32 v182, v133
	v_mul_f32_e32 v133, 0xbfb8aa3b, v138
	v_exp_f32_e32 v133, v133
	s_nop 0
	v_add_f32_e32 v133, 1.0, v133
	v_rcp_f32_e32 v184, v133
	v_mul_f32_e32 v133, 0xbfb8aa3b, v137
	v_exp_f32_e32 v133, v133
	s_nop 0
	v_add_f32_e32 v133, 1.0, v133
	v_rcp_f32_e32 v183, v133
	v_mul_f32_e32 v133, 0xbfb8aa3b, v139
	v_exp_f32_e32 v133, v133
	v_pk_mul_f32 v[136:137], v[136:137], v[182:183]
	v_add_f32_e32 v133, 1.0, v133
	v_rcp_f32_e32 v185, v133
	s_nop 0
	v_pk_mul_f32 v[138:139], v[138:139], v[184:185]

; __device__ __forceinline__ float silu_f(float x) { return x * __builtin_amdgcn_rcpf(1.0f + __builtin_amdgcn_exp2f(-1.4426950408889634f * x)); }
; __device__ __forceinline__ float gelu_tanh_f(float x) { const float u = (2.0f * 1.4426950408889634f * 0.7978845608028654f) * (x + 0.044715f * x * x * x); return x * __builtin_amdgcn_rcpf(1.0f + __builtin_amdgcn_exp2f(-u)); }
;     __device__ __forceinline__ void operator()(const f32x4 (&acc)[2][2][4][2], const pg8::Unit& u, int wr, int wc, int fr_, int fq_, int tid) {
;     ...
;             for (int ai = 0; ai < 2; ++ai)
; #pragma unroll
;                 for (int m = 0; m < 4; ++m) {
;                     const int s = s0 + ai * 128 + m * 16; const float rs = rsl[rl0 + ai * 128 + m * 16];
; #pragma unroll
;                     for (int bj = 0; bj < 2; ++bj) { const int head = 2 * (idx & 1) + bj;
;                         f32x4 v0 = acc[ai][bj][m][0] * rs, v1 = acc[ai][bj][m][1] * rs;
;                         if (kind == 1) {
; #pragma unroll
;                             for (int i = 0; i < 4; ++i) { v0[i] = silu_f(v0[i]); v1[i] = silu_f(v1[i]); } }
;                         if (kind >= 2) {
; #pragma unroll
;                             for (int i = 0; i < 4; ++i) { v0[i] = gelu_tanh_f(v0[i]); v1[i] = gelu_tanh_f(v1[i]); } }
;                         *(u32x4*)(base + ((size_t)(b * RETH + head) * SEQ + s) * HD + wc * 32 + 8 * fq) = pack8bf(v0, v1); }
.LBB0_422:
	v_lshlrev_b64 v[134:135], 8, v[154:155]
	v_lshl_add_u64 v[134:135], v[130:131], 0, v[134:135]
	s_mov_b64 s[40:41], 0x9000
	v_lshl_add_u64 v[134:135], v[134:135], 0, s[40:41]
	v_mov_b32_e32 v133, v132
	v_cvt_pk_bf16_f32 v180, v140, v141
	v_cvt_pk_bf16_f32 v181, v136, v137
	v_cvt_pk_bf16_f32 v182, v156, v157
	v_cvt_pk_bf16_f32 v183, v138, v139
	v_lshl_add_u64 v[136:137], v[134:135], 0, s[0:1]
	v_mov_b32_e32 v138, v132
	v_mov_b32_e32 v139, v132
	global_store_dwordx4 v[136:137], v[180:183], off sc1
	v_pk_mul_f32 v[136:137], v[40:41], v[138:139]
	v_pk_mul_f32 v[140:141], v[38:39], v[132:133]
	v_pk_mul_f32 v[138:139], v[36:37], v[138:139]
	s_and_b64 vcc, exec, s[8:9]
	v_pk_mul_f32 v[132:133], v[34:35], v[132:133]
	s_cbranch_vccnz .LBB0_424
	v_mul_f32_e32 v179, 0xbfb8aa3b, v133
	v_exp_f32_e32 v179, v179
	v_mul_f32_e32 v157, 0xbfb8aa3b, v132
	v_exp_f32_e32 v157, v157
	v_mul_f32_e32 v156, 0xbfb8aa3b, v140
	v_add_f32_e32 v179, 1.0, v179
	v_rcp_f32_e32 v181, v179
	v_mul_f32_e32 v179, 0xbfb8aa3b, v136
	v_add_f32_e32 v157, 1.0, v157
	v_exp_f32_e32 v179, v179
	v_rcp_f32_e32 v180, v157
	v_mul_f32_e32 v157, 0xbfb8aa3b, v141
	v_exp_f32_e32 v156, v156
	v_exp_f32_e32 v157, v157
	v_add_f32_e32 v179, 1.0, v179
	v_rcp_f32_e32 v182, v179
	v_mul_f32_e32 v179, 0xbfb8aa3b, v138
	v_add_f32_e32 v156, 1.0, v156
	v_add_f32_e32 v157, 1.0, v157
	v_exp_f32_e32 v179, v179
	v_rcp_f32_e32 v156, v156
	v_rcp_f32_e32 v157, v157
	v_pk_mul_f32 v[132:133], v[132:133], v[180:181]
	v_add_f32_e32 v179, 1.0, v179
	v_rcp_f32_e32 v184, v179
	v_mul_f32_e32 v179, 0xbfb8aa3b, v137
	v_pk_mul_f32 v[140:141], v[140:141], v[156:157]
	v_mul_f32_e32 v156, 0xbfb8aa3b, v139
	v_exp_f32_e32 v179, v179
	v_exp_f32_e32 v156, v156
	v_add_f32_e32 v179, 1.0, v179
	v_add_f32_e32 v156, 1.0, v156
	v_rcp_f32_e32 v183, v179
	v_rcp_f32_e32 v185, v156
	v_pk_mul_f32 v[136:137], v[136:137], v[182:183]
	v_pk_mul_f32 v[138:139], v[138:139], v[184:185]

; __device__ __forceinline__ float silu_f(float x) { return x * __builtin_amdgcn_rcpf(1.0f + __builtin_amdgcn_exp2f(-1.4426950408889634f * x)); }
; __device__ __forceinline__ float gelu_tanh_f(float x) { const float u = (2.0f * 1.4426950408889634f * 0.7978845608028654f) * (x + 0.044715f * x * x * x); return x * __builtin_amdgcn_rcpf(1.0f + __builtin_amdgcn_exp2f(-u)); }
;     __device__ __forceinline__ void operator()(const f32x4 (&acc)[2][2][4][2], const pg8::Unit& u, int wr, int wc, int fr_, int fq_, int tid) {
;     ...
;             for (int ai = 0; ai < 2; ++ai)
; #pragma unroll
;                 for (int m = 0; m < 4; ++m) {
;                     const int s = s0 + ai * 128 + m * 16; const float rs = rsl[rl0 + ai * 128 + m * 16];
; #pragma unroll
;                     for (int bj = 0; bj < 2; ++bj) { const int head = 2 * (idx & 1) + bj;
;                         f32x4 v0 = acc[ai][bj][m][0] * rs, v1 = acc[ai][bj][m][1] * rs;
;                         if (kind == 1) {
; #pragma unroll
;                             for (int i = 0; i < 4; ++i) { v0[i] = silu_f(v0[i]); v1[i] = silu_f(v1[i]); } }
;                         if (kind >= 2) {
; #pragma unroll
;                             for (int i = 0; i < 4; ++i) { v0[i] = gelu_tanh_f(v0[i]); v1[i] = gelu_tanh_f(v1[i]); } }
;                         *(u32x4*)(base + ((size_t)(b * RETH + head) * SEQ + s) * HD + wc * 32 + 8 * fq) = pack8bf(v0, v1); }
.LBB0_426:
	v_cvt_pk_bf16_f32 v180, v140, v141
	v_cvt_pk_bf16_f32 v181, v136, v137
	v_cvt_pk_bf16_f32 v182, v132, v133
	s_nop 0
	v_cvt_pk_bf16_f32 v183, v138, v139
	ds_read_b32 v132, v158 offset:640
	v_lshl_add_u64 v[134:135], v[134:135], 0, s[42:43]
	s_and_b64 vcc, exec, s[8:9]
	global_store_dwordx4 v[134:135], v[180:183], off sc1
	s_waitcnt lgkmcnt(0)
	v_pk_mul_f32 v[136:137], v[32:33], v[132:133] op_sel_hi:[1,0]
	v_pk_mul_f32 v[140:141], v[30:31], v[132:133] op_sel_hi:[1,0]
	v_pk_mul_f32 v[138:139], v[28:29], v[132:133] op_sel_hi:[1,0]
	v_pk_mul_f32 v[156:157], v[26:27], v[132:133] op_sel_hi:[1,0]
	s_cbranch_vccnz .LBB0_428
	v_mul_f32_e32 v133, 0xbfb8aa3b, v140
	v_exp_f32_e32 v133, v133
	s_nop 0
	v_add_f32_e32 v133, 1.0, v133
	v_rcp_f32_e32 v134, v133
	v_mul_f32_e32 v133, 0xbfb8aa3b, v156
	v_exp_f32_e32 v133, v133
	s_nop 0
	v_add_f32_e32 v133, 1.0, v133
	v_rcp_f32_e32 v180, v133
	v_mul_f32_e32 v133, 0xbfb8aa3b, v141
	v_exp_f32_e32 v133, v133
	s_nop 0
	v_add_f32_e32 v133, 1.0, v133
	v_rcp_f32_e32 v135, v133
	v_mul_f32_e32 v133, 0xbfb8aa3b, v157
	v_exp_f32_e32 v133, v133
	v_pk_mul_f32 v[140:141], v[140:141], v[134:135]
	v_add_f32_e32 v133, 1.0, v133
	v_rcp_f32_e32 v181, v133
	v_mul_f32_e32 v133, 0xbfb8aa3b, v136
	v_exp_f32_e32 v133, v133
	v_pk_mul_f32 v[156:157], v[156:157], v[180:181]
	v_add_f32_e32 v133, 1.0, v133
	v_rcp_f32_e32 v182, v133
	v_mul_f32_e32 v133, 0xbfb8aa3b, v138
	v_exp_f32_e32 v133, v133
	s_nop 0
	v_add_f32_e32 v133, 1.0, v133
	v_rcp_f32_e32 v184, v133
	v_mul_f32_e32 v133, 0xbfb8aa3b, v137
	v_exp_f32_e32 v133, v133
	s_nop 0
	v_add_f32_e32 v133, 1.0, v133
	v_rcp_f32_e32 v183, v133
	v_mul_f32_e32 v133, 0xbfb8aa3b, v139
	v_exp_f32_e32 v133, v133
	v_pk_mul_f32 v[136:137], v[136:137], v[182:183]
	v_add_f32_e32 v133, 1.0, v133
	v_rcp_f32_e32 v185, v133
	s_nop 0
	v_pk_mul_f32 v[138:139], v[138:139], v[184:185]

; __device__ __forceinline__ float silu_f(float x) { return x * __builtin_amdgcn_rcpf(1.0f + __builtin_amdgcn_exp2f(-1.4426950408889634f * x)); }
; __device__ __forceinline__ float gelu_tanh_f(float x) { const float u = (2.0f * 1.4426950408889634f * 0.7978845608028654f) * (x + 0.044715f * x * x * x); return x * __builtin_amdgcn_rcpf(1.0f + __builtin_amdgcn_exp2f(-u)); }
;     __device__ __forceinline__ void operator()(const f32x4 (&acc)[2][2][4][2], const pg8::Unit& u, int wr, int wc, int fr_, int fq_, int tid) {
;     ...
;             for (int ai = 0; ai < 2; ++ai)
; #pragma unroll
;                 for (int m = 0; m < 4; ++m) {
;                     const int s = s0 + ai * 128 + m * 16; const float rs = rsl[rl0 + ai * 128 + m * 16];
; #pragma unroll
;                     for (int bj = 0; bj < 2; ++bj) { const int head = 2 * (idx & 1) + bj;
;                         f32x4 v0 = acc[ai][bj][m][0] * rs, v1 = acc[ai][bj][m][1] * rs;
;                         if (kind == 1) {
; #pragma unroll
;                             for (int i = 0; i < 4; ++i) { v0[i] = silu_f(v0[i]); v1[i] = silu_f(v1[i]); } }
;                         if (kind >= 2) {
; #pragma unroll
;                             for (int i = 0; i < 4; ++i) { v0[i] = gelu_tanh_f(v0[i]); v1[i] = gelu_tanh_f(v1[i]); } }
;                         *(u32x4*)(base + ((size_t)(b * RETH + head) * SEQ + s) * HD + wc * 32 + 8 * fq) = pack8bf(v0, v1); }
.LBB0_430:
	v_lshlrev_b64 v[134:135], 8, v[154:155]
	v_lshl_add_u64 v[134:135], v[130:131], 0, v[134:135]
	s_mov_b64 s[40:41], 0xa000
	v_lshl_add_u64 v[134:135], v[134:135], 0, s[40:41]
	v_mov_b32_e32 v133, v132
	v_cvt_pk_bf16_f32 v180, v140, v141
	v_cvt_pk_bf16_f32 v181, v136, v137
	v_cvt_pk_bf16_f32 v182, v156, v157
	v_cvt_pk_bf16_f32 v183, v138, v139
	v_lshl_add_u64 v[136:137], v[134:135], 0, s[0:1]
	v_mov_b32_e32 v138, v132
	v_mov_b32_e32 v139, v132
	global_store_dwordx4 v[136:137], v[180:183], off sc1
	v_pk_mul_f32 v[136:137], v[24:25], v[138:139]
	v_pk_mul_f32 v[140:141], v[22:23], v[132:133]
	v_pk_mul_f32 v[138:139], v[20:21], v[138:139]
	s_and_b64 vcc, exec, s[8:9]
	v_pk_mul_f32 v[132:133], v[18:19], v[132:133]
	s_cbranch_vccnz .LBB0_432
	v_mul_f32_e32 v179, 0xbfb8aa3b, v133
	v_exp_f32_e32 v179, v179
	v_mul_f32_e32 v157, 0xbfb8aa3b, v132
	v_exp_f32_e32 v157, v157
	v_mul_f32_e32 v156, 0xbfb8aa3b, v140
	v_add_f32_e32 v179, 1.0, v179
	v_rcp_f32_e32 v181, v179
	v_mul_f32_e32 v179, 0xbfb8aa3b, v136
	v_add_f32_e32 v157, 1.0, v157
	v_exp_f32_e32 v179, v179
	v_rcp_f32_e32 v180, v157
	v_mul_f32_e32 v157, 0xbfb8aa3b, v141
	v_exp_f32_e32 v156, v156
	v_exp_f32_e32 v157, v157
	v_add_f32_e32 v179, 1.0, v179
	v_rcp_f32_e32 v182, v179
	v_mul_f32_e32 v179, 0xbfb8aa3b, v138
	v_add_f32_e32 v156, 1.0, v156
	v_add_f32_e32 v157, 1.0, v157
	v_exp_f32_e32 v179, v179
	v_rcp_f32_e32 v156, v156
	v_rcp_f32_e32 v157, v157
	v_pk_mul_f32 v[132:133], v[132:133], v[180:181]
	v_add_f32_e32 v179, 1.0, v179
	v_rcp_f32_e32 v184, v179
	v_mul_f32_e32 v179, 0xbfb8aa3b, v137
	v_pk_mul_f32 v[140:141], v[140:141], v[156:157]
	v_mul_f32_e32 v156, 0xbfb8aa3b, v139
	v_exp_f32_e32 v179, v179
	v_exp_f32_e32 v156, v156
	v_add_f32_e32 v179, 1.0, v179
	v_add_f32_e32 v156, 1.0, v156
	v_rcp_f32_e32 v183, v179
	v_rcp_f32_e32 v185, v156
	v_pk_mul_f32 v[136:137], v[136:137], v[182:183]
	v_pk_mul_f32 v[138:139], v[138:139], v[184:185]

; __device__ __forceinline__ float silu_f(float x) { return x * __builtin_amdgcn_rcpf(1.0f + __builtin_amdgcn_exp2f(-1.4426950408889634f * x)); }
; __device__ __forceinline__ float gelu_tanh_f(float x) { const float u = (2.0f * 1.4426950408889634f * 0.7978845608028654f) * (x + 0.044715f * x * x * x); return x * __builtin_amdgcn_rcpf(1.0f + __builtin_amdgcn_exp2f(-u)); }
;     __device__ __forceinline__ void operator()(const f32x4 (&acc)[2][2][4][2], const pg8::Unit& u, int wr, int wc, int fr_, int fq_, int tid) {
;     ...
;             for (int ai = 0; ai < 2; ++ai)
; #pragma unroll
;                 for (int m = 0; m < 4; ++m) {
;                     const int s = s0 + ai * 128 + m * 16; const float rs = rsl[rl0 + ai * 128 + m * 16];
; #pragma unroll
;                     for (int bj = 0; bj < 2; ++bj) { const int head = 2 * (idx & 1) + bj;
;                         f32x4 v0 = acc[ai][bj][m][0] * rs, v1 = acc[ai][bj][m][1] * rs;
;                         if (kind == 1) {
; #pragma unroll
;                             for (int i = 0; i < 4; ++i) { v0[i] = silu_f(v0[i]); v1[i] = silu_f(v1[i]); } }
;                         if (kind >= 2) {
; #pragma unroll
;                             for (int i = 0; i < 4; ++i) { v0[i] = gelu_tanh_f(v0[i]); v1[i] = gelu_tanh_f(v1[i]); } }
;                         *(u32x4*)(base + ((size_t)(b * RETH + head) * SEQ + s) * HD + wc * 32 + 8 * fq) = pack8bf(v0, v1); }
.LBB0_434:
	v_cvt_pk_bf16_f32 v180, v140, v141
	v_cvt_pk_bf16_f32 v181, v136, v137
	v_cvt_pk_bf16_f32 v182, v132, v133
	s_nop 0
	v_cvt_pk_bf16_f32 v183, v138, v139
	ds_read_b32 v132, v158 offset:704
	v_lshl_add_u64 v[134:135], v[134:135], 0, s[42:43]
	global_store_dwordx4 v[134:135], v[180:183], off sc1
	s_and_b64 vcc, exec, s[8:9]
	s_waitcnt lgkmcnt(0)
	v_pk_mul_f32 v[134:135], v[16:17], v[132:133] op_sel_hi:[1,0]
	v_pk_mul_f32 v[138:139], v[14:15], v[132:133] op_sel_hi:[1,0]
	v_pk_mul_f32 v[136:137], v[12:13], v[132:133] op_sel_hi:[1,0]
	v_pk_mul_f32 v[140:141], v[10:11], v[132:133] op_sel_hi:[1,0]
	s_cbranch_vccnz .LBB0_436
	v_mul_f32_e32 v133, 0xbfb8aa3b, v138
	v_exp_f32_e32 v133, v133
	s_nop 0
	v_add_f32_e32 v133, 1.0, v133
	v_rcp_f32_e32 v156, v133
	v_mul_f32_e32 v133, 0xbfb8aa3b, v140
	v_exp_f32_e32 v133, v133
	s_nop 0
	v_add_f32_e32 v133, 1.0, v133
	v_rcp_f32_e32 v180, v133
	v_mul_f32_e32 v133, 0xbfb8aa3b, v139
	v_exp_f32_e32 v133, v133
	s_nop 0
	v_add_f32_e32 v133, 1.0, v133
	v_rcp_f32_e32 v157, v133
	v_mul_f32_e32 v133, 0xbfb8aa3b, v141
	v_exp_f32_e32 v133, v133
	v_pk_mul_f32 v[138:139], v[138:139], v[156:157]
	v_add_f32_e32 v133, 1.0, v133
	v_rcp_f32_e32 v181, v133
	v_mul_f32_e32 v133, 0xbfb8aa3b, v134
	v_exp_f32_e32 v133, v133
	v_pk_mul_f32 v[140:141], v[140:141], v[180:181]
	v_add_f32_e32 v133, 1.0, v133
	v_rcp_f32_e32 v182, v133
	v_mul_f32_e32 v133, 0xbfb8aa3b, v136
	v_exp_f32_e32 v133, v133
	s_nop 0
	v_add_f32_e32 v133, 1.0, v133
	v_rcp_f32_e32 v184, v133
	v_mul_f32_e32 v133, 0xbfb8aa3b, v135
	v_exp_f32_e32 v133, v133
	s_nop 0
	v_add_f32_e32 v133, 1.0, v133
	v_rcp_f32_e32 v183, v133
	v_mul_f32_e32 v133, 0xbfb8aa3b, v137
	v_exp_f32_e32 v133, v133
	v_pk_mul_f32 v[134:135], v[134:135], v[182:183]
	v_add_f32_e32 v133, 1.0, v133
	v_rcp_f32_e32 v185, v133
	s_nop 0
	v_pk_mul_f32 v[136:137], v[136:137], v[184:185]

; __device__ __forceinline__ float silu_f(float x) { return x * __builtin_amdgcn_rcpf(1.0f + __builtin_amdgcn_exp2f(-1.4426950408889634f * x)); }
; __device__ __forceinline__ float gelu_tanh_f(float x) { const float u = (2.0f * 1.4426950408889634f * 0.7978845608028654f) * (x + 0.044715f * x * x * x); return x * __builtin_amdgcn_rcpf(1.0f + __builtin_amdgcn_exp2f(-u)); }
;     __device__ __forceinline__ void operator()(const f32x4 (&acc)[2][2][4][2], const pg8::Unit& u, int wr, int wc, int fr_, int fq_, int tid) {
;     ...
;             for (int ai = 0; ai < 2; ++ai)
; #pragma unroll
;                 for (int m = 0; m < 4; ++m) {
;                     const int s = s0 + ai * 128 + m * 16; const float rs = rsl[rl0 + ai * 128 + m * 16];
; #pragma unroll
;                     for (int bj = 0; bj < 2; ++bj) { const int head = 2 * (idx & 1) + bj;
;                         f32x4 v0 = acc[ai][bj][m][0] * rs, v1 = acc[ai][bj][m][1] * rs;
;                         if (kind == 1) {
; #pragma unroll
;                             for (int i = 0; i < 4; ++i) { v0[i] = silu_f(v0[i]); v1[i] = silu_f(v1[i]); } }
;                         if (kind >= 2) {
; #pragma unroll
;                             for (int i = 0; i < 4; ++i) { v0[i] = gelu_tanh_f(v0[i]); v1[i] = gelu_tanh_f(v1[i]); } }
;                         *(u32x4*)(base + ((size_t)(b * RETH + head) * SEQ + s) * HD + wc * 32 + 8 * fq) = pack8bf(v0, v1); }
.LBB0_438:
	v_lshlrev_b64 v[156:157], 8, v[154:155]
	v_lshl_add_u64 v[130:131], v[130:131], 0, v[156:157]
	s_mov_b64 s[40:41], 0xb000
	v_lshl_add_u64 v[130:131], v[130:131], 0, s[40:41]
	v_mov_b32_e32 v133, v132
	v_cvt_pk_bf16_f32 v138, v138, v139
	v_cvt_pk_bf16_f32 v139, v134, v135
	v_cvt_pk_bf16_f32 v140, v140, v141
	v_cvt_pk_bf16_f32 v141, v136, v137
	v_lshl_add_u64 v[134:135], v[130:131], 0, s[0:1]
	v_mov_b32_e32 v136, v132
	v_mov_b32_e32 v137, v132
	global_store_dwordx4 v[134:135], v[138:141], off sc1
	v_pk_mul_f32 v[134:135], v[8:9], v[136:137]
	v_pk_mul_f32 v[136:137], v[4:5], v[136:137]
	v_pk_mul_f32 v[138:139], v[6:7], v[132:133]
	s_and_b64 vcc, exec, s[8:9]
	v_pk_mul_f32 v[132:133], v[2:3], v[132:133]
	s_cbranch_vccnz .LBB0_440
	v_mul_f32_e32 v155, 0xbfb8aa3b, v133
	v_exp_f32_e32 v155, v155
	v_mul_f32_e32 v141, 0xbfb8aa3b, v132
	v_exp_f32_e32 v141, v141
	v_mul_f32_e32 v140, 0xbfb8aa3b, v138
	v_add_f32_e32 v155, 1.0, v155
	v_rcp_f32_e32 v157, v155
	v_mul_f32_e32 v155, 0xbfb8aa3b, v134
	v_add_f32_e32 v141, 1.0, v141
	v_exp_f32_e32 v155, v155
	v_rcp_f32_e32 v156, v141
	v_mul_f32_e32 v141, 0xbfb8aa3b, v139
	v_exp_f32_e32 v140, v140
	v_exp_f32_e32 v141, v141
	v_add_f32_e32 v155, 1.0, v155
	v_rcp_f32_e32 v180, v155
	v_mul_f32_e32 v155, 0xbfb8aa3b, v136
	v_add_f32_e32 v140, 1.0, v140
	v_add_f32_e32 v141, 1.0, v141
	v_exp_f32_e32 v155, v155
	v_rcp_f32_e32 v140, v140
	v_rcp_f32_e32 v141, v141
	v_pk_mul_f32 v[132:133], v[132:133], v[156:157]
	v_add_f32_e32 v155, 1.0, v155
	v_rcp_f32_e32 v182, v155
	v_mul_f32_e32 v155, 0xbfb8aa3b, v135
	v_pk_mul_f32 v[138:139], v[138:139], v[140:141]
	v_mul_f32_e32 v140, 0xbfb8aa3b, v137
	v_exp_f32_e32 v155, v155
	v_exp_f32_e32 v140, v140
	v_add_f32_e32 v155, 1.0, v155
	v_add_f32_e32 v140, 1.0, v140
	v_rcp_f32_e32 v181, v155
	v_rcp_f32_e32 v183, v140
	v_pk_mul_f32 v[134:135], v[134:135], v[180:181]
	v_pk_mul_f32 v[136:137], v[136:137], v[182:183]

;     __device__ __forceinline__ void operator()(const f32x4 (&acc)[2][2][4][2], const pg8::Unit& u, int wr, int wc, int fr_, int fq_, int tid) {
;     ...
;         } else if (pn < 16) {
;             const int seg = (pn - 12) >> 1, hh = 2 * ((pn - 12) & 1) + (wc >> 1), dp = 32 * (wc & 1) + 8 * fq;
;             bf16_t* base = RQ + (size_t)seg * (SZ_R / 2); const float ksc = seg ? 0.08838834764831845f : 1.0f;
; #pragma unroll
;             for (int ai = 0; ai < 2; ++ai)
; #pragma unroll
;                 for (int m = 0; m < 4; ++m) {
;                     const int s = s0 + ai * 128 + m * 16; const float rs = rsl[rl0 + ai * 128 + m * 16] * ksc;
;                     const f32x4 c0 = *(const f32x4*)(ropec + (size_t)s * 64 + dp), c1 = *(const f32x4*)(ropec + (size_t)s * 64 + dp + 4);
;                     const f32x4 n0 = *(const f32x4*)(ropes + (size_t)s * 64 + dp), n1 = *(const f32x4*)(ropes + (size_t)s * 64 + dp + 4);
;                     const f32x4 a0 = acc[ai][0][m][0] * rs, a1 = acc[ai][0][m][1] * rs, b0 = acc[ai][1][m][0] * rs, b1 = acc[ai][1][m][1] * rs;
;                     bf16_t* dst = base + ((size_t)(b * RETH + hh) * SEQ + s) * HD + dp;
;                     *(u32x4*)(dst) = pack8bf(a0 * c0 - b0 * n0, a1 * c1 - b1 * n1);
;                     *(u32x4*)(dst + 64) = pack8bf(a0 * n0 + b0 * c0, a1 * n1 + b1 * c1);
;                     if (m & 1) asm volatile("" ::: "memory");
;                 }
.LBB0_442:
	v_lshl_add_u64 v[130:131], v[130:131], 0, s[42:43]
	v_cvt_pk_bf16_f32 v138, v138, v139
	v_cvt_pk_bf16_f32 v139, v134, v135
	v_cvt_pk_bf16_f32 v140, v132, v133
	v_cvt_pk_bf16_f32 v141, v136, v137
	global_store_dwordx4 v[130:131], v[138:141], off sc1
	s_mov_b64 s[0:1], 0
.LBB0_443:
	s_and_b64 vcc, exec, s[0:1]
	s_cbranch_vccz .LBB0_445
	s_add_i32 s8, s38, -12
	s_lshl_b32 s0, s38, 1
	s_lshr_b32 s96, s8, 1
	s_and_b32 s0, s0, 2
	s_or_b32 s9, s67, s0
	s_lshl_b64 s[0:1], s[96:97], 24
	s_add_u32 s10, s57, s0
	s_addc_u32 s11, s58, s1
	s_cmp_lt_u32 s8, 2
	v_lshl_add_u32 v132, v178, 2, 0
	s_cselect_b64 s[0:1], -1, 0
	s_waitcnt lgkmcnt(0)
	v_mov_b32_e32 v131, 0x3db504f3
	v_add_u32_e32 v136, 0x20400, v132
	v_cndmask_b32_e64 v135, v131, 1.0, s[0:1]
	s_lshl_b32 s0, s29, 2
	ds_read_b32 v132, v136
	s_or_b32 s0, s9, s0
	s_ashr_i32 s1, s0, 31
	s_lshl_b64 s[0:1], s[0:1], 20
	v_lshl_add_u32 v130, v176, 3, s68
	s_add_u32 s0, s10, s0
	v_ashrrev_i32_e32 v155, 31, v154
	v_ashrrev_i32_e32 v131, 31, v130
	s_addc_u32 s1, s11, s1
	s_waitcnt lgkmcnt(0)
	v_mul_f32_e32 v134, v135, v132
	v_lshlrev_b64 v[132:133], 8, v[154:155]
	v_lshl_add_u64 v[156:157], v[130:131], 1, s[0:1]
	v_lshl_add_u64 v[138:139], s[22:23], 0, v[132:133]
	v_lshlrev_b64 v[130:131], 2, v[130:131]
	v_lshl_add_u64 v[184:185], s[24:25], 0, v[132:133]
	v_lshl_add_u64 v[180:181], v[138:139], 0, v[130:131]
	v_lshl_add_u64 v[188:189], v[184:185], 0, v[130:131]
	global_load_dwordx4 v[138:141], v[180:181], off offset:16
	s_nop 0
	global_load_dwordx4 v[180:183], v[180:181], off
	s_nop 0
	global_load_dwordx4 v[184:187], v[188:189], off offset:16
	s_nop 0
	global_load_dwordx4 v[188:191], v[188:189], off
	v_pk_mul_f32 v[228:229], v[118:119], v[134:135] op_sel_hi:[1,0]
	v_pk_mul_f32 v[230:231], v[120:121], v[134:135] op_sel_hi:[1,0]
	v_pk_mul_f32 v[220:221], v[126:127], v[134:135] op_sel_hi:[1,0]
	v_pk_mul_f32 v[222:223], v[128:129], v[134:135] op_sel_hi:[1,0]
	v_pk_mul_f32 v[232:233], v[114:115], v[134:135] op_sel_hi:[1,0]
	v_pk_mul_f32 v[234:235], v[116:117], v[134:135] op_sel_hi:[1,0]
	v_pk_mul_f32 v[224:225], v[122:123], v[134:135] op_sel_hi:[1,0]
	v_pk_mul_f32 v[226:227], v[124:125], v[134:135] op_sel_hi:[1,0]
	v_lshl_add_u64 v[236:237], v[156:157], 0, v[132:133]
	s_mov_b64 s[0:1], 0x1000
	s_waitcnt vmcnt(0)
	v_pk_mul_f32 v[240:241], v[184:185], v[232:233]
	v_pk_mul_f32 v[216:217], v[190:191], v[230:231]
	v_pk_mul_f32 v[218:219], v[188:189], v[228:229]
	v_pk_fma_f32 v[238:239], v[182:183], v[222:223], v[216:217] neg_lo:[0,0,1] neg_hi:[0,0,1]
	v_pk_fma_f32 v[216:217], v[180:181], v[220:221], v[218:219] neg_lo:[0,0,1] neg_hi:[0,0,1]
	v_pk_mul_f32 v[218:219], v[186:187], v[234:235]
	v_cvt_pk_bf16_f32 v216, v216, v217
	v_cvt_pk_bf16_f32 v217, v238, v239
	v_pk_mul_f32 v[182:183], v[182:183], v[230:231]
	v_pk_fma_f32 v[242:243], v[140:141], v[226:227], v[218:219] neg_lo:[0,0,1] neg_hi:[0,0,1]
	v_pk_fma_f32 v[218:219], v[138:139], v[224:225], v[240:241] neg_lo:[0,0,1] neg_hi:[0,0,1]
	v_pk_mul_f32 v[180:181], v[180:181], v[228:229]
	v_pk_mul_f32 v[140:141], v[140:141], v[234:235]
	v_pk_mul_f32 v[138:139], v[138:139], v[232:233]
	v_cvt_pk_bf16_f32 v218, v218, v219
	v_cvt_pk_bf16_f32 v219, v242, v243
	global_store_dwordx4 v[236:237], v[216:219], off sc1
	v_pk_fma_f32 v[182:183], v[190:191], v[222:223], v[182:183]
	v_pk_fma_f32 v[180:181], v[188:189], v[220:221], v[180:181]
	v_pk_fma_f32 v[186:187], v[186:187], v[226:227], v[140:141]
	v_pk_fma_f32 v[140:141], v[184:185], v[224:225], v[138:139]
	v_cvt_pk_bf16_f32 v138, v180, v181
	v_cvt_pk_bf16_f32 v139, v182, v183
	v_lshl_add_u64 v[216:217], v[132:133], 0, s[0:1]
	v_cvt_pk_bf16_f32 v140, v140, v141
	v_cvt_pk_bf16_f32 v141, v186, v187
	global_store_dwordx4 v[236:237], v[138:141], off offset:128 sc1
	v_lshl_add_u64 v[184:185], s[24:25], 0, v[216:217]
	v_lshl_add_u64 v[188:189], v[184:185], 0, v[130:131]
	v_lshl_add_u64 v[138:139], s[22:23], 0, v[216:217]
	v_lshl_add_u64 v[180:181], v[138:139], 0, v[130:131]
	ds_read_b32 v134, v136 offset:64
	global_load_dwordx4 v[138:141], v[180:181], off offset:16
	s_nop 0
	global_load_dwordx4 v[180:183], v[180:181], off
	s_nop 0
	global_load_dwordx4 v[184:187], v[188:189], off offset:16
	s_nop 0
	global_load_dwordx4 v[188:191], v[188:189], off
	v_lshl_add_u64 v[236:237], v[156:157], 0, v[216:217]
	s_mov_b64 s[0:1], 0x2000
	s_waitcnt lgkmcnt(0)
	v_mul_f32_e32 v134, v135, v134
	v_pk_mul_f32 v[228:229], v[102:103], v[134:135] op_sel_hi:[1,0]
	v_pk_mul_f32 v[230:231], v[104:105], v[134:135] op_sel_hi:[1,0]
	v_pk_mul_f32 v[220:221], v[110:111], v[134:135] op_sel_hi:[1,0]
	v_pk_mul_f32 v[222:223], v[112:113], v[134:135] op_sel_hi:[1,0]
	v_pk_mul_f32 v[232:233], v[98:99], v[134:135] op_sel_hi:[1,0]
	v_pk_mul_f32 v[234:235], v[100:101], v[134:135] op_sel_hi:[1,0]
	v_pk_mul_f32 v[224:225], v[106:107], v[134:135] op_sel_hi:[1,0]
	v_pk_mul_f32 v[226:227], v[108:109], v[134:135] op_sel_hi:[1,0]
	s_waitcnt vmcnt(1)
	v_pk_mul_f32 v[240:241], v[184:185], v[232:233]
	s_waitcnt vmcnt(0)
;     __device__ __forceinline__ void operator()(const f32x4 (&acc)[2][2][4][2], const pg8::Unit& u, int wr, int wc, int fr_, int fq_, int tid) {
;     ...
;         } else if (pn < 16) {
;             const int seg = (pn - 12) >> 1, hh = 2 * ((pn - 12) & 1) + (wc >> 1), dp = 32 * (wc & 1) + 8 * fq;
;             bf16_t* base = RQ + (size_t)seg * (SZ_R / 2); const float ksc = seg ? 0.08838834764831845f : 1.0f;
; #pragma unroll
;             for (int ai = 0; ai < 2; ++ai)
; #pragma unroll
;                 for (int m = 0; m < 4; ++m) {
;                     const int s = s0 + ai * 128 + m * 16; const float rs = rsl[rl0 + ai * 128 + m * 16] * ksc;
;                     const f32x4 c0 = *(const f32x4*)(ropec + (size_t)s * 64 + dp), c1 = *(const f32x4*)(ropec + (size_t)s * 64 + dp + 4);
;                     const f32x4 n0 = *(const f32x4*)(ropes + (size_t)s * 64 + dp), n1 = *(const f32x4*)(ropes + (size_t)s * 64 + dp + 4);
;                     const f32x4 a0 = acc[ai][0][m][0] * rs, a1 = acc[ai][0][m][1] * rs, b0 = acc[ai][1][m][0] * rs, b1 = acc[ai][1][m][1] * rs;
;                     bf16_t* dst = base + ((size_t)(b * RETH + hh) * SEQ + s) * HD + dp;
;                     *(u32x4*)(dst) = pack8bf(a0 * c0 - b0 * n0, a1 * c1 - b1 * n1);
;                     *(u32x4*)(dst + 64) = pack8bf(a0 * n0 + b0 * c0, a1 * n1 + b1 * c1);
;                     if (m & 1) asm volatile("" ::: "memory");
;                 }
	v_pk_mul_f32 v[216:217], v[190:191], v[230:231]
	v_pk_mul_f32 v[218:219], v[188:189], v[228:229]
	v_pk_fma_f32 v[238:239], v[182:183], v[222:223], v[216:217] neg_lo:[0,0,1] neg_hi:[0,0,1]
	v_pk_fma_f32 v[216:217], v[180:181], v[220:221], v[218:219] neg_lo:[0,0,1] neg_hi:[0,0,1]
	v_pk_mul_f32 v[218:219], v[186:187], v[234:235]
	v_cvt_pk_bf16_f32 v216, v216, v217
	v_cvt_pk_bf16_f32 v217, v238, v239
	v_pk_mul_f32 v[182:183], v[182:183], v[230:231]
	v_pk_fma_f32 v[242:243], v[140:141], v[226:227], v[218:219] neg_lo:[0,0,1] neg_hi:[0,0,1]
	v_pk_fma_f32 v[218:219], v[138:139], v[224:225], v[240:241] neg_lo:[0,0,1] neg_hi:[0,0,1]
	v_pk_mul_f32 v[180:181], v[180:181], v[228:229]
	v_pk_mul_f32 v[140:141], v[140:141], v[234:235]
	v_pk_mul_f32 v[138:139], v[138:139], v[232:233]
	v_cvt_pk_bf16_f32 v218, v218, v219
	v_cvt_pk_bf16_f32 v219, v242, v243
	global_store_dwordx4 v[236:237], v[216:219], off sc1
	v_pk_fma_f32 v[182:183], v[190:191], v[222:223], v[182:183]
	v_pk_fma_f32 v[180:181], v[188:189], v[220:221], v[180:181]
	v_pk_fma_f32 v[186:187], v[186:187], v[226:227], v[140:141]
	v_pk_fma_f32 v[140:141], v[184:185], v[224:225], v[138:139]
	v_cvt_pk_bf16_f32 v138, v180, v181
	v_cvt_pk_bf16_f32 v139, v182, v183
	v_lshl_add_u64 v[216:217], v[132:133], 0, s[0:1]
	v_cvt_pk_bf16_f32 v140, v140, v141
	v_cvt_pk_bf16_f32 v141, v186, v187
	global_store_dwordx4 v[236:237], v[138:141], off offset:128 sc1
	v_lshl_add_u64 v[184:185], s[24:25], 0, v[216:217]
	v_lshl_add_u64 v[188:189], v[184:185], 0, v[130:131]
	v_lshl_add_u64 v[138:139], s[22:23], 0, v[216:217]
	v_lshl_add_u64 v[180:181], v[138:139], 0, v[130:131]
	ds_read_b32 v134, v136 offset:128
	global_load_dwordx4 v[138:141], v[180:181], off offset:16
	s_nop 0
	global_load_dwordx4 v[180:183], v[180:181], off
	s_nop 0
	global_load_dwordx4 v[184:187], v[188:189], off offset:16
	s_nop 0
	global_load_dwordx4 v[188:191], v[188:189], off
	v_lshl_add_u64 v[236:237], v[156:157], 0, v[216:217]
	s_mov_b64 s[0:1], 0x3000
	s_waitcnt lgkmcnt(0)
	v_mul_f32_e32 v134, v135, v134
	v_pk_mul_f32 v[228:229], v[86:87], v[134:135] op_sel_hi:[1,0]
	v_pk_mul_f32 v[230:231], v[88:89], v[134:135] op_sel_hi:[1,0]
	v_pk_mul_f32 v[220:221], v[94:95], v[134:135] op_sel_hi:[1,0]
	v_pk_mul_f32 v[222:223], v[96:97], v[134:135] op_sel_hi:[1,0]
	v_pk_mul_f32 v[232:233], v[82:83], v[134:135] op_sel_hi:[1,0]
	v_pk_mul_f32 v[234:235], v[84:85], v[134:135] op_sel_hi:[1,0]
	v_pk_mul_f32 v[224:225], v[90:91], v[134:135] op_sel_hi:[1,0]
	v_pk_mul_f32 v[226:227], v[92:93], v[134:135] op_sel_hi:[1,0]
	s_waitcnt vmcnt(1)
	v_pk_mul_f32 v[240:241], v[184:185], v[232:233]
	s_waitcnt vmcnt(0)
	v_pk_mul_f32 v[216:217], v[190:191], v[230:231]
	v_pk_mul_f32 v[218:219], v[188:189], v[228:229]
	v_pk_fma_f32 v[238:239], v[182:183], v[222:223], v[216:217] neg_lo:[0,0,1] neg_hi:[0,0,1]
	v_pk_fma_f32 v[216:217], v[180:181], v[220:221], v[218:219] neg_lo:[0,0,1] neg_hi:[0,0,1]
	v_pk_mul_f32 v[218:219], v[186:187], v[234:235]
	v_cvt_pk_bf16_f32 v216, v216, v217
	v_cvt_pk_bf16_f32 v217, v238, v239
	v_pk_mul_f32 v[182:183], v[182:183], v[230:231]
	v_pk_fma_f32 v[242:243], v[140:141], v[226:227], v[218:219] neg_lo:[0,0,1] neg_hi:[0,0,1]
	v_pk_fma_f32 v[218:219], v[138:139], v[224:225], v[240:241] neg_lo:[0,0,1] neg_hi:[0,0,1]
	v_pk_mul_f32 v[180:181], v[180:181], v[228:229]
	v_pk_mul_f32 v[140:141], v[140:141], v[234:235]
	v_pk_mul_f32 v[138:139], v[138:139], v[232:233]
	v_cvt_pk_bf16_f32 v218, v218, v219
	v_cvt_pk_bf16_f32 v219, v242, v243
	global_store_dwordx4 v[236:237], v[216:219], off sc1
	v_pk_fma_f32 v[182:183], v[190:191], v[222:223], v[182:183]
	v_pk_fma_f32 v[180:181], v[188:189], v[220:221], v[180:181]
	v_pk_fma_f32 v[186:187], v[186:187], v[226:227], v[140:141]
	v_pk_fma_f32 v[140:141], v[184:185], v[224:225], v[138:139]
	v_cvt_pk_bf16_f32 v138, v180, v181
	v_cvt_pk_bf16_f32 v139, v182, v183
	v_lshl_add_u64 v[216:217], v[132:133], 0, s[0:1]
	v_cvt_pk_bf16_f32 v140, v140, v141
	v_cvt_pk_bf16_f32 v141, v186, v187
	global_store_dwordx4 v[236:237], v[138:141], off offset:128 sc1
	v_lshl_add_u64 v[184:185], s[24:25], 0, v[216:217]
	v_lshl_add_u64 v[188:189], v[184:185], 0, v[130:131]
	v_lshl_add_u64 v[138:139], s[22:23], 0, v[216:217]
	v_lshl_add_u64 v[180:181], v[138:139], 0, v[130:131]
	ds_read_b32 v134, v136 offset:192
	global_load_dwordx4 v[138:141], v[180:181], off offset:16
	s_nop 0
	global_load_dwordx4 v[180:183], v[180:181], off
	s_nop 0
	global_load_dwordx4 v[184:187], v[188:189], off offset:16
	s_nop 0
	global_load_dwordx4 v[188:191], v[188:189], off
	v_lshl_add_u64 v[236:237], v[156:157], 0, v[216:217]
	s_mov_b64 s[0:1], 0x8000
	s_waitcnt lgkmcnt(0)
	v_mul_f32_e32 v134, v135, v134
	v_pk_mul_f32 v[228:229], v[70:71], v[134:135] op_sel_hi:[1,0]
	v_pk_mul_f32 v[230:231], v[72:73], v[134:135] op_sel_hi:[1,0]
	v_pk_mul_f32 v[220:221], v[78:79], v[134:135] op_sel_hi:[1,0]
	v_pk_mul_f32 v[222:223], v[80:81], v[134:135] op_sel_hi:[1,0]
	v_pk_mul_f32 v[232:233], v[66:67], v[134:135] op_sel_hi:[1,0]
	v_pk_mul_f32 v[234:235], v[68:69], v[134:135] op_sel_hi:[1,0]
	v_pk_mul_f32 v[224:225], v[74:75], v[134:135] op_sel_hi:[1,0]
	v_pk_mul_f32 v[226:227], v[76:77], v[134:135] op_sel_hi:[1,0]
	s_waitcnt vmcnt(1)
	v_pk_mul_f32 v[240:241], v[184:185], v[232:233]
	s_waitcnt vmcnt(0)
;     __device__ __forceinline__ void operator()(const f32x4 (&acc)[2][2][4][2], const pg8::Unit& u, int wr, int wc, int fr_, int fq_, int tid) {
;     ...
;         } else if (pn < 16) {
;             const int seg = (pn - 12) >> 1, hh = 2 * ((pn - 12) & 1) + (wc >> 1), dp = 32 * (wc & 1) + 8 * fq;
;             bf16_t* base = RQ + (size_t)seg * (SZ_R / 2); const float ksc = seg ? 0.08838834764831845f : 1.0f;
; #pragma unroll
;             for (int ai = 0; ai < 2; ++ai)
; #pragma unroll
;                 for (int m = 0; m < 4; ++m) {
;                     const int s = s0 + ai * 128 + m * 16; const float rs = rsl[rl0 + ai * 128 + m * 16] * ksc;
;                     const f32x4 c0 = *(const f32x4*)(ropec + (size_t)s * 64 + dp), c1 = *(const f32x4*)(ropec + (size_t)s * 64 + dp + 4);
;                     const f32x4 n0 = *(const f32x4*)(ropes + (size_t)s * 64 + dp), n1 = *(const f32x4*)(ropes + (size_t)s * 64 + dp + 4);
;                     const f32x4 a0 = acc[ai][0][m][0] * rs, a1 = acc[ai][0][m][1] * rs, b0 = acc[ai][1][m][0] * rs, b1 = acc[ai][1][m][1] * rs;
;                     bf16_t* dst = base + ((size_t)(b * RETH + hh) * SEQ + s) * HD + dp;
;                     *(u32x4*)(dst) = pack8bf(a0 * c0 - b0 * n0, a1 * c1 - b1 * n1);
;                     *(u32x4*)(dst + 64) = pack8bf(a0 * n0 + b0 * c0, a1 * n1 + b1 * c1);
;                     if (m & 1) asm volatile("" ::: "memory");
;                 }
	v_pk_mul_f32 v[216:217], v[190:191], v[230:231]
	v_pk_mul_f32 v[218:219], v[188:189], v[228:229]
	v_pk_fma_f32 v[238:239], v[182:183], v[222:223], v[216:217] neg_lo:[0,0,1] neg_hi:[0,0,1]
	v_pk_fma_f32 v[216:217], v[180:181], v[220:221], v[218:219] neg_lo:[0,0,1] neg_hi:[0,0,1]
	v_pk_mul_f32 v[218:219], v[186:187], v[234:235]
	v_cvt_pk_bf16_f32 v216, v216, v217
	v_cvt_pk_bf16_f32 v217, v238, v239
	v_pk_mul_f32 v[182:183], v[182:183], v[230:231]
	v_pk_fma_f32 v[242:243], v[140:141], v[226:227], v[218:219] neg_lo:[0,0,1] neg_hi:[0,0,1]
	v_pk_fma_f32 v[218:219], v[138:139], v[224:225], v[240:241] neg_lo:[0,0,1] neg_hi:[0,0,1]
	v_pk_mul_f32 v[180:181], v[180:181], v[228:229]
	v_pk_mul_f32 v[140:141], v[140:141], v[234:235]
	v_pk_mul_f32 v[138:139], v[138:139], v[232:233]
	v_cvt_pk_bf16_f32 v218, v218, v219
	v_cvt_pk_bf16_f32 v219, v242, v243
	global_store_dwordx4 v[236:237], v[216:219], off sc1
	v_pk_fma_f32 v[182:183], v[190:191], v[222:223], v[182:183]
	v_pk_fma_f32 v[180:181], v[188:189], v[220:221], v[180:181]
	v_pk_fma_f32 v[186:187], v[186:187], v[226:227], v[140:141]
	v_pk_fma_f32 v[140:141], v[184:185], v[224:225], v[138:139]
	v_cvt_pk_bf16_f32 v138, v180, v181
	v_cvt_pk_bf16_f32 v139, v182, v183
	v_lshl_add_u64 v[216:217], v[132:133], 0, s[0:1]
	v_cvt_pk_bf16_f32 v140, v140, v141
	v_cvt_pk_bf16_f32 v141, v186, v187
	global_store_dwordx4 v[236:237], v[138:141], off offset:128 sc1
	v_lshl_add_u64 v[184:185], s[24:25], 0, v[216:217]
	v_lshl_add_u64 v[188:189], v[184:185], 0, v[130:131]
	v_lshl_add_u64 v[138:139], s[22:23], 0, v[216:217]
	v_lshl_add_u64 v[180:181], v[138:139], 0, v[130:131]
	ds_read_b32 v134, v136 offset:512
	global_load_dwordx4 v[138:141], v[180:181], off offset:16
	s_nop 0
	global_load_dwordx4 v[180:183], v[180:181], off
	s_nop 0
	global_load_dwordx4 v[184:187], v[188:189], off offset:16
	s_nop 0
	global_load_dwordx4 v[188:191], v[188:189], off
	v_lshl_add_u64 v[236:237], v[156:157], 0, v[216:217]
	s_mov_b64 s[0:1], 0x9000
	s_waitcnt lgkmcnt(0)
	v_mul_f32_e32 v134, v135, v134
	v_pk_mul_f32 v[228:229], v[54:55], v[134:135] op_sel_hi:[1,0]
	v_pk_mul_f32 v[230:231], v[56:57], v[134:135] op_sel_hi:[1,0]
	v_pk_mul_f32 v[220:221], v[62:63], v[134:135] op_sel_hi:[1,0]
	v_pk_mul_f32 v[222:223], v[64:65], v[134:135] op_sel_hi:[1,0]
	v_pk_mul_f32 v[232:233], v[50:51], v[134:135] op_sel_hi:[1,0]
	v_pk_mul_f32 v[234:235], v[52:53], v[134:135] op_sel_hi:[1,0]
	v_pk_mul_f32 v[224:225], v[58:59], v[134:135] op_sel_hi:[1,0]
	v_pk_mul_f32 v[226:227], v[60:61], v[134:135] op_sel_hi:[1,0]
	s_waitcnt vmcnt(1)
	v_pk_mul_f32 v[240:241], v[184:185], v[232:233]
	s_waitcnt vmcnt(0)
	v_pk_mul_f32 v[216:217], v[190:191], v[230:231]
	v_pk_mul_f32 v[218:219], v[188:189], v[228:229]
	v_pk_fma_f32 v[238:239], v[182:183], v[222:223], v[216:217] neg_lo:[0,0,1] neg_hi:[0,0,1]
	v_pk_fma_f32 v[216:217], v[180:181], v[220:221], v[218:219] neg_lo:[0,0,1] neg_hi:[0,0,1]
	v_pk_mul_f32 v[218:219], v[186:187], v[234:235]
	v_cvt_pk_bf16_f32 v216, v216, v217
	v_cvt_pk_bf16_f32 v217, v238, v239
	v_pk_mul_f32 v[182:183], v[182:183], v[230:231]
	v_pk_fma_f32 v[242:243], v[140:141], v[226:227], v[218:219] neg_lo:[0,0,1] neg_hi:[0,0,1]
	v_pk_fma_f32 v[218:219], v[138:139], v[224:225], v[240:241] neg_lo:[0,0,1] neg_hi:[0,0,1]
	v_pk_mul_f32 v[180:181], v[180:181], v[228:229]
	v_pk_mul_f32 v[140:141], v[140:141], v[234:235]
	v_pk_mul_f32 v[138:139], v[138:139], v[232:233]
	v_cvt_pk_bf16_f32 v218, v218, v219
	v_cvt_pk_bf16_f32 v219, v242, v243
	global_store_dwordx4 v[236:237], v[216:219], off sc1
	v_pk_fma_f32 v[182:183], v[190:191], v[222:223], v[182:183]
	v_pk_fma_f32 v[180:181], v[188:189], v[220:221], v[180:181]
	v_pk_fma_f32 v[186:187], v[186:187], v[226:227], v[140:141]
	v_pk_fma_f32 v[140:141], v[184:185], v[224:225], v[138:139]
	v_cvt_pk_bf16_f32 v138, v180, v181
	v_cvt_pk_bf16_f32 v139, v182, v183
	v_lshl_add_u64 v[216:217], v[132:133], 0, s[0:1]
	v_cvt_pk_bf16_f32 v140, v140, v141
	v_cvt_pk_bf16_f32 v141, v186, v187
	global_store_dwordx4 v[236:237], v[138:141], off offset:128 sc1
	v_lshl_add_u64 v[184:185], s[24:25], 0, v[216:217]
	v_lshl_add_u64 v[188:189], v[184:185], 0, v[130:131]
	v_lshl_add_u64 v[138:139], s[22:23], 0, v[216:217]
	v_lshl_add_u64 v[180:181], v[138:139], 0, v[130:131]
	ds_read_b32 v134, v136 offset:576
	global_load_dwordx4 v[138:141], v[180:181], off offset:16
	s_nop 0
	global_load_dwordx4 v[180:183], v[180:181], off
	s_nop 0
	global_load_dwordx4 v[184:187], v[188:189], off offset:16
	s_nop 0
	global_load_dwordx4 v[188:191], v[188:189], off
	v_lshl_add_u64 v[236:237], v[156:157], 0, v[216:217]
	s_mov_b64 s[0:1], 0xa000
	s_waitcnt lgkmcnt(0)
	v_mul_f32_e32 v134, v135, v134
	v_pk_mul_f32 v[228:229], v[38:39], v[134:135] op_sel_hi:[1,0]
	v_pk_mul_f32 v[230:231], v[40:41], v[134:135] op_sel_hi:[1,0]
	v_pk_mul_f32 v[220:221], v[46:47], v[134:135] op_sel_hi:[1,0]
	v_pk_mul_f32 v[222:223], v[48:49], v[134:135] op_sel_hi:[1,0]
	v_pk_mul_f32 v[232:233], v[34:35], v[134:135] op_sel_hi:[1,0]
	v_pk_mul_f32 v[234:235], v[36:37], v[134:135] op_sel_hi:[1,0]
	v_pk_mul_f32 v[224:225], v[42:43], v[134:135] op_sel_hi:[1,0]
	v_pk_mul_f32 v[226:227], v[44:45], v[134:135] op_sel_hi:[1,0]
	s_waitcnt vmcnt(1)
	v_pk_mul_f32 v[240:241], v[184:185], v[232:233]
	s_waitcnt vmcnt(0)
;     __device__ __forceinline__ void operator()(const f32x4 (&acc)[2][2][4][2], const pg8::Unit& u, int wr, int wc, int fr_, int fq_, int tid) {
;     ...
;         } else if (pn < 16) {
;             const int seg = (pn - 12) >> 1, hh = 2 * ((pn - 12) & 1) + (wc >> 1), dp = 32 * (wc & 1) + 8 * fq;
;             bf16_t* base = RQ + (size_t)seg * (SZ_R / 2); const float ksc = seg ? 0.08838834764831845f : 1.0f;
; #pragma unroll
;             for (int ai = 0; ai < 2; ++ai)
; #pragma unroll
;                 for (int m = 0; m < 4; ++m) {
;                     const int s = s0 + ai * 128 + m * 16; const float rs = rsl[rl0 + ai * 128 + m * 16] * ksc;
;                     const f32x4 c0 = *(const f32x4*)(ropec + (size_t)s * 64 + dp), c1 = *(const f32x4*)(ropec + (size_t)s * 64 + dp + 4);
;                     const f32x4 n0 = *(const f32x4*)(ropes + (size_t)s * 64 + dp), n1 = *(const f32x4*)(ropes + (size_t)s * 64 + dp + 4);
;                     const f32x4 a0 = acc[ai][0][m][0] * rs, a1 = acc[ai][0][m][1] * rs, b0 = acc[ai][1][m][0] * rs, b1 = acc[ai][1][m][1] * rs;
;                     bf16_t* dst = base + ((size_t)(b * RETH + hh) * SEQ + s) * HD + dp;
;                     *(u32x4*)(dst) = pack8bf(a0 * c0 - b0 * n0, a1 * c1 - b1 * n1);
;                     *(u32x4*)(dst + 64) = pack8bf(a0 * n0 + b0 * c0, a1 * n1 + b1 * c1);
;                     if (m & 1) asm volatile("" ::: "memory");
;                 }
	v_pk_mul_f32 v[216:217], v[190:191], v[230:231]
	v_pk_mul_f32 v[218:219], v[188:189], v[228:229]
	v_pk_fma_f32 v[238:239], v[182:183], v[222:223], v[216:217] neg_lo:[0,0,1] neg_hi:[0,0,1]
	v_pk_fma_f32 v[216:217], v[180:181], v[220:221], v[218:219] neg_lo:[0,0,1] neg_hi:[0,0,1]
	v_pk_mul_f32 v[218:219], v[186:187], v[234:235]
	v_cvt_pk_bf16_f32 v216, v216, v217
	v_cvt_pk_bf16_f32 v217, v238, v239
	v_pk_mul_f32 v[182:183], v[182:183], v[230:231]
	v_pk_fma_f32 v[242:243], v[140:141], v[226:227], v[218:219] neg_lo:[0,0,1] neg_hi:[0,0,1]
	v_pk_fma_f32 v[218:219], v[138:139], v[224:225], v[240:241] neg_lo:[0,0,1] neg_hi:[0,0,1]
	v_pk_mul_f32 v[180:181], v[180:181], v[228:229]
	v_pk_mul_f32 v[140:141], v[140:141], v[234:235]
	v_pk_mul_f32 v[138:139], v[138:139], v[232:233]
	v_cvt_pk_bf16_f32 v218, v218, v219
	v_cvt_pk_bf16_f32 v219, v242, v243
	global_store_dwordx4 v[236:237], v[216:219], off sc1
	v_pk_fma_f32 v[182:183], v[190:191], v[222:223], v[182:183]
	v_pk_fma_f32 v[180:181], v[188:189], v[220:221], v[180:181]
	v_pk_fma_f32 v[186:187], v[186:187], v[226:227], v[140:141]
	v_pk_fma_f32 v[140:141], v[184:185], v[224:225], v[138:139]
	v_cvt_pk_bf16_f32 v138, v180, v181
	v_cvt_pk_bf16_f32 v139, v182, v183
	v_lshl_add_u64 v[216:217], v[132:133], 0, s[0:1]
	v_cvt_pk_bf16_f32 v140, v140, v141
	v_cvt_pk_bf16_f32 v141, v186, v187
	global_store_dwordx4 v[236:237], v[138:141], off offset:128 sc1
	v_lshl_add_u64 v[184:185], s[24:25], 0, v[216:217]
	v_lshl_add_u64 v[188:189], v[184:185], 0, v[130:131]
	v_lshl_add_u64 v[138:139], s[22:23], 0, v[216:217]
	v_lshl_add_u64 v[180:181], v[138:139], 0, v[130:131]
	ds_read_b32 v134, v136 offset:640
	global_load_dwordx4 v[138:141], v[180:181], off offset:16
	s_nop 0
	global_load_dwordx4 v[180:183], v[180:181], off
	s_nop 0
	global_load_dwordx4 v[184:187], v[188:189], off offset:16
	s_nop 0
	global_load_dwordx4 v[188:191], v[188:189], off
	v_lshl_add_u64 v[236:237], v[156:157], 0, v[216:217]
	s_mov_b64 s[0:1], 0xb000
	s_waitcnt lgkmcnt(0)
	v_mul_f32_e32 v134, v135, v134
	v_pk_mul_f32 v[228:229], v[22:23], v[134:135] op_sel_hi:[1,0]
	v_pk_mul_f32 v[230:231], v[24:25], v[134:135] op_sel_hi:[1,0]
	v_pk_mul_f32 v[220:221], v[30:31], v[134:135] op_sel_hi:[1,0]
	v_pk_mul_f32 v[222:223], v[32:33], v[134:135] op_sel_hi:[1,0]
	v_pk_mul_f32 v[232:233], v[18:19], v[134:135] op_sel_hi:[1,0]
	v_pk_mul_f32 v[234:235], v[20:21], v[134:135] op_sel_hi:[1,0]
	v_pk_mul_f32 v[224:225], v[26:27], v[134:135] op_sel_hi:[1,0]
	v_pk_mul_f32 v[226:227], v[28:29], v[134:135] op_sel_hi:[1,0]
	s_waitcnt vmcnt(1)
	v_pk_mul_f32 v[240:241], v[184:185], v[232:233]
	s_waitcnt vmcnt(0)
	v_pk_mul_f32 v[216:217], v[190:191], v[230:231]
	v_pk_mul_f32 v[218:219], v[188:189], v[228:229]
	v_pk_fma_f32 v[238:239], v[182:183], v[222:223], v[216:217] neg_lo:[0,0,1] neg_hi:[0,0,1]
	v_pk_fma_f32 v[216:217], v[180:181], v[220:221], v[218:219] neg_lo:[0,0,1] neg_hi:[0,0,1]
	v_pk_mul_f32 v[218:219], v[186:187], v[234:235]
	v_pk_mul_f32 v[182:183], v[182:183], v[230:231]
	v_pk_fma_f32 v[242:243], v[140:141], v[226:227], v[218:219] neg_lo:[0,0,1] neg_hi:[0,0,1]
	v_pk_fma_f32 v[218:219], v[138:139], v[224:225], v[240:241] neg_lo:[0,0,1] neg_hi:[0,0,1]
	v_pk_mul_f32 v[140:141], v[140:141], v[234:235]
	v_pk_mul_f32 v[138:139], v[138:139], v[232:233]
	v_pk_mul_f32 v[180:181], v[180:181], v[228:229]
	v_pk_fma_f32 v[186:187], v[186:187], v[226:227], v[140:141]
	v_pk_fma_f32 v[140:141], v[184:185], v[224:225], v[138:139]
	v_cvt_pk_bf16_f32 v216, v216, v217
	v_cvt_pk_bf16_f32 v217, v238, v239
	v_cvt_pk_bf16_f32 v218, v218, v219
	v_cvt_pk_bf16_f32 v219, v242, v243
	global_store_dwordx4 v[236:237], v[216:219], off sc1
	v_pk_fma_f32 v[182:183], v[190:191], v[222:223], v[182:183]
	v_pk_fma_f32 v[180:181], v[188:189], v[220:221], v[180:181]
	v_lshl_add_u64 v[184:185], v[132:133], 0, s[0:1]
	v_cvt_pk_bf16_f32 v138, v180, v181
	v_cvt_pk_bf16_f32 v139, v182, v183
	v_cvt_pk_bf16_f32 v140, v140, v141
	v_cvt_pk_bf16_f32 v141, v186, v187
	ds_read_b32 v134, v136 offset:704
	v_lshl_add_u64 v[132:133], s[22:23], 0, v[184:185]
	global_store_dwordx4 v[236:237], v[138:141], off offset:128 sc1
	v_lshl_add_u64 v[132:133], v[132:133], 0, v[130:131]
	v_lshl_add_u64 v[156:157], v[156:157], 0, v[184:185]
	s_waitcnt lgkmcnt(0)
	v_mul_f32_e32 v158, v135, v134
	global_load_dwordx4 v[134:137], v[132:133], off offset:16
	global_load_dwordx4 v[138:141], v[132:133], off
	v_lshl_add_u64 v[132:133], s[24:25], 0, v[184:185]
	v_lshl_add_u64 v[180:181], v[132:133], 0, v[130:131]
	global_load_dwordx4 v[130:133], v[180:181], off offset:16
	s_nop 0
	global_load_dwordx4 v[180:183], v[180:181], off
	v_pk_mul_f32 v[220:221], v[6:7], v[158:159] op_sel_hi:[1,0]
	v_pk_mul_f32 v[222:223], v[8:9], v[158:159] op_sel_hi:[1,0]
	v_pk_mul_f32 v[188:189], v[14:15], v[158:159] op_sel_hi:[1,0]
	v_pk_mul_f32 v[190:191], v[16:17], v[158:159] op_sel_hi:[1,0]
	v_pk_mul_f32 v[224:225], v[2:3], v[158:159] op_sel_hi:[1,0]
	v_pk_mul_f32 v[226:227], v[4:5], v[158:159] op_sel_hi:[1,0]
	v_pk_mul_f32 v[216:217], v[10:11], v[158:159] op_sel_hi:[1,0]
	v_pk_mul_f32 v[218:219], v[12:13], v[158:159] op_sel_hi:[1,0]
	s_waitcnt vmcnt(1)
	v_pk_mul_f32 v[230:231], v[130:131], v[224:225]
	s_waitcnt vmcnt(0)
	v_pk_mul_f32 v[184:185], v[182:183], v[222:223]
	v_pk_mul_f32 v[186:187], v[180:181], v[220:221]
	v_pk_fma_f32 v[228:229], v[140:141], v[190:191], v[184:185] neg_lo:[0,0,1] neg_hi:[0,0,1]
	v_pk_fma_f32 v[184:185], v[138:139], v[188:189], v[186:187] neg_lo:[0,0,1] neg_hi:[0,0,1]
	v_pk_mul_f32 v[186:187], v[132:133], v[226:227]
	v_pk_mul_f32 v[140:141], v[140:141], v[222:223]
	v_pk_fma_f32 v[232:233], v[136:137], v[218:219], v[186:187] neg_lo:[0,0,1] neg_hi:[0,0,1]
	v_pk_fma_f32 v[186:187], v[134:135], v[216:217], v[230:231] neg_lo:[0,0,1] neg_hi:[0,0,1]
	v_pk_mul_f32 v[136:137], v[136:137], v[226:227]
	v_pk_mul_f32 v[134:135], v[134:135], v[224:225]
	v_pk_mul_f32 v[138:139], v[138:139], v[220:221]
	v_pk_fma_f32 v[136:137], v[132:133], v[218:219], v[136:137]
	v_pk_fma_f32 v[132:133], v[130:131], v[216:217], v[134:135]
	v_cvt_pk_bf16_f32 v184, v184, v185
	v_cvt_pk_bf16_f32 v185, v228, v229
	v_cvt_pk_bf16_f32 v186, v186, v187
	v_cvt_pk_bf16_f32 v187, v232, v233
	global_store_dwordx4 v[156:157], v[184:187], off sc1
	v_pk_fma_f32 v[140:141], v[182:183], v[190:191], v[140:141]
	v_pk_fma_f32 v[138:139], v[180:181], v[188:189], v[138:139]
	s_nop 0
	v_cvt_pk_bf16_f32 v130, v138, v139
	v_cvt_pk_bf16_f32 v131, v140, v141
	v_cvt_pk_bf16_f32 v132, v132, v133
	v_cvt_pk_bf16_f32 v133, v136, v137
	global_store_dwordx4 v[156:157], v[130:133], off offset:128 sc1

;     __device__ __forceinline__ void operator()(const f32x4 (&acc)[2][2][4][2], const pg8::Unit& u, int wr, int wc, int fr_, int fq_, int tid) {
;     ...
;         if (pn < 12) {
;             const int t = pn >> 2; bf16_t* base = FQ + (size_t)t * (SZ_FOX / 2);
;             float mx[2][2] = {{0.f, 0.f}, {0.f, 0.f}};
; #pragma unroll
;             for (int ai = 0; ai < 2; ++ai)
; #pragma unroll
;                 for (int m = 0; m < 4; ++m) {
;                     const int s = s0 + ai * 128 + m * 16; const float rs = rsl[rl0 + ai * 128 + m * 16];
; #pragma unroll
;                     for (int bj = 0; bj < 2; ++bj) { const int head = 2 * (pn & 3) + bj;
;                         const u32x4 w = pack8bf(acc[ai][bj][m][0] * rs, acc[ai][bj][m][1] * rs);
;                         *(u32x4*)(base + ((size_t)(b * FOXH + head) * SEQ + s) * HD + wc * 32 + 8 * fq) = w;
;                         if (t < 2) { float f[8]; unpack8(w, f);
;                             float ss = ((f[0] * f[0] + f[1] * f[1]) + (f[2] * f[2] + f[3] * f[3])) + ((f[4] * f[4] + f[5] * f[5]) + (f[6] * f[6] + f[7] * f[7]));
;                             ss += __shfl_xor(ss, 16); ss += __shfl_xor(ss, 32); mx[ai][bj] = fmaxf(mx[ai][bj], ss); } }
;                 }
.LBB0_446:
	s_andn2_b64 vcc, exec, s[0:1]
	s_cbranch_vccnz .LBB0_487
	s_ashr_i32 s0, s38, 2
	s_ashr_i32 s1, s0, 31
	s_lshl_b64 s[10:11], s[0:1], 25
	s_lshl_b32 s1, s38, 1
	v_lshl_add_u32 v132, v178, 2, 0
	s_and_b32 s1, s1, 6
	s_lshl_b32 s29, s29, 3
	v_add_u32_e32 v136, 0x20400, v132
	s_or_b32 s8, s29, s1
	ds_read_b32 v134, v136
	s_add_u32 s10, s73, s10
	s_addc_u32 s11, s74, s11
	v_lshlrev_b32_e32 v130, 3, v176
	s_waitcnt lgkmcnt(0)
	v_ashrrev_i32_e32 v131, 31, v130
	s_cmp_lt_i32 s0, 2
	v_ashrrev_i32_e32 v155, 31, v154
	v_lshl_add_u64 v[130:131], v[130:131], 1, s[10:11]
	s_cselect_b64 s[40:41], -1, 0
	s_ashr_i32 s9, s8, 31
	v_lshlrev_b64 v[132:133], 8, v[154:155]
	s_lshl_b64 s[10:11], s[8:9], 20
	v_lshl_add_u64 v[132:133], v[130:131], 0, v[132:133]
	v_pk_mul_f32 v[126:127], v[126:127], v[134:135] op_sel_hi:[1,0]
	v_pk_mul_f32 v[138:139], v[124:125], v[134:135] op_sel_hi:[1,0]
	v_pk_mul_f32 v[124:125], v[122:123], v[134:135] op_sel_hi:[1,0]
	v_cvt_pk_bf16_f32 v122, v126, v127
	v_lshl_add_u64 v[126:127], v[132:133], 0, s[10:11]
	s_cmp_gt_i32 s0, 1
	v_pk_mul_f32 v[128:129], v[128:129], v[134:135] op_sel_hi:[1,0]
	s_nop 0
	v_cvt_pk_bf16_f32 v123, v128, v129
	v_cvt_pk_bf16_f32 v124, v124, v125
	v_cvt_pk_bf16_f32 v125, v138, v139
	global_store_dwordx4 v[126:127], v[122:125], off sc1
	v_mov_b32_e32 v126, 0
	v_mov_b32_e32 v127, 0
	s_cbranch_scc1 .LBB0_449
	v_lshlrev_b32_e32 v129, 16, v124
	v_and_b32_e32 v139, 0xffff0000, v124
	v_and_b32_e32 v138, 0xffff0000, v122
	v_lshlrev_b32_e32 v141, 16, v125
	v_and_b32_e32 v125, 0xffff0000, v125
	v_and_b32_e32 v124, 0xffff0000, v123
	v_lshlrev_b32_e32 v128, 16, v122
	v_lshlrev_b32_e32 v140, 16, v123
	v_pk_mul_f32 v[122:123], v[138:139], v[138:139]
	v_pk_mul_f32 v[124:125], v[124:125], v[124:125]
	v_pk_fma_f32 v[122:123], v[128:129], v[128:129], v[122:123]
	v_pk_fma_f32 v[124:125], v[140:141], v[140:141], v[124:125]
	v_cmp_lt_i32_e32 vcc, v203, v198
	v_pk_add_f32 v[122:123], v[122:123], v[124:125]
	s_nop 0
	v_add_f32_e32 v122, v122, v123
	v_cndmask_b32_e32 v123, v195, v203, vcc
	v_lshlrev_b32_e32 v123, 2, v123
	ds_bpermute_b32 v123, v123, v122
	v_cmp_lt_i32_e32 vcc, v204, v198
	s_waitcnt lgkmcnt(0)
	v_add_f32_e32 v122, v122, v123
	v_cndmask_b32_e32 v123, v195, v204, vcc
	v_lshlrev_b32_e32 v123, 2, v123
	ds_bpermute_b32 v123, v123, v122
	s_waitcnt lgkmcnt(0)
	v_add_f32_e32 v122, v122, v123
	v_max_f32_e32 v127, 0, v122
.LBB0_449:
	v_mov_b32_e32 v122, v134
	v_mov_b32_e32 v123, v134
	s_or_b32 s8, s8, 1
	v_mov_b32_e32 v135, v134
	v_pk_mul_f32 v[120:121], v[120:121], v[122:123]
	s_ashr_i32 s9, s8, 31
	v_pk_mul_f32 v[118:119], v[118:119], v[134:135]
	v_pk_mul_f32 v[122:123], v[116:117], v[122:123]
	v_pk_mul_f32 v[116:117], v[114:115], v[134:135]
	v_cvt_pk_bf16_f32 v114, v118, v119
	v_cvt_pk_bf16_f32 v115, v120, v121
	s_lshl_b64 s[38:39], s[8:9], 20
	v_cndmask_b32_e64 v120, 0, 1, s[40:41]
	v_lshl_add_u64 v[118:119], v[132:133], 0, s[38:39]
	v_cmp_ne_u32_e64 s[8:9], 1, v120
	s_andn2_b64 vcc, exec, s[40:41]
	v_cvt_pk_bf16_f32 v116, v116, v117
	v_cvt_pk_bf16_f32 v117, v122, v123
	global_store_dwordx4 v[118:119], v[114:117], off sc1
	s_cbranch_vccnz .LBB0_451
	v_lshlrev_b32_e32 v119, 16, v116
	v_and_b32_e32 v121, 0xffff0000, v116
	v_and_b32_e32 v120, 0xffff0000, v114
	v_lshlrev_b32_e32 v123, 16, v117
	v_and_b32_e32 v117, 0xffff0000, v117
	v_and_b32_e32 v116, 0xffff0000, v115
	v_lshlrev_b32_e32 v118, 16, v114
	v_lshlrev_b32_e32 v122, 16, v115
	v_pk_mul_f32 v[114:115], v[120:121], v[120:121]
	v_pk_mul_f32 v[116:117], v[116:117], v[116:117]
	v_pk_fma_f32 v[114:115], v[118:119], v[118:119], v[114:115]
	v_pk_fma_f32 v[116:117], v[122:123], v[122:123], v[116:117]
	v_cmp_lt_i32_e32 vcc, v203, v198
	v_pk_add_f32 v[114:115], v[114:115], v[116:117]
	s_nop 0
	v_add_f32_e32 v114, v114, v115
	v_cndmask_b32_e32 v115, v195, v203, vcc
	v_lshlrev_b32_e32 v115, 2, v115
	ds_bpermute_b32 v115, v115, v114
	v_cmp_lt_i32_e32 vcc, v204, v198
	s_waitcnt lgkmcnt(0)
	v_add_f32_e32 v114, v114, v115
	v_cndmask_b32_e32 v115, v195, v204, vcc
	v_lshlrev_b32_e32 v115, 2, v115
	ds_bpermute_b32 v115, v115, v114
	s_waitcnt lgkmcnt(0)
	v_add_f32_e32 v114, v114, v115
	v_max_f32_e32 v126, 0, v114
.LBB0_451:
	ds_read_b32 v116, v136 offset:64
	v_lshlrev_b64 v[114:115], 8, v[154:155]
	v_lshl_add_u64 v[114:115], v[130:131], 0, v[114:115]
	s_mov_b64 s[40:41], 0x1000
	v_lshl_add_u64 v[114:115], v[114:115], 0, s[40:41]
	s_waitcnt lgkmcnt(0)
	v_pk_mul_f32 v[110:111], v[110:111], v[116:117] op_sel_hi:[1,0]
	v_pk_mul_f32 v[118:119], v[108:109], v[116:117] op_sel_hi:[1,0]
	v_pk_mul_f32 v[108:109], v[106:107], v[116:117] op_sel_hi:[1,0]
	v_cvt_pk_bf16_f32 v106, v110, v111
	v_lshl_add_u64 v[110:111], v[114:115], 0, s[10:11]
	s_and_b64 vcc, exec, s[8:9]
	v_pk_mul_f32 v[112:113], v[112:113], v[116:117] op_sel_hi:[1,0]
	s_nop 0
	v_cvt_pk_bf16_f32 v107, v112, v113
	v_cvt_pk_bf16_f32 v108, v108, v109
	v_cvt_pk_bf16_f32 v109, v118, v119
	global_store_dwordx4 v[110:111], v[106:109], off sc1
	s_cbranch_vccnz .LBB0_453
	v_lshlrev_b32_e32 v111, 16, v108
	v_and_b32_e32 v113, 0xffff0000, v108
	v_and_b32_e32 v112, 0xffff0000, v106
	v_lshlrev_b32_e32 v119, 16, v109
	v_and_b32_e32 v109, 0xffff0000, v109
	v_and_b32_e32 v108, 0xffff0000, v107
	v_lshlrev_b32_e32 v110, 16, v106
	v_lshlrev_b32_e32 v118, 16, v107
	v_pk_mul_f32 v[106:107], v[112:113], v[112:113]
	v_pk_mul_f32 v[108:109], v[108:109], v[108:109]
	v_pk_fma_f32 v[106:107], v[110:111], v[110:111], v[106:107]
	v_pk_fma_f32 v[108:109], v[118:119], v[118:119], v[108:109]
	v_cmp_lt_i32_e32 vcc, v203, v198
	v_pk_add_f32 v[106:107], v[106:107], v[108:109]
	s_nop 0
	v_add_f32_e32 v106, v106, v107
	v_cndmask_b32_e32 v107, v195, v203, vcc
	v_lshlrev_b32_e32 v107, 2, v107
	ds_bpermute_b32 v107, v107, v106
	v_cmp_lt_i32_e32 vcc, v204, v198
	s_waitcnt lgkmcnt(0)
	v_add_f32_e32 v106, v106, v107
	v_cndmask_b32_e32 v107, v195, v204, vcc
	v_lshlrev_b32_e32 v107, 2, v107
	ds_bpermute_b32 v107, v107, v106
	s_waitcnt lgkmcnt(0)
	v_add_f32_e32 v106, v106, v107
	v_max_f32_e32 v107, v127, v127
	v_max_f32_e32 v127, v107, v106
;     __device__ __forceinline__ void operator()(const f32x4 (&acc)[2][2][4][2], const pg8::Unit& u, int wr, int wc, int fr_, int fq_, int tid) {
;     ...
; #pragma unroll
;             for (int ai = 0; ai < 2; ++ai)
; #pragma unroll
;                 for (int m = 0; m < 4; ++m) {
;                     const int s = s0 + ai * 128 + m * 16; const float rs = rsl[rl0 + ai * 128 + m * 16];
; #pragma unroll
;                     for (int bj = 0; bj < 2; ++bj) { const int head = 2 * (pn & 3) + bj;
;                         const u32x4 w = pack8bf(acc[ai][bj][m][0] * rs, acc[ai][bj][m][1] * rs);
;                         *(u32x4*)(base + ((size_t)(b * FOXH + head) * SEQ + s) * HD + wc * 32 + 8 * fq) = w;
;                         if (t < 2) { float f[8]; unpack8(w, f);
;                             float ss = ((f[0] * f[0] + f[1] * f[1]) + (f[2] * f[2] + f[3] * f[3])) + ((f[4] * f[4] + f[5] * f[5]) + (f[6] * f[6] + f[7] * f[7]));
;                             ss += __shfl_xor(ss, 16); ss += __shfl_xor(ss, 32); mx[ai][bj] = fmaxf(mx[ai][bj], ss); } }
;                 }
.LBB0_453:
	v_mov_b32_e32 v117, v116
	v_mov_b32_e32 v106, v116
	v_mov_b32_e32 v107, v116
	v_pk_mul_f32 v[102:103], v[102:103], v[116:117]
	v_pk_mul_f32 v[104:105], v[104:105], v[106:107]
	v_pk_mul_f32 v[106:107], v[100:101], v[106:107]
	v_pk_mul_f32 v[100:101], v[98:99], v[116:117]
	v_cvt_pk_bf16_f32 v98, v102, v103
	v_lshl_add_u64 v[102:103], v[114:115], 0, s[38:39]
	s_and_b64 vcc, exec, s[8:9]
	v_cvt_pk_bf16_f32 v99, v104, v105
	v_cvt_pk_bf16_f32 v100, v100, v101
	v_cvt_pk_bf16_f32 v101, v106, v107
	global_store_dwordx4 v[102:103], v[98:101], off sc1
	s_cbranch_vccnz .LBB0_455
	v_lshlrev_b32_e32 v103, 16, v100
	v_and_b32_e32 v105, 0xffff0000, v100
	v_and_b32_e32 v104, 0xffff0000, v98
	v_lshlrev_b32_e32 v107, 16, v101
	v_and_b32_e32 v101, 0xffff0000, v101
	v_and_b32_e32 v100, 0xffff0000, v99
	v_lshlrev_b32_e32 v102, 16, v98
	v_lshlrev_b32_e32 v106, 16, v99
	v_pk_mul_f32 v[98:99], v[104:105], v[104:105]
	v_pk_mul_f32 v[100:101], v[100:101], v[100:101]
	v_pk_fma_f32 v[98:99], v[102:103], v[102:103], v[98:99]
	v_pk_fma_f32 v[100:101], v[106:107], v[106:107], v[100:101]
	v_cmp_lt_i32_e32 vcc, v203, v198
	v_pk_add_f32 v[98:99], v[98:99], v[100:101]
	s_nop 0
	v_add_f32_e32 v98, v98, v99
	v_cndmask_b32_e32 v99, v195, v203, vcc
	v_lshlrev_b32_e32 v99, 2, v99
	ds_bpermute_b32 v99, v99, v98
	v_cmp_lt_i32_e32 vcc, v204, v198
	s_waitcnt lgkmcnt(0)
	v_add_f32_e32 v98, v98, v99
	v_cndmask_b32_e32 v99, v195, v204, vcc
	v_lshlrev_b32_e32 v99, 2, v99
	ds_bpermute_b32 v99, v99, v98
	s_waitcnt lgkmcnt(0)
	v_add_f32_e32 v98, v98, v99
	v_max_f32_e32 v99, v126, v126
	v_max_f32_e32 v126, v99, v98
.LBB0_455:
	ds_read_b32 v100, v136 offset:128
	v_lshlrev_b64 v[98:99], 8, v[154:155]
	v_lshl_add_u64 v[98:99], v[130:131], 0, v[98:99]
	s_mov_b64 s[40:41], 0x2000
	v_lshl_add_u64 v[98:99], v[98:99], 0, s[40:41]
	s_waitcnt lgkmcnt(0)
	v_pk_mul_f32 v[94:95], v[94:95], v[100:101] op_sel_hi:[1,0]
	v_pk_mul_f32 v[102:103], v[92:93], v[100:101] op_sel_hi:[1,0]
	v_pk_mul_f32 v[92:93], v[90:91], v[100:101] op_sel_hi:[1,0]
	v_cvt_pk_bf16_f32 v90, v94, v95
	v_lshl_add_u64 v[94:95], v[98:99], 0, s[10:11]
	s_and_b64 vcc, exec, s[8:9]
	v_pk_mul_f32 v[96:97], v[96:97], v[100:101] op_sel_hi:[1,0]
	s_nop 0
	v_cvt_pk_bf16_f32 v91, v96, v97
	v_cvt_pk_bf16_f32 v92, v92, v93
	v_cvt_pk_bf16_f32 v93, v102, v103
	global_store_dwordx4 v[94:95], v[90:93], off sc1
	s_cbranch_vccnz .LBB0_457
	v_lshlrev_b32_e32 v95, 16, v92
	v_and_b32_e32 v97, 0xffff0000, v92
	v_and_b32_e32 v96, 0xffff0000, v90
	v_lshlrev_b32_e32 v103, 16, v93
	v_and_b32_e32 v93, 0xffff0000, v93
	v_and_b32_e32 v92, 0xffff0000, v91
	v_lshlrev_b32_e32 v94, 16, v90
	v_lshlrev_b32_e32 v102, 16, v91
	v_pk_mul_f32 v[90:91], v[96:97], v[96:97]
	v_pk_mul_f32 v[92:93], v[92:93], v[92:93]
	v_pk_fma_f32 v[90:91], v[94:95], v[94:95], v[90:91]
	v_pk_fma_f32 v[92:93], v[102:103], v[102:103], v[92:93]
	v_cmp_lt_i32_e32 vcc, v203, v198
	v_pk_add_f32 v[90:91], v[90:91], v[92:93]
	s_nop 0
	v_add_f32_e32 v90, v90, v91
	v_cndmask_b32_e32 v91, v195, v203, vcc
	v_lshlrev_b32_e32 v91, 2, v91
	ds_bpermute_b32 v91, v91, v90
	v_cmp_lt_i32_e32 vcc, v204, v198
	s_waitcnt lgkmcnt(0)
	v_add_f32_e32 v90, v90, v91
	v_cndmask_b32_e32 v91, v195, v204, vcc
	v_lshlrev_b32_e32 v91, 2, v91
	ds_bpermute_b32 v91, v91, v90
	s_waitcnt lgkmcnt(0)
	v_add_f32_e32 v90, v90, v91
	v_max_f32_e32 v91, v127, v127
	v_max_f32_e32 v127, v91, v90
.LBB0_457:
	v_mov_b32_e32 v101, v100
	v_mov_b32_e32 v90, v100
	v_mov_b32_e32 v91, v100
	v_pk_mul_f32 v[86:87], v[86:87], v[100:101]
	v_pk_mul_f32 v[88:89], v[88:89], v[90:91]
	v_pk_mul_f32 v[90:91], v[84:85], v[90:91]
	v_pk_mul_f32 v[84:85], v[82:83], v[100:101]
	v_cvt_pk_bf16_f32 v82, v86, v87
	v_lshl_add_u64 v[86:87], v[98:99], 0, s[38:39]
	s_and_b64 vcc, exec, s[8:9]
	v_cvt_pk_bf16_f32 v83, v88, v89
	v_cvt_pk_bf16_f32 v84, v84, v85
	v_cvt_pk_bf16_f32 v85, v90, v91
	global_store_dwordx4 v[86:87], v[82:85], off sc1
	s_cbranch_vccnz .LBB0_459
	v_lshlrev_b32_e32 v87, 16, v84
	v_and_b32_e32 v89, 0xffff0000, v84
	v_and_b32_e32 v88, 0xffff0000, v82
	v_lshlrev_b32_e32 v91, 16, v85
	v_and_b32_e32 v85, 0xffff0000, v85
	v_and_b32_e32 v84, 0xffff0000, v83
	v_lshlrev_b32_e32 v86, 16, v82
	v_lshlrev_b32_e32 v90, 16, v83
	v_pk_mul_f32 v[82:83], v[88:89], v[88:89]
	v_pk_mul_f32 v[84:85], v[84:85], v[84:85]
	v_pk_fma_f32 v[82:83], v[86:87], v[86:87], v[82:83]
	v_pk_fma_f32 v[84:85], v[90:91], v[90:91], v[84:85]
	v_cmp_lt_i32_e32 vcc, v203, v198
	v_pk_add_f32 v[82:83], v[82:83], v[84:85]
	s_nop 0
	v_add_f32_e32 v82, v82, v83
	v_cndmask_b32_e32 v83, v195, v203, vcc
	v_lshlrev_b32_e32 v83, 2, v83
	ds_bpermute_b32 v83, v83, v82
	v_cmp_lt_i32_e32 vcc, v204, v198
	s_waitcnt lgkmcnt(0)
	v_add_f32_e32 v82, v82, v83
	v_cndmask_b32_e32 v83, v195, v204, vcc
	v_lshlrev_b32_e32 v83, 2, v83
	ds_bpermute_b32 v83, v83, v82
	s_waitcnt lgkmcnt(0)
	v_add_f32_e32 v82, v82, v83
	v_max_f32_e32 v83, v126, v126
	v_max_f32_e32 v126, v83, v82
;     __device__ __forceinline__ void operator()(const f32x4 (&acc)[2][2][4][2], const pg8::Unit& u, int wr, int wc, int fr_, int fq_, int tid) {
;     ...
; #pragma unroll
;             for (int ai = 0; ai < 2; ++ai)
; #pragma unroll
;                 for (int m = 0; m < 4; ++m) {
;                     const int s = s0 + ai * 128 + m * 16; const float rs = rsl[rl0 + ai * 128 + m * 16];
; #pragma unroll
;                     for (int bj = 0; bj < 2; ++bj) { const int head = 2 * (pn & 3) + bj;
;                         const u32x4 w = pack8bf(acc[ai][bj][m][0] * rs, acc[ai][bj][m][1] * rs);
;                         *(u32x4*)(base + ((size_t)(b * FOXH + head) * SEQ + s) * HD + wc * 32 + 8 * fq) = w;
;                         if (t < 2) { float f[8]; unpack8(w, f);
;                             float ss = ((f[0] * f[0] + f[1] * f[1]) + (f[2] * f[2] + f[3] * f[3])) + ((f[4] * f[4] + f[5] * f[5]) + (f[6] * f[6] + f[7] * f[7]));
;                             ss += __shfl_xor(ss, 16); ss += __shfl_xor(ss, 32); mx[ai][bj] = fmaxf(mx[ai][bj], ss); } }
;                 }
.LBB0_459:
	ds_read_b32 v84, v136 offset:192
	v_lshlrev_b64 v[82:83], 8, v[154:155]
	v_lshl_add_u64 v[82:83], v[130:131], 0, v[82:83]
	s_mov_b64 s[40:41], 0x3000
	v_lshl_add_u64 v[82:83], v[82:83], 0, s[40:41]
	s_waitcnt lgkmcnt(0)
	v_pk_mul_f32 v[78:79], v[78:79], v[84:85] op_sel_hi:[1,0]
	v_pk_mul_f32 v[86:87], v[76:77], v[84:85] op_sel_hi:[1,0]
	v_pk_mul_f32 v[76:77], v[74:75], v[84:85] op_sel_hi:[1,0]
	v_cvt_pk_bf16_f32 v74, v78, v79
	v_lshl_add_u64 v[78:79], v[82:83], 0, s[10:11]
	s_and_b64 vcc, exec, s[8:9]
	v_pk_mul_f32 v[80:81], v[80:81], v[84:85] op_sel_hi:[1,0]
	s_nop 0
	v_cvt_pk_bf16_f32 v75, v80, v81
	v_cvt_pk_bf16_f32 v76, v76, v77
	v_cvt_pk_bf16_f32 v77, v86, v87
	global_store_dwordx4 v[78:79], v[74:77], off sc1
	s_cbranch_vccnz .LBB0_461
	v_lshlrev_b32_e32 v79, 16, v76
	v_and_b32_e32 v81, 0xffff0000, v76
	v_and_b32_e32 v80, 0xffff0000, v74
	v_lshlrev_b32_e32 v87, 16, v77
	v_and_b32_e32 v77, 0xffff0000, v77
	v_and_b32_e32 v76, 0xffff0000, v75
	v_lshlrev_b32_e32 v78, 16, v74
	v_lshlrev_b32_e32 v86, 16, v75
	v_pk_mul_f32 v[74:75], v[80:81], v[80:81]
	v_pk_mul_f32 v[76:77], v[76:77], v[76:77]
	v_pk_fma_f32 v[74:75], v[78:79], v[78:79], v[74:75]
	v_pk_fma_f32 v[76:77], v[86:87], v[86:87], v[76:77]
	v_cmp_lt_i32_e32 vcc, v203, v198
	v_pk_add_f32 v[74:75], v[74:75], v[76:77]
	s_nop 0
	v_add_f32_e32 v74, v74, v75
	v_cndmask_b32_e32 v75, v195, v203, vcc
	v_lshlrev_b32_e32 v75, 2, v75
	ds_bpermute_b32 v75, v75, v74
	v_cmp_lt_i32_e32 vcc, v204, v198
	s_waitcnt lgkmcnt(0)
	v_add_f32_e32 v74, v74, v75
	v_cndmask_b32_e32 v75, v195, v204, vcc
	v_lshlrev_b32_e32 v75, 2, v75
	ds_bpermute_b32 v75, v75, v74
	s_waitcnt lgkmcnt(0)
	v_add_f32_e32 v74, v74, v75
	v_max_f32_e32 v75, v127, v127
	v_max_f32_e32 v127, v75, v74
.LBB0_461:
	v_mov_b32_e32 v85, v84
	v_mov_b32_e32 v74, v84
	v_mov_b32_e32 v75, v84
	v_pk_mul_f32 v[70:71], v[70:71], v[84:85]
	v_pk_mul_f32 v[72:73], v[72:73], v[74:75]
	v_pk_mul_f32 v[74:75], v[68:69], v[74:75]
	v_pk_mul_f32 v[68:69], v[66:67], v[84:85]
	v_cvt_pk_bf16_f32 v66, v70, v71
	v_lshl_add_u64 v[70:71], v[82:83], 0, s[38:39]
	s_and_b64 vcc, exec, s[8:9]
	v_cvt_pk_bf16_f32 v67, v72, v73
	v_cvt_pk_bf16_f32 v68, v68, v69
	v_cvt_pk_bf16_f32 v69, v74, v75
	global_store_dwordx4 v[70:71], v[66:69], off sc1
	s_cbranch_vccnz .LBB0_463
	v_lshlrev_b32_e32 v71, 16, v68
	v_and_b32_e32 v73, 0xffff0000, v68
	v_and_b32_e32 v72, 0xffff0000, v66
	v_lshlrev_b32_e32 v75, 16, v69
	v_and_b32_e32 v69, 0xffff0000, v69
	v_and_b32_e32 v68, 0xffff0000, v67
	v_lshlrev_b32_e32 v70, 16, v66
	v_lshlrev_b32_e32 v74, 16, v67
	v_pk_mul_f32 v[66:67], v[72:73], v[72:73]
	v_pk_mul_f32 v[68:69], v[68:69], v[68:69]
	v_pk_fma_f32 v[66:67], v[70:71], v[70:71], v[66:67]
	v_pk_fma_f32 v[68:69], v[74:75], v[74:75], v[68:69]
	v_cmp_lt_i32_e32 vcc, v203, v198
	v_pk_add_f32 v[66:67], v[66:67], v[68:69]
	s_nop 0
	v_add_f32_e32 v66, v66, v67
	v_cndmask_b32_e32 v67, v195, v203, vcc
	v_lshlrev_b32_e32 v67, 2, v67
	ds_bpermute_b32 v67, v67, v66
	v_cmp_lt_i32_e32 vcc, v204, v198
	s_waitcnt lgkmcnt(0)
	v_add_f32_e32 v66, v66, v67
	v_cndmask_b32_e32 v67, v195, v204, vcc
	v_lshlrev_b32_e32 v67, 2, v67
	ds_bpermute_b32 v67, v67, v66
	s_waitcnt lgkmcnt(0)
	v_add_f32_e32 v66, v66, v67
	v_max_f32_e32 v67, v126, v126
	v_max_f32_e32 v126, v67, v66
.LBB0_463:
	ds_read_b32 v68, v136 offset:512
	v_lshlrev_b64 v[66:67], 8, v[154:155]
	v_lshl_add_u64 v[66:67], v[130:131], 0, v[66:67]
	s_mov_b64 s[40:41], 0x8000
	v_lshl_add_u64 v[66:67], v[66:67], 0, s[40:41]
	s_waitcnt lgkmcnt(0)
	v_pk_mul_f32 v[62:63], v[62:63], v[68:69] op_sel_hi:[1,0]
	v_pk_mul_f32 v[70:71], v[60:61], v[68:69] op_sel_hi:[1,0]
	v_pk_mul_f32 v[60:61], v[58:59], v[68:69] op_sel_hi:[1,0]
	v_cvt_pk_bf16_f32 v58, v62, v63
	v_lshl_add_u64 v[62:63], v[66:67], 0, s[10:11]
	v_pk_mul_f32 v[64:65], v[64:65], v[68:69] op_sel_hi:[1,0]
	s_and_b64 vcc, exec, s[8:9]
	v_cvt_pk_bf16_f32 v59, v64, v65
	v_cvt_pk_bf16_f32 v60, v60, v61
	v_cvt_pk_bf16_f32 v61, v70, v71
	global_store_dwordx4 v[62:63], v[58:61], off sc1
	v_mov_b32_e32 v62, 0
	v_mov_b32_e32 v63, 0
	s_cbranch_vccnz .LBB0_465
	v_lshlrev_b32_e32 v65, 16, v60
	v_and_b32_e32 v71, 0xffff0000, v60
	v_and_b32_e32 v70, 0xffff0000, v58
	v_lshlrev_b32_e32 v73, 16, v61
	v_and_b32_e32 v61, 0xffff0000, v61
	v_and_b32_e32 v60, 0xffff0000, v59
	v_lshlrev_b32_e32 v64, 16, v58
	v_lshlrev_b32_e32 v72, 16, v59
	v_pk_mul_f32 v[58:59], v[70:71], v[70:71]
	v_pk_mul_f32 v[60:61], v[60:61], v[60:61]
	v_pk_fma_f32 v[58:59], v[64:65], v[64:65], v[58:59]
	v_pk_fma_f32 v[60:61], v[72:73], v[72:73], v[60:61]
	v_cmp_lt_i32_e32 vcc, v203, v198
	v_pk_add_f32 v[58:59], v[58:59], v[60:61]
	s_nop 0
	v_add_f32_e32 v58, v58, v59
	v_cndmask_b32_e32 v59, v195, v203, vcc
	v_lshlrev_b32_e32 v59, 2, v59
	ds_bpermute_b32 v59, v59, v58
	v_cmp_lt_i32_e32 vcc, v204, v198
	s_waitcnt lgkmcnt(0)
	v_add_f32_e32 v58, v58, v59
	v_cndmask_b32_e32 v59, v195, v204, vcc
	v_lshlrev_b32_e32 v59, 2, v59
	ds_bpermute_b32 v59, v59, v58
	s_waitcnt lgkmcnt(0)
	v_add_f32_e32 v58, v58, v59
	v_max_f32_e32 v63, 0, v58
;     __device__ __forceinline__ void operator()(const f32x4 (&acc)[2][2][4][2], const pg8::Unit& u, int wr, int wc, int fr_, int fq_, int tid) {
;     ...
; #pragma unroll
;             for (int ai = 0; ai < 2; ++ai)
; #pragma unroll
;                 for (int m = 0; m < 4; ++m) {
;                     const int s = s0 + ai * 128 + m * 16; const float rs = rsl[rl0 + ai * 128 + m * 16];
; #pragma unroll
;                     for (int bj = 0; bj < 2; ++bj) { const int head = 2 * (pn & 3) + bj;
;                         const u32x4 w = pack8bf(acc[ai][bj][m][0] * rs, acc[ai][bj][m][1] * rs);
;                         *(u32x4*)(base + ((size_t)(b * FOXH + head) * SEQ + s) * HD + wc * 32 + 8 * fq) = w;
;                         if (t < 2) { float f[8]; unpack8(w, f);
;                             float ss = ((f[0] * f[0] + f[1] * f[1]) + (f[2] * f[2] + f[3] * f[3])) + ((f[4] * f[4] + f[5] * f[5]) + (f[6] * f[6] + f[7] * f[7]));
;                             ss += __shfl_xor(ss, 16); ss += __shfl_xor(ss, 32); mx[ai][bj] = fmaxf(mx[ai][bj], ss); } }
;                 }
.LBB0_465:
	v_mov_b32_e32 v69, v68
	v_mov_b32_e32 v58, v68
	v_mov_b32_e32 v59, v68
	v_pk_mul_f32 v[54:55], v[54:55], v[68:69]
	v_pk_mul_f32 v[56:57], v[56:57], v[58:59]
	v_pk_mul_f32 v[58:59], v[52:53], v[58:59]
	v_pk_mul_f32 v[52:53], v[50:51], v[68:69]
	v_cvt_pk_bf16_f32 v50, v54, v55
	v_lshl_add_u64 v[54:55], v[66:67], 0, s[38:39]
	s_and_b64 vcc, exec, s[8:9]
	v_cvt_pk_bf16_f32 v51, v56, v57
	v_cvt_pk_bf16_f32 v52, v52, v53
	v_cvt_pk_bf16_f32 v53, v58, v59
	global_store_dwordx4 v[54:55], v[50:53], off sc1
	s_cbranch_vccnz .LBB0_467
	v_lshlrev_b32_e32 v55, 16, v52
	v_and_b32_e32 v57, 0xffff0000, v52
	v_and_b32_e32 v56, 0xffff0000, v50
	v_lshlrev_b32_e32 v59, 16, v53
	v_and_b32_e32 v53, 0xffff0000, v53
	v_and_b32_e32 v52, 0xffff0000, v51
	v_lshlrev_b32_e32 v54, 16, v50
	v_lshlrev_b32_e32 v58, 16, v51
	v_pk_mul_f32 v[50:51], v[56:57], v[56:57]
	v_pk_mul_f32 v[52:53], v[52:53], v[52:53]
	v_pk_fma_f32 v[50:51], v[54:55], v[54:55], v[50:51]
	v_pk_fma_f32 v[52:53], v[58:59], v[58:59], v[52:53]
	v_cmp_lt_i32_e32 vcc, v203, v198
	v_pk_add_f32 v[50:51], v[50:51], v[52:53]
	s_nop 0
	v_add_f32_e32 v50, v50, v51
	v_cndmask_b32_e32 v51, v195, v203, vcc
	v_lshlrev_b32_e32 v51, 2, v51
	ds_bpermute_b32 v51, v51, v50
	v_cmp_lt_i32_e32 vcc, v204, v198
	s_waitcnt lgkmcnt(0)
	v_add_f32_e32 v50, v50, v51
	v_cndmask_b32_e32 v51, v195, v204, vcc
	v_lshlrev_b32_e32 v51, 2, v51
	ds_bpermute_b32 v51, v51, v50
	s_waitcnt lgkmcnt(0)
	v_add_f32_e32 v50, v50, v51
	v_max_f32_e32 v62, 0, v50
.LBB0_467:
	ds_read_b32 v52, v136 offset:576
	v_lshlrev_b64 v[50:51], 8, v[154:155]
	v_lshl_add_u64 v[50:51], v[130:131], 0, v[50:51]
	s_mov_b64 s[40:41], 0x9000
	v_lshl_add_u64 v[50:51], v[50:51], 0, s[40:41]
	s_waitcnt lgkmcnt(0)
	v_pk_mul_f32 v[46:47], v[46:47], v[52:53] op_sel_hi:[1,0]
	v_pk_mul_f32 v[54:55], v[44:45], v[52:53] op_sel_hi:[1,0]
	v_pk_mul_f32 v[44:45], v[42:43], v[52:53] op_sel_hi:[1,0]
	v_cvt_pk_bf16_f32 v42, v46, v47
	v_lshl_add_u64 v[46:47], v[50:51], 0, s[10:11]
	s_and_b64 vcc, exec, s[8:9]
	v_pk_mul_f32 v[48:49], v[48:49], v[52:53] op_sel_hi:[1,0]
	s_nop 0
	v_cvt_pk_bf16_f32 v43, v48, v49
	v_cvt_pk_bf16_f32 v44, v44, v45
	v_cvt_pk_bf16_f32 v45, v54, v55
	global_store_dwordx4 v[46:47], v[42:45], off sc1
	s_cbranch_vccnz .LBB0_469
	v_lshlrev_b32_e32 v47, 16, v44
	v_and_b32_e32 v49, 0xffff0000, v44
	v_and_b32_e32 v48, 0xffff0000, v42
	v_lshlrev_b32_e32 v55, 16, v45
	v_and_b32_e32 v45, 0xffff0000, v45
	v_and_b32_e32 v44, 0xffff0000, v43
	v_lshlrev_b32_e32 v46, 16, v42
	v_lshlrev_b32_e32 v54, 16, v43
	v_pk_mul_f32 v[42:43], v[48:49], v[48:49]
	v_pk_mul_f32 v[44:45], v[44:45], v[44:45]
	v_pk_fma_f32 v[42:43], v[46:47], v[46:47], v[42:43]
	v_pk_fma_f32 v[44:45], v[54:55], v[54:55], v[44:45]
	v_cmp_lt_i32_e32 vcc, v203, v198
	v_pk_add_f32 v[42:43], v[42:43], v[44:45]
	s_nop 0
	v_add_f32_e32 v42, v42, v43
	v_cndmask_b32_e32 v43, v195, v203, vcc
	v_lshlrev_b32_e32 v43, 2, v43
	ds_bpermute_b32 v43, v43, v42
	v_cmp_lt_i32_e32 vcc, v204, v198
	s_waitcnt lgkmcnt(0)
	v_add_f32_e32 v42, v42, v43
	v_cndmask_b32_e32 v43, v195, v204, vcc
	v_lshlrev_b32_e32 v43, 2, v43
	ds_bpermute_b32 v43, v43, v42
	s_waitcnt lgkmcnt(0)
	v_add_f32_e32 v42, v42, v43
	v_max_f32_e32 v43, v63, v63
	v_max_f32_e32 v63, v43, v42
.LBB0_469:
	v_mov_b32_e32 v53, v52
	v_mov_b32_e32 v42, v52
	v_mov_b32_e32 v43, v52
	v_pk_mul_f32 v[38:39], v[38:39], v[52:53]
	v_pk_mul_f32 v[40:41], v[40:41], v[42:43]
	v_pk_mul_f32 v[42:43], v[36:37], v[42:43]
	v_pk_mul_f32 v[36:37], v[34:35], v[52:53]
	v_cvt_pk_bf16_f32 v34, v38, v39
	v_lshl_add_u64 v[38:39], v[50:51], 0, s[38:39]
	s_and_b64 vcc, exec, s[8:9]
	v_cvt_pk_bf16_f32 v35, v40, v41
	v_cvt_pk_bf16_f32 v36, v36, v37
	v_cvt_pk_bf16_f32 v37, v42, v43
	global_store_dwordx4 v[38:39], v[34:37], off sc1
	s_cbranch_vccnz .LBB0_471
	v_lshlrev_b32_e32 v39, 16, v36
	v_and_b32_e32 v41, 0xffff0000, v36
	v_and_b32_e32 v40, 0xffff0000, v34
	v_lshlrev_b32_e32 v43, 16, v37
	v_and_b32_e32 v37, 0xffff0000, v37
	v_and_b32_e32 v36, 0xffff0000, v35
	v_lshlrev_b32_e32 v38, 16, v34
	v_lshlrev_b32_e32 v42, 16, v35
	v_pk_mul_f32 v[34:35], v[40:41], v[40:41]
	v_pk_mul_f32 v[36:37], v[36:37], v[36:37]
	v_pk_fma_f32 v[34:35], v[38:39], v[38:39], v[34:35]
	v_pk_fma_f32 v[36:37], v[42:43], v[42:43], v[36:37]
	v_cmp_lt_i32_e32 vcc, v203, v198
	v_pk_add_f32 v[34:35], v[34:35], v[36:37]
	s_nop 0
	v_add_f32_e32 v34, v34, v35
	v_cndmask_b32_e32 v35, v195, v203, vcc
	v_lshlrev_b32_e32 v35, 2, v35
	ds_bpermute_b32 v35, v35, v34
	v_cmp_lt_i32_e32 vcc, v204, v198
	s_waitcnt lgkmcnt(0)
	v_add_f32_e32 v34, v34, v35
	v_cndmask_b32_e32 v35, v195, v204, vcc
	v_lshlrev_b32_e32 v35, 2, v35
	ds_bpermute_b32 v35, v35, v34
	s_waitcnt lgkmcnt(0)
	v_add_f32_e32 v34, v34, v35
	v_max_f32_e32 v35, v62, v62
	v_max_f32_e32 v62, v35, v34
.LBB0_471:
	ds_read_b32 v36, v136 offset:640
	v_lshlrev_b64 v[34:35], 8, v[154:155]
	v_lshl_add_u64 v[34:35], v[130:131], 0, v[34:35]
	s_mov_b64 s[40:41], 0xa000
	v_lshl_add_u64 v[34:35], v[34:35], 0, s[40:41]
	s_waitcnt lgkmcnt(0)
	v_pk_mul_f32 v[30:31], v[30:31], v[36:37] op_sel_hi:[1,0]
	v_pk_mul_f32 v[38:39], v[28:29], v[36:37] op_sel_hi:[1,0]
	v_pk_mul_f32 v[28:29], v[26:27], v[36:37] op_sel_hi:[1,0]
	v_cvt_pk_bf16_f32 v26, v30, v31
	v_lshl_add_u64 v[30:31], v[34:35], 0, s[10:11]
	s_and_b64 vcc, exec, s[8:9]
	v_pk_mul_f32 v[32:33], v[32:33], v[36:37] op_sel_hi:[1,0]
	s_nop 0
	v_cvt_pk_bf16_f32 v27, v32, v33
	v_cvt_pk_bf16_f32 v28, v28, v29
	v_cvt_pk_bf16_f32 v29, v38, v39
	global_store_dwordx4 v[30:31], v[26:29], off sc1
	s_cbranch_vccnz .LBB0_473
	v_lshlrev_b32_e32 v31, 16, v28
	v_and_b32_e32 v33, 0xffff0000, v28
	v_and_b32_e32 v32, 0xffff0000, v26
	v_lshlrev_b32_e32 v39, 16, v29
	v_and_b32_e32 v29, 0xffff0000, v29
	v_and_b32_e32 v28, 0xffff0000, v27
	v_lshlrev_b32_e32 v30, 16, v26
	v_lshlrev_b32_e32 v38, 16, v27
	v_pk_mul_f32 v[26:27], v[32:33], v[32:33]
	v_pk_mul_f32 v[28:29], v[28:29], v[28:29]
	v_pk_fma_f32 v[26:27], v[30:31], v[30:31], v[26:27]
	v_pk_fma_f32 v[28:29], v[38:39], v[38:39], v[28:29]
	v_cmp_lt_i32_e32 vcc, v203, v198
	v_pk_add_f32 v[26:27], v[26:27], v[28:29]
	s_nop 0
	v_add_f32_e32 v26, v26, v27
	v_cndmask_b32_e32 v27, v195, v203, vcc
	v_lshlrev_b32_e32 v27, 2, v27
	ds_bpermute_b32 v27, v27, v26
	v_cmp_lt_i32_e32 vcc, v204, v198
	s_waitcnt lgkmcnt(0)
	v_add_f32_e32 v26, v26, v27
	v_cndmask_b32_e32 v27, v195, v204, vcc
	v_lshlrev_b32_e32 v27, 2, v27
	ds_bpermute_b32 v27, v27, v26
	s_waitcnt lgkmcnt(0)
	v_add_f32_e32 v26, v26, v27
	v_max_f32_e32 v27, v63, v63
	v_max_f32_e32 v63, v27, v26
;     __device__ __forceinline__ void operator()(const f32x4 (&acc)[2][2][4][2], const pg8::Unit& u, int wr, int wc, int fr_, int fq_, int tid) {
;     ...
; #pragma unroll
;             for (int ai = 0; ai < 2; ++ai)
; #pragma unroll
;                 for (int m = 0; m < 4; ++m) {
;                     const int s = s0 + ai * 128 + m * 16; const float rs = rsl[rl0 + ai * 128 + m * 16];
; #pragma unroll
;                     for (int bj = 0; bj < 2; ++bj) { const int head = 2 * (pn & 3) + bj;
;                         const u32x4 w = pack8bf(acc[ai][bj][m][0] * rs, acc[ai][bj][m][1] * rs);
;                         *(u32x4*)(base + ((size_t)(b * FOXH + head) * SEQ + s) * HD + wc * 32 + 8 * fq) = w;
;                         if (t < 2) { float f[8]; unpack8(w, f);
;                             float ss = ((f[0] * f[0] + f[1] * f[1]) + (f[2] * f[2] + f[3] * f[3])) + ((f[4] * f[4] + f[5] * f[5]) + (f[6] * f[6] + f[7] * f[7]));
;                             ss += __shfl_xor(ss, 16); ss += __shfl_xor(ss, 32); mx[ai][bj] = fmaxf(mx[ai][bj], ss); } }
;                 }
.LBB0_473:
	v_mov_b32_e32 v37, v36
	v_mov_b32_e32 v26, v36
	v_mov_b32_e32 v27, v36
	v_pk_mul_f32 v[22:23], v[22:23], v[36:37]
	v_pk_mul_f32 v[24:25], v[24:25], v[26:27]
	v_pk_mul_f32 v[26:27], v[20:21], v[26:27]
	v_pk_mul_f32 v[20:21], v[18:19], v[36:37]
	v_cvt_pk_bf16_f32 v18, v22, v23
	v_lshl_add_u64 v[22:23], v[34:35], 0, s[38:39]
	s_and_b64 vcc, exec, s[8:9]
	v_cvt_pk_bf16_f32 v19, v24, v25
	v_cvt_pk_bf16_f32 v20, v20, v21
	v_cvt_pk_bf16_f32 v21, v26, v27
	global_store_dwordx4 v[22:23], v[18:21], off sc1
	s_cbranch_vccnz .LBB0_475
	v_lshlrev_b32_e32 v23, 16, v20
	v_and_b32_e32 v25, 0xffff0000, v20
	v_and_b32_e32 v24, 0xffff0000, v18
	v_lshlrev_b32_e32 v27, 16, v21
	v_and_b32_e32 v21, 0xffff0000, v21
	v_and_b32_e32 v20, 0xffff0000, v19
	v_lshlrev_b32_e32 v22, 16, v18
	v_lshlrev_b32_e32 v26, 16, v19
	v_pk_mul_f32 v[18:19], v[24:25], v[24:25]
	v_pk_mul_f32 v[20:21], v[20:21], v[20:21]
	v_pk_fma_f32 v[18:19], v[22:23], v[22:23], v[18:19]
	v_pk_fma_f32 v[20:21], v[26:27], v[26:27], v[20:21]
	v_cmp_lt_i32_e32 vcc, v203, v198
	v_pk_add_f32 v[18:19], v[18:19], v[20:21]
	s_nop 0
	v_add_f32_e32 v18, v18, v19
	v_cndmask_b32_e32 v19, v195, v203, vcc
	v_lshlrev_b32_e32 v19, 2, v19
	ds_bpermute_b32 v19, v19, v18
	v_cmp_lt_i32_e32 vcc, v204, v198
	s_waitcnt lgkmcnt(0)
	v_add_f32_e32 v18, v18, v19
	v_cndmask_b32_e32 v19, v195, v204, vcc
	v_lshlrev_b32_e32 v19, 2, v19
	ds_bpermute_b32 v19, v19, v18
	s_waitcnt lgkmcnt(0)
	v_add_f32_e32 v18, v18, v19
	v_max_f32_e32 v19, v62, v62
	v_max_f32_e32 v62, v19, v18
.LBB0_475:
	ds_read_b32 v20, v136 offset:704
	v_lshlrev_b64 v[18:19], 8, v[154:155]
	v_lshl_add_u64 v[18:19], v[130:131], 0, v[18:19]
	s_mov_b64 s[40:41], 0xb000
	v_lshl_add_u64 v[18:19], v[18:19], 0, s[40:41]
	s_waitcnt lgkmcnt(0)
	v_pk_mul_f32 v[14:15], v[14:15], v[20:21] op_sel_hi:[1,0]
	v_pk_mul_f32 v[22:23], v[12:13], v[20:21] op_sel_hi:[1,0]
	v_pk_mul_f32 v[12:13], v[10:11], v[20:21] op_sel_hi:[1,0]
	v_cvt_pk_bf16_f32 v10, v14, v15
	v_lshl_add_u64 v[14:15], v[18:19], 0, s[10:11]
	s_and_b64 vcc, exec, s[8:9]
	v_pk_mul_f32 v[16:17], v[16:17], v[20:21] op_sel_hi:[1,0]
	s_nop 0
	v_cvt_pk_bf16_f32 v11, v16, v17
	v_cvt_pk_bf16_f32 v12, v12, v13
	v_cvt_pk_bf16_f32 v13, v22, v23
	global_store_dwordx4 v[14:15], v[10:13], off sc1
	s_cbranch_vccnz .LBB0_477
	v_lshlrev_b32_e32 v15, 16, v12
	v_and_b32_e32 v17, 0xffff0000, v12
	v_and_b32_e32 v16, 0xffff0000, v10
	v_lshlrev_b32_e32 v23, 16, v13
	v_and_b32_e32 v13, 0xffff0000, v13
	v_and_b32_e32 v12, 0xffff0000, v11
	v_lshlrev_b32_e32 v14, 16, v10
	v_lshlrev_b32_e32 v22, 16, v11
	v_pk_mul_f32 v[10:11], v[16:17], v[16:17]
	v_pk_mul_f32 v[12:13], v[12:13], v[12:13]
	v_pk_fma_f32 v[10:11], v[14:15], v[14:15], v[10:11]
	v_pk_fma_f32 v[12:13], v[22:23], v[22:23], v[12:13]
	v_cmp_lt_i32_e32 vcc, v203, v198
	v_pk_add_f32 v[10:11], v[10:11], v[12:13]
	s_nop 0
	v_add_f32_e32 v10, v10, v11
	v_cndmask_b32_e32 v11, v195, v203, vcc
	v_lshlrev_b32_e32 v11, 2, v11
	ds_bpermute_b32 v11, v11, v10
	v_cmp_lt_i32_e32 vcc, v204, v198
	s_waitcnt lgkmcnt(0)
	v_add_f32_e32 v10, v10, v11
	v_cndmask_b32_e32 v11, v195, v204, vcc
	v_lshlrev_b32_e32 v11, 2, v11
	ds_bpermute_b32 v11, v11, v10
	s_waitcnt lgkmcnt(0)
	v_add_f32_e32 v10, v10, v11
	v_max_f32_e32 v11, v63, v63
	v_max_f32_e32 v63, v11, v10
;     __device__ __forceinline__ void operator()(const f32x4 (&acc)[2][2][4][2], const pg8::Unit& u, int wr, int wc, int fr_, int fq_, int tid) {
;     ...
;                         const u32x4 w = pack8bf(acc[ai][bj][m][0] * rs, acc[ai][bj][m][1] * rs);
;                         *(u32x4*)(base + ((size_t)(b * FOXH + head) * SEQ + s) * HD + wc * 32 + 8 * fq) = w;
;                         if (t < 2) { float f[8]; unpack8(w, f);
;                             float ss = ((f[0] * f[0] + f[1] * f[1]) + (f[2] * f[2] + f[3] * f[3])) + ((f[4] * f[4] + f[5] * f[5]) + (f[6] * f[6] + f[7] * f[7]));
;                             ss += __shfl_xor(ss, 16); ss += __shfl_xor(ss, 32); mx[ai][bj] = fmaxf(mx[ai][bj], ss); } }
;                 }
;             if (t < 2) {
; #pragma unroll
;                 for (int ai = 0; ai < 2; ++ai)
; #pragma unroll
;                     for (int bj = 0; bj < 2; ++bj) { float v = mx[ai][bj];
;                         v = fmaxf(v, __shfl_xor(v, 1)); v = fmaxf(v, __shfl_xor(v, 2)); v = fmaxf(v, __shfl_xor(v, 4)); v = fmaxf(v, __shfl_xor(v, 8));
;                         if (fr == 0 && fq == 0) norms4[((((1 - t) * 32 + b * FOXH + 2 * (pn & 3) + bj) * 64 + (((u.pm & 15) * 4 + 2 * ai + wr))) << 2) + wc] = v; }
.LBB0_477:
	v_mov_b32_e32 v21, v20
	v_mov_b32_e32 v10, v20
	v_mov_b32_e32 v11, v20
	v_pk_mul_f32 v[6:7], v[6:7], v[20:21]
	v_pk_mul_f32 v[8:9], v[8:9], v[10:11]
	v_pk_mul_f32 v[10:11], v[4:5], v[10:11]
	v_pk_mul_f32 v[4:5], v[2:3], v[20:21]
	v_cvt_pk_bf16_f32 v2, v6, v7
	v_lshl_add_u64 v[6:7], v[18:19], 0, s[38:39]
	s_and_b64 vcc, exec, s[8:9]
	v_cvt_pk_bf16_f32 v3, v8, v9
	v_cvt_pk_bf16_f32 v4, v4, v5
	v_cvt_pk_bf16_f32 v5, v10, v11
	global_store_dwordx4 v[6:7], v[2:5], off sc1
	s_cbranch_vccnz .LBB0_487
	v_lshlrev_b32_e32 v6, 16, v2
	v_and_b32_e32 v2, 0xffff0000, v2
	v_lshlrev_b32_e32 v7, 16, v3
	v_and_b32_e32 v3, 0xffff0000, v3
	v_mul_f32_e32 v2, v2, v2
	v_mul_f32_e32 v3, v3, v3
	v_lshlrev_b32_e32 v8, 16, v4
	v_and_b32_e32 v4, 0xffff0000, v4
	v_lshlrev_b32_e32 v9, 16, v5
	v_and_b32_e32 v5, 0xffff0000, v5
	v_fmac_f32_e32 v2, v6, v6
	v_fmac_f32_e32 v3, v7, v7
	v_add_f32_e32 v2, v2, v3
	v_mul_f32_e32 v3, v4, v4
	v_mul_f32_e32 v4, v5, v5
	v_fmac_f32_e32 v3, v8, v8
	v_fmac_f32_e32 v4, v9, v9
	v_add_f32_e32 v3, v3, v4
	v_cmp_lt_i32_e32 vcc, v203, v198
	v_add_f32_e32 v2, v2, v3
	v_max_f32_e32 v9, v127, v127
	v_cndmask_b32_e32 v3, v195, v203, vcc
	v_lshlrev_b32_e32 v3, 2, v3
	ds_bpermute_b32 v3, v3, v2
	v_cmp_lt_i32_e32 vcc, v204, v198
	s_lshl_b32 s0, s0, 5
	s_sub_i32 s0, s1, s0
	s_add_i32 s8, s0, s29
	s_waitcnt lgkmcnt(0)
	v_add_f32_e32 v2, v2, v3
	v_cndmask_b32_e32 v3, v195, v204, vcc
	v_cmp_lt_i32_e32 vcc, v199, v198
	v_lshlrev_b32_e32 v3, 2, v3
	ds_bpermute_b32 v3, v3, v2
	v_cndmask_b32_e32 v4, v195, v199, vcc
	v_lshlrev_b32_e32 v4, 2, v4
	ds_bpermute_b32 v7, v4, v127
	v_cmp_lt_i32_e32 vcc, v200, v198
	s_lshl_b32 s0, s20, 2
	s_and_b32 s0, s0, 60
	v_cndmask_b32_e32 v5, v195, v200, vcc
	s_waitcnt lgkmcnt(0)
	v_max_f32_e32 v7, v7, v7
	v_lshlrev_b32_e32 v5, 2, v5
	v_max_f32_e32 v9, v9, v7
	ds_bpermute_b32 v10, v5, v9
	v_cmp_lt_i32_e32 vcc, v201, v198
	s_add_i32 s0, s0, s52
	s_lshl_b32 s9, s0, 2
	v_cndmask_b32_e32 v6, v195, v201, vcc
	v_cmp_lt_i32_e32 vcc, v202, v198
	v_lshlrev_b32_e32 v6, 2, v6
	s_add_i32 s8, s8, 32
	v_cndmask_b32_e32 v8, v195, v202, vcc
	v_lshlrev_b32_e32 v7, 2, v8
	v_or_b32_e32 v8, v177, v176
	v_cmp_eq_u32_e32 vcc, 0, v8
	s_waitcnt lgkmcnt(0)
	v_max_f32_e32 v8, v10, v10
	v_max_f32_e32 v8, v9, v8
	ds_bpermute_b32 v9, v6, v8
	s_or_b32 s10, s9, s61
	s_waitcnt lgkmcnt(0)
	v_max_f32_e32 v9, v9, v9
	v_max_f32_e32 v8, v8, v9
	ds_bpermute_b32 v9, v7, v8
	s_and_saveexec_b64 s[0:1], vcc
	s_cbranch_execz .LBB0_480
	s_lshl_b32 s11, s8, 8
	s_add_i32 s38, s11, s10
	s_ashr_i32 s39, s38, 31
	s_lshl_b64 s[38:39], s[38:39], 2
	s_waitcnt lgkmcnt(0)
	v_max_f32_e32 v9, v9, v9
	v_max_f32_e32 v8, v8, v8
	s_add_u32 s38, s59, s38
	v_max_f32_e32 v8, v8, v9
	s_addc_u32 s39, s60, s39
	global_store_dword v163, v8, s[38:39] sc1
.LBB0_480:
	s_or_b64 exec, exec, s[0:1]
	ds_bpermute_b32 v8, v4, v126
	s_waitcnt lgkmcnt(0)
	v_max_f32_e32 v9, v126, v126
	v_max_f32_e32 v8, v8, v8
	v_max_f32_e32 v8, v9, v8
	ds_bpermute_b32 v9, v5, v8
	s_waitcnt lgkmcnt(0)
	v_max_f32_e32 v9, v9, v9
	v_max_f32_e32 v8, v8, v9
	ds_bpermute_b32 v9, v6, v8
	s_waitcnt lgkmcnt(0)
	v_max_f32_e32 v9, v9, v9
	v_max_f32_e32 v8, v8, v9
	ds_bpermute_b32 v9, v7, v8
	s_and_saveexec_b64 s[0:1], vcc
	s_cbranch_execz .LBB0_482
	s_lshl_b32 s11, s8, 8
	s_add_i32 s10, s10, s11
	s_addk_i32 s10, 0x100
	s_ashr_i32 s11, s10, 31
	s_lshl_b64 s[10:11], s[10:11], 2
	s_waitcnt lgkmcnt(0)
	v_max_f32_e32 v9, v9, v9
	v_max_f32_e32 v8, v8, v8
	s_add_u32 s10, s59, s10
	v_max_f32_e32 v8, v8, v9
	s_addc_u32 s11, s60, s11
	global_store_dword v163, v8, s[10:11] sc1
.LBB0_482:
	s_or_b64 exec, exec, s[0:1]
	ds_bpermute_b32 v8, v4, v63
	s_waitcnt lgkmcnt(0)
	v_max_f32_e32 v9, v63, v63
	s_add_i32 s9, s9, s65
	v_max_f32_e32 v8, v8, v8
	v_max_f32_e32 v8, v9, v8
	ds_bpermute_b32 v9, v5, v8
	s_waitcnt lgkmcnt(0)
	v_max_f32_e32 v9, v9, v9
	v_max_f32_e32 v8, v8, v9
	ds_bpermute_b32 v9, v6, v8
	s_waitcnt lgkmcnt(0)
	v_max_f32_e32 v9, v9, v9
	v_max_f32_e32 v8, v8, v9
	ds_bpermute_b32 v9, v7, v8
	s_and_saveexec_b64 s[0:1], vcc
	s_cbranch_execz .LBB0_484
	s_lshl_b32 s10, s8, 8
	s_add_i32 s10, s9, s10
	s_ashr_i32 s11, s10, 31
	s_lshl_b64 s[10:11], s[10:11], 2
	s_waitcnt lgkmcnt(0)
	v_max_f32_e32 v9, v9, v9
	v_max_f32_e32 v8, v8, v8
	s_add_u32 s10, s59, s10
	v_max_f32_e32 v8, v8, v9
	s_addc_u32 s11, s60, s11
	global_store_dword v163, v8, s[10:11] sc1
.LBB0_484:
	s_or_b64 exec, exec, s[0:1]
	v_add_f32_e32 v2, v2, v3
	v_max_f32_e32 v3, v62, v62
	v_max_f32_e32 v2, v3, v2
	ds_bpermute_b32 v3, v4, v2
	s_waitcnt lgkmcnt(0)
	v_max_f32_e32 v3, v3, v3
	v_max_f32_e32 v2, v2, v3
	ds_bpermute_b32 v3, v5, v2
	s_waitcnt lgkmcnt(0)
	v_max_f32_e32 v3, v3, v3
	v_max_f32_e32 v2, v2, v3
	ds_bpermute_b32 v3, v6, v2
	s_waitcnt lgkmcnt(0)
	v_max_f32_e32 v3, v3, v3
	v_max_f32_e32 v2, v2, v3
	ds_bpermute_b32 v3, v7, v2
	s_and_saveexec_b64 s[0:1], vcc
	s_cbranch_execz .LBB0_486
	s_lshl_b32 s8, s8, 8
	s_add_i32 s8, s9, s8
	s_addk_i32 s8, 0x100
	s_ashr_i32 s9, s8, 31
	s_lshl_b64 s[8:9], s[8:9], 2
	s_waitcnt lgkmcnt(0)
	v_max_f32_e32 v3, v3, v3
	v_max_f32_e32 v2, v2, v2
	s_add_u32 s8, s59, s8
	v_max_f32_e32 v2, v2, v3
	s_addc_u32 s9, s60, s9
	global_store_dword v163, v2, s[8:9] sc1

;     __device__ __forceinline__ void operator()(const f32x4 (&acc)[2][2][4][2], const pg8::Unit& u, int wr, int wc, int fr_, int fq_, int tid) {
;     ...
;         const int row0 = u.pm * 256 + wr * 64 + fr, col0 = u.pn * 256 + wc * 32 + 8 * fq;
;         const size_t base = (size_t)row0 * DM + col0;
;         f32x4 cur[4], nxt[4];
;     ...
;         ER_LD(cur, 0);
; #pragma unroll
;         for (int g = 0; g < 8; ++g) {
;             const int ai = g >> 2, m = g & 3;
;             if (g < 7) ER_LD(nxt, g + 1);
;             const size_t off = base + (size_t)(ai * 128 + m * 16) * DM; float s = 0.f;
; #pragma unroll
;             for (int bj = 0; bj < 2; ++bj) {
;                 const f32x4 n0 = cur[2 * bj] + acc[ai][bj][m][0] * alpha, n1 = cur[2 * bj + 1] + acc[ai][bj][m][1] * alpha;
;                 const u32x4 w = pack8bf(n0, n1);
;                 *(u32x4*)(xb + off + bj * 128) = w;
;                 float q[8]; unpack8(w, q);
;                 s += ((q[0] * q[0] + q[1] * q[1]) + (q[2] * q[2] + q[3] * q[3])) + ((q[4] * q[4] + q[5] * q[5]) + (q[6] * q[6] + q[7] * q[7]));
;             }
;             s += __shfl_xor(s, 16); s += __shfl_xor(s, 32);
;             if (fq == 0) ssq[(size_t)(row0 + ai * 128 + m * 16) * 32 + u.pn * 4 + wc] = s;
; #pragma unroll
;             for (int j = 0; j < 4; ++j) cur[j] = nxt[j];
;         }
.LBB0_1027:
	s_lshl_b32 s7, s22, 8
	v_mov_b32_e32 v130, v1
	v_mov_b32_e32 v173, v150
	s_add_i32 s7, s7, s44
	v_cmp_lt_i32_e32 vcc, v203, v198
	v_add_u32_e32 v174, s7, v130
	s_lshl_b32 s7, s6, 8
	s_or_b32 s7, s7, s45
	v_ashrrev_i32_e32 v175, 31, v174
	v_lshl_add_u32 v130, v173, 3, s7
	v_lshlrev_b64 v[132:133], 12, v[174:175]
	v_ashrrev_i32_e32 v131, 31, v130
	v_lshl_add_u64 v[132:133], s[8:9], 0, v[132:133]
	v_lshl_add_u64 v[148:149], v[130:131], 1, v[132:133]
	global_load_dwordx4 v[154:157], v[148:149], off
	global_load_dwordx4 v[158:161], v[148:149], off offset:256
	v_cndmask_b32_e32 v130, v195, v203, vcc
	v_lshlrev_b32_e32 v153, 2, v130
	v_add_co_u32_e32 v130, vcc, s86, v148
	s_lshl_b32 s22, s6, 2
	s_nop 0
	v_addc_co_u32_e32 v131, vcc, 0, v149, vcc
	global_load_dwordx4 v[134:137], v[130:131], off
	s_nop 0
	global_load_dwordx4 v[130:133], v[130:131], off offset:256
	v_cmp_lt_i32_e32 vcc, v204, v198
	v_cmp_eq_u32_e64 s[6:7], 0, v173
	s_ashr_i32 s23, s22, 31
	s_waitcnt vmcnt(0)
	v_lshlrev_b32_e32 v176, 16, v154
	v_and_b32_e32 v177, 0xffff0000, v154
	v_lshlrev_b32_e32 v154, 16, v155
	v_and_b32_e32 v155, 0xffff0000, v155
	v_lshlrev_b32_e32 v178, 16, v156
	v_and_b32_e32 v179, 0xffff0000, v156
	v_lshlrev_b32_e32 v156, 16, v157
	v_and_b32_e32 v157, 0xffff0000, v157
	v_lshlrev_b32_e32 v182, 16, v160
	v_and_b32_e32 v183, 0xffff0000, v160
	v_lshlrev_b32_e32 v180, 16, v158
	v_and_b32_e32 v181, 0xffff0000, v158
	v_lshlrev_b32_e32 v158, 16, v159
	v_and_b32_e32 v159, 0xffff0000, v159
	v_lshlrev_b32_e32 v160, 16, v161
	v_and_b32_e32 v161, 0xffff0000, v161
	v_pk_add_f32 v[128:129], v[128:129], v[154:155]
	v_pk_add_f32 v[126:127], v[126:127], v[176:177]
	v_pk_add_f32 v[124:125], v[124:125], v[156:157]
	v_pk_add_f32 v[122:123], v[122:123], v[178:179]
	v_pk_add_f32 v[156:157], v[114:115], v[182:183]
	v_cvt_pk_bf16_f32 v114, v126, v127
	v_cvt_pk_bf16_f32 v115, v128, v129
	v_pk_add_f32 v[120:121], v[120:121], v[158:159]
	v_pk_add_f32 v[118:119], v[118:119], v[180:181]
	v_pk_add_f32 v[154:155], v[116:117], v[160:161]
	v_cvt_pk_bf16_f32 v116, v122, v123
	v_cvt_pk_bf16_f32 v117, v124, v125
	global_store_dwordx4 v[148:149], v[114:117], off sc1
	v_lshlrev_b32_e32 v122, 16, v114
	v_lshlrev_b32_e32 v123, 16, v115
	v_and_b32_e32 v114, 0xffff0000, v114
	v_and_b32_e32 v115, 0xffff0000, v115
	v_and_b32_e32 v125, 0xffff0000, v116
	v_and_b32_e32 v127, 0xffff0000, v117
	v_lshlrev_b32_e32 v124, 16, v116
	v_lshlrev_b32_e32 v126, 16, v117
	v_cvt_pk_bf16_f32 v116, v118, v119
	v_cvt_pk_bf16_f32 v117, v120, v121
	v_cvt_pk_bf16_f32 v118, v156, v157
	v_cvt_pk_bf16_f32 v119, v154, v155
	v_mul_f32_e32 v114, v114, v114
	v_mul_f32_e32 v115, v115, v115
	v_mul_f32_e32 v120, v125, v125
	v_mul_f32_e32 v121, v127, v127
	v_and_b32_e32 v127, 0xffff0000, v116
	v_and_b32_e32 v129, 0xffff0000, v117
	v_and_b32_e32 v155, 0xffff0000, v118
	v_and_b32_e32 v157, 0xffff0000, v119
	v_lshlrev_b32_e32 v125, 16, v116
	v_lshlrev_b32_e32 v128, 16, v117
	v_lshlrev_b32_e32 v154, 16, v118
	v_lshlrev_b32_e32 v156, 16, v119
	v_fmac_f32_e32 v114, v122, v122
	v_fmac_f32_e32 v115, v123, v123
	v_fmac_f32_e32 v120, v124, v124
	v_fmac_f32_e32 v121, v126, v126
	v_mul_f32_e32 v122, v127, v127
	v_mul_f32_e32 v123, v129, v129
	v_mul_f32_e32 v124, v155, v155
	v_mul_f32_e32 v126, v157, v157
	v_add_f32_e32 v114, v114, v115
	v_add_f32_e32 v115, v120, v121
	v_fmac_f32_e32 v122, v125, v125
	v_fmac_f32_e32 v123, v128, v128
	v_fmac_f32_e32 v124, v154, v154
	v_fmac_f32_e32 v126, v156, v156
	v_add_f32_e32 v114, v114, v115
	v_add_f32_e32 v115, v122, v123
	v_add_f32_e32 v120, v124, v126
	v_add_f32_e32 v115, v115, v120
	v_add_f32_e32 v114, v114, v115
	ds_bpermute_b32 v115, v153, v114
	v_cndmask_b32_e32 v120, v195, v204, vcc
	v_lshlrev_b32_e32 v124, 2, v120
	global_store_dwordx4 v[148:149], v[116:119], off offset:256 sc1
	s_waitcnt lgkmcnt(0)
	v_add_f32_e32 v114, v114, v115
	ds_bpermute_b32 v115, v124, v114
	v_lshlrev_b64 v[116:117], 7, v[174:175]
	v_lshl_add_u64 v[122:123], s[10:11], 0, v[116:117]
	s_and_saveexec_b64 s[24:25], s[6:7]
	s_cbranch_execz .LBB0_1029
	v_lshl_add_u64 v[116:117], s[22:23], 2, v[122:123]
	s_lshl_b32 s96, s43, 2
	v_lshl_add_u64 v[116:117], v[116:117], 0, s[96:97]
	s_waitcnt lgkmcnt(0)
	v_add_f32_e32 v114, v114, v115
	global_store_dword v[116:117], v114, off sc1
;     __device__ __forceinline__ void operator()(const f32x4 (&acc)[2][2][4][2], const pg8::Unit& u, int wr, int wc, int fr_, int fq_, int tid) {
;     ...
;         const int row0 = u.pm * 256 + wr * 64 + fr, col0 = u.pn * 256 + wc * 32 + 8 * fq;
;         const size_t base = (size_t)row0 * DM + col0;
;         f32x4 cur[4], nxt[4];
;     ...
;         ER_LD(cur, 0);
; #pragma unroll
;         for (int g = 0; g < 8; ++g) {
;             const int ai = g >> 2, m = g & 3;
;             if (g < 7) ER_LD(nxt, g + 1);
;             const size_t off = base + (size_t)(ai * 128 + m * 16) * DM; float s = 0.f;
; #pragma unroll
;             for (int bj = 0; bj < 2; ++bj) {
;                 const f32x4 n0 = cur[2 * bj] + acc[ai][bj][m][0] * alpha, n1 = cur[2 * bj + 1] + acc[ai][bj][m][1] * alpha;
;                 const u32x4 w = pack8bf(n0, n1);
;                 *(u32x4*)(xb + off + bj * 128) = w;
;                 float q[8]; unpack8(w, q);
;                 s += ((q[0] * q[0] + q[1] * q[1]) + (q[2] * q[2] + q[3] * q[3])) + ((q[4] * q[4] + q[5] * q[5]) + (q[6] * q[6] + q[7] * q[7]));
;             }
;             s += __shfl_xor(s, 16); s += __shfl_xor(s, 32);
;             if (fq == 0) ssq[(size_t)(row0 + ai * 128 + m * 16) * 32 + u.pn * 4 + wc] = s;
; #pragma unroll
;             for (int j = 0; j < 4; ++j) cur[j] = nxt[j];
;         }
.LBB0_1029:
	s_or_b64 exec, exec, s[24:25]
	v_add_co_u32_e32 v114, vcc, s89, v148
	s_mov_b64 s[24:25], 0x10000
	s_waitcnt lgkmcnt(0)
	v_addc_co_u32_e32 v115, vcc, 0, v149, vcc
	global_load_dwordx4 v[118:121], v[114:115], off
	s_nop 0
	global_load_dwordx4 v[114:117], v[114:115], off offset:256
	v_lshlrev_b32_e32 v128, 16, v134
	v_and_b32_e32 v129, 0xffff0000, v134
	v_lshlrev_b32_e32 v134, 16, v135
	v_and_b32_e32 v135, 0xffff0000, v135
	v_lshlrev_b32_e32 v154, 16, v136
	v_and_b32_e32 v155, 0xffff0000, v136
	v_lshlrev_b32_e32 v136, 16, v137
	v_and_b32_e32 v137, 0xffff0000, v137
	v_lshl_add_u64 v[126:127], v[148:149], 0, s[24:25]
	v_pk_add_f32 v[112:113], v[112:113], v[134:135]
	v_pk_add_f32 v[110:111], v[110:111], v[128:129]
	v_pk_add_f32 v[128:129], v[108:109], v[136:137]
	v_pk_add_f32 v[108:109], v[106:107], v[154:155]
	v_cvt_pk_bf16_f32 v106, v110, v111
	v_cvt_pk_bf16_f32 v107, v112, v113
	v_lshlrev_b32_e32 v156, 16, v130
	v_cvt_pk_bf16_f32 v108, v108, v109
	v_cvt_pk_bf16_f32 v109, v128, v129
	global_store_dwordx4 v[126:127], v[106:109], off sc1
	v_lshlrev_b32_e32 v110, 16, v106
	v_lshlrev_b32_e32 v111, 16, v107
	v_and_b32_e32 v106, 0xffff0000, v106
	v_and_b32_e32 v107, 0xffff0000, v107
	v_mul_f32_e32 v106, v106, v106
	v_mul_f32_e32 v107, v107, v107
	v_lshlrev_b32_e32 v112, 16, v108
	v_and_b32_e32 v108, 0xffff0000, v108
	v_lshlrev_b32_e32 v113, 16, v109
	v_and_b32_e32 v109, 0xffff0000, v109
	v_fmac_f32_e32 v106, v110, v110
	v_fmac_f32_e32 v107, v111, v111
	v_add_f32_e32 v106, v106, v107
	v_mul_f32_e32 v107, v108, v108
	v_mul_f32_e32 v108, v109, v109
	v_and_b32_e32 v157, 0xffff0000, v130
	v_lshlrev_b32_e32 v158, 16, v132
	v_and_b32_e32 v159, 0xffff0000, v132
	v_fmac_f32_e32 v107, v112, v112
	v_fmac_f32_e32 v108, v113, v113
	v_lshlrev_b32_e32 v130, 16, v131
	v_and_b32_e32 v131, 0xffff0000, v131
	v_lshlrev_b32_e32 v132, 16, v133
	v_and_b32_e32 v133, 0xffff0000, v133
	v_add_f32_e32 v107, v107, v108
	v_pk_add_f32 v[102:103], v[102:103], v[156:157]
	v_pk_add_f32 v[98:99], v[98:99], v[158:159]
	v_add_f32_e32 v108, v106, v107
	v_pk_add_f32 v[104:105], v[104:105], v[130:131]
	v_pk_add_f32 v[106:107], v[100:101], v[132:133]
	v_cvt_pk_bf16_f32 v100, v102, v103
	v_cvt_pk_bf16_f32 v101, v104, v105
	v_cvt_pk_bf16_f32 v102, v98, v99
	s_mov_b64 s[24:25], 0x10100
	v_and_b32_e32 v99, 0xffff0000, v100
	v_lshlrev_b32_e32 v98, 16, v100
	v_and_b32_e32 v105, 0xffff0000, v101
	v_mul_f32_e32 v99, v99, v99
	v_lshlrev_b32_e32 v104, 16, v101
	v_fmac_f32_e32 v99, v98, v98
	v_mul_f32_e32 v98, v105, v105
	v_cvt_pk_bf16_f32 v103, v106, v107
	v_and_b32_e32 v107, 0xffff0000, v102
	v_and_b32_e32 v110, 0xffff0000, v103
	v_fmac_f32_e32 v98, v104, v104
	v_lshlrev_b32_e32 v106, 16, v102
	v_lshlrev_b32_e32 v109, 16, v103
	v_add_f32_e32 v98, v99, v98
	v_mul_f32_e32 v99, v107, v107
	v_mul_f32_e32 v104, v110, v110
	v_fmac_f32_e32 v99, v106, v106
	v_fmac_f32_e32 v104, v109, v109
	v_add_f32_e32 v99, v99, v104
	v_add_f32_e32 v98, v98, v99
	v_add_f32_e32 v98, v108, v98
	ds_bpermute_b32 v99, v153, v98
	v_lshl_add_u64 v[104:105], v[148:149], 0, s[24:25]
	global_store_dwordx4 v[104:105], v[100:103], off sc1
	s_waitcnt lgkmcnt(0)
	v_add_f32_e32 v98, v98, v99
	ds_bpermute_b32 v99, v124, v98
	s_and_saveexec_b64 s[24:25], s[6:7]
	s_cbranch_execz .LBB0_1031
	s_waitcnt lgkmcnt(0)
	v_add_f32_e32 v100, v98, v99
	v_lshl_add_u64 v[98:99], s[22:23], 2, v[122:123]
	s_lshl_b32 s96, s43, 2
	v_lshl_add_u64 v[98:99], v[98:99], 0, s[96:97]
	global_store_dword v[98:99], v100, off offset:2048 sc1
.LBB0_1031:
	s_or_b64 exec, exec, s[24:25]
	v_add_co_u32_e32 v98, vcc, s90, v148
	s_waitcnt vmcnt(3)
	v_lshlrev_b32_e32 v108, 16, v118
	s_waitcnt lgkmcnt(0)
	v_addc_co_u32_e32 v99, vcc, 0, v149, vcc
	global_load_dwordx4 v[102:105], v[98:99], off
	s_nop 0
	global_load_dwordx4 v[98:101], v[98:99], off offset:256
	v_and_b32_e32 v109, 0xffff0000, v118
	v_lshlrev_b32_e32 v110, 16, v119
	v_and_b32_e32 v111, 0xffff0000, v119
	v_lshlrev_b32_e32 v112, 16, v120
	v_and_b32_e32 v113, 0xffff0000, v120
	v_lshlrev_b32_e32 v118, 16, v121
	v_and_b32_e32 v119, 0xffff0000, v121
	v_lshl_add_u64 v[106:107], v[148:149], 0, s[64:65]
	v_pk_add_f32 v[96:97], v[96:97], v[110:111]
	v_pk_add_f32 v[94:95], v[94:95], v[108:109]
	v_pk_add_f32 v[108:109], v[92:93], v[118:119]
	v_pk_add_f32 v[92:93], v[90:91], v[112:113]
	v_cvt_pk_bf16_f32 v90, v94, v95
	v_cvt_pk_bf16_f32 v91, v96, v97
	s_waitcnt vmcnt(4)
	v_lshlrev_b32_e32 v120, 16, v114
	v_cvt_pk_bf16_f32 v92, v92, v93
	v_cvt_pk_bf16_f32 v93, v108, v109
	global_store_dwordx4 v[106:107], v[90:93], off sc1
	v_lshlrev_b32_e32 v94, 16, v90
	v_lshlrev_b32_e32 v95, 16, v91
	v_and_b32_e32 v90, 0xffff0000, v90
	v_and_b32_e32 v91, 0xffff0000, v91
	v_mul_f32_e32 v90, v90, v90
	v_mul_f32_e32 v91, v91, v91
	v_lshlrev_b32_e32 v96, 16, v92
	v_and_b32_e32 v92, 0xffff0000, v92
	v_lshlrev_b32_e32 v97, 16, v93
	v_and_b32_e32 v93, 0xffff0000, v93
	v_fmac_f32_e32 v90, v94, v94
	v_fmac_f32_e32 v91, v95, v95
	v_add_f32_e32 v90, v90, v91
	v_mul_f32_e32 v91, v92, v92
	v_mul_f32_e32 v92, v93, v93
	v_and_b32_e32 v121, 0xffff0000, v114
	v_lshlrev_b32_e32 v126, 16, v116
	v_and_b32_e32 v127, 0xffff0000, v116
	v_fmac_f32_e32 v91, v96, v96
	v_fmac_f32_e32 v92, v97, v97
	v_lshlrev_b32_e32 v114, 16, v115
	v_and_b32_e32 v115, 0xffff0000, v115
	v_lshlrev_b32_e32 v116, 16, v117
	v_and_b32_e32 v117, 0xffff0000, v117
	v_add_f32_e32 v91, v91, v92
	v_pk_add_f32 v[86:87], v[86:87], v[120:121]
	v_pk_add_f32 v[82:83], v[82:83], v[126:127]
	v_add_f32_e32 v92, v90, v91
	v_pk_add_f32 v[88:89], v[88:89], v[114:115]
	v_pk_add_f32 v[90:91], v[84:85], v[116:117]
	v_cvt_pk_bf16_f32 v84, v86, v87
	v_cvt_pk_bf16_f32 v85, v88, v89
	v_cvt_pk_bf16_f32 v86, v82, v83
	s_mov_b64 s[24:25], 0x20100
	v_and_b32_e32 v83, 0xffff0000, v84
	v_lshlrev_b32_e32 v82, 16, v84
	v_and_b32_e32 v89, 0xffff0000, v85
	v_mul_f32_e32 v83, v83, v83
	v_lshlrev_b32_e32 v88, 16, v85
	v_fmac_f32_e32 v83, v82, v82
	v_mul_f32_e32 v82, v89, v89
	v_cvt_pk_bf16_f32 v87, v90, v91
	v_and_b32_e32 v91, 0xffff0000, v86
	v_and_b32_e32 v94, 0xffff0000, v87
	v_fmac_f32_e32 v82, v88, v88
	v_lshlrev_b32_e32 v90, 16, v86
	v_lshlrev_b32_e32 v93, 16, v87
	v_add_f32_e32 v82, v83, v82
	v_mul_f32_e32 v83, v91, v91
	v_mul_f32_e32 v88, v94, v94
	v_fmac_f32_e32 v83, v90, v90
	v_fmac_f32_e32 v88, v93, v93
	v_add_f32_e32 v83, v83, v88
	v_add_f32_e32 v82, v82, v83
	v_add_f32_e32 v82, v92, v82
	ds_bpermute_b32 v83, v153, v82
	v_lshl_add_u64 v[88:89], v[148:149], 0, s[24:25]
	global_store_dwordx4 v[88:89], v[84:87], off sc1
	s_waitcnt lgkmcnt(0)
	v_add_f32_e32 v82, v82, v83
	ds_bpermute_b32 v83, v124, v82
	s_and_saveexec_b64 s[24:25], s[6:7]
	s_cbranch_execz .LBB0_1033
	s_waitcnt lgkmcnt(0)
	v_add_f32_e32 v84, v82, v83
	v_lshl_add_u64 v[82:83], s[22:23], 2, v[122:123]
	s_lshl_b32 s96, s43, 2
	v_lshl_add_u64 v[82:83], v[82:83], 0, s[96:97]
	v_add_co_u32_e32 v82, vcc, 0x1000, v82
	s_nop 1
	v_addc_co_u32_e32 v83, vcc, 0, v83, vcc
	global_store_dword v[82:83], v84, off sc1
;     __device__ __forceinline__ void operator()(const f32x4 (&acc)[2][2][4][2], const pg8::Unit& u, int wr, int wc, int fr_, int fq_, int tid) {
;     ...
;         const int row0 = u.pm * 256 + wr * 64 + fr, col0 = u.pn * 256 + wc * 32 + 8 * fq;
;         const size_t base = (size_t)row0 * DM + col0;
;         f32x4 cur[4], nxt[4];
;     ...
;         ER_LD(cur, 0);
; #pragma unroll
;         for (int g = 0; g < 8; ++g) {
;             const int ai = g >> 2, m = g & 3;
;             if (g < 7) ER_LD(nxt, g + 1);
;             const size_t off = base + (size_t)(ai * 128 + m * 16) * DM; float s = 0.f;
; #pragma unroll
;             for (int bj = 0; bj < 2; ++bj) {
;                 const f32x4 n0 = cur[2 * bj] + acc[ai][bj][m][0] * alpha, n1 = cur[2 * bj + 1] + acc[ai][bj][m][1] * alpha;
;                 const u32x4 w = pack8bf(n0, n1);
;                 *(u32x4*)(xb + off + bj * 128) = w;
;                 float q[8]; unpack8(w, q);
;                 s += ((q[0] * q[0] + q[1] * q[1]) + (q[2] * q[2] + q[3] * q[3])) + ((q[4] * q[4] + q[5] * q[5]) + (q[6] * q[6] + q[7] * q[7]));
;             }
;             s += __shfl_xor(s, 16); s += __shfl_xor(s, 32);
;             if (fq == 0) ssq[(size_t)(row0 + ai * 128 + m * 16) * 32 + u.pn * 4 + wc] = s;
; #pragma unroll
;             for (int j = 0; j < 4; ++j) cur[j] = nxt[j];
;         }
.LBB0_1033:
	s_or_b64 exec, exec, s[24:25]
	v_add_co_u32_e32 v82, vcc, s91, v148
	s_waitcnt vmcnt(3)
	v_lshlrev_b32_e32 v92, 16, v102
	s_waitcnt lgkmcnt(0)
	v_addc_co_u32_e32 v83, vcc, 0, v149, vcc
	global_load_dwordx4 v[86:89], v[82:83], off
	s_nop 0
	global_load_dwordx4 v[82:85], v[82:83], off offset:256
	v_and_b32_e32 v93, 0xffff0000, v102
	v_lshlrev_b32_e32 v94, 16, v103
	v_and_b32_e32 v95, 0xffff0000, v103
	v_lshlrev_b32_e32 v96, 16, v104
	v_and_b32_e32 v97, 0xffff0000, v104
	v_lshlrev_b32_e32 v102, 16, v105
	v_and_b32_e32 v103, 0xffff0000, v105
	v_lshl_add_u64 v[90:91], v[148:149], 0, s[66:67]
	v_pk_add_f32 v[80:81], v[80:81], v[94:95]
	v_pk_add_f32 v[78:79], v[78:79], v[92:93]
	v_pk_add_f32 v[92:93], v[76:77], v[102:103]
	v_pk_add_f32 v[76:77], v[74:75], v[96:97]
	v_cvt_pk_bf16_f32 v74, v78, v79
	v_cvt_pk_bf16_f32 v75, v80, v81
	s_waitcnt vmcnt(4)
	v_lshlrev_b32_e32 v104, 16, v98
	v_cvt_pk_bf16_f32 v76, v76, v77
	v_cvt_pk_bf16_f32 v77, v92, v93
	global_store_dwordx4 v[90:91], v[74:77], off sc1
	v_lshlrev_b32_e32 v78, 16, v74
	v_lshlrev_b32_e32 v79, 16, v75
	v_and_b32_e32 v74, 0xffff0000, v74
	v_and_b32_e32 v75, 0xffff0000, v75
	v_mul_f32_e32 v74, v74, v74
	v_mul_f32_e32 v75, v75, v75
	v_lshlrev_b32_e32 v80, 16, v76
	v_and_b32_e32 v76, 0xffff0000, v76
	v_lshlrev_b32_e32 v81, 16, v77
	v_and_b32_e32 v77, 0xffff0000, v77
	v_fmac_f32_e32 v74, v78, v78
	v_fmac_f32_e32 v75, v79, v79
	v_add_f32_e32 v74, v74, v75
	v_mul_f32_e32 v75, v76, v76
	v_mul_f32_e32 v76, v77, v77
	v_and_b32_e32 v105, 0xffff0000, v98
	v_lshlrev_b32_e32 v106, 16, v100
	v_and_b32_e32 v107, 0xffff0000, v100
	v_fmac_f32_e32 v75, v80, v80
	v_fmac_f32_e32 v76, v81, v81
	v_lshlrev_b32_e32 v98, 16, v99
	v_and_b32_e32 v99, 0xffff0000, v99
	v_lshlrev_b32_e32 v100, 16, v101
	v_and_b32_e32 v101, 0xffff0000, v101
	v_add_f32_e32 v75, v75, v76
	v_pk_add_f32 v[70:71], v[70:71], v[104:105]
	v_pk_add_f32 v[66:67], v[66:67], v[106:107]
	v_add_f32_e32 v76, v74, v75
	v_pk_add_f32 v[72:73], v[72:73], v[98:99]
	v_pk_add_f32 v[74:75], v[68:69], v[100:101]
	v_cvt_pk_bf16_f32 v68, v70, v71
	v_cvt_pk_bf16_f32 v69, v72, v73
	v_cvt_pk_bf16_f32 v70, v66, v67
	s_mov_b64 s[24:25], 0x30100
	v_and_b32_e32 v67, 0xffff0000, v68
	v_lshlrev_b32_e32 v66, 16, v68
	v_and_b32_e32 v73, 0xffff0000, v69
	v_mul_f32_e32 v67, v67, v67
	v_lshlrev_b32_e32 v72, 16, v69
	v_fmac_f32_e32 v67, v66, v66
	v_mul_f32_e32 v66, v73, v73
	v_cvt_pk_bf16_f32 v71, v74, v75
	v_and_b32_e32 v75, 0xffff0000, v70
	v_and_b32_e32 v78, 0xffff0000, v71
	v_fmac_f32_e32 v66, v72, v72
	v_lshlrev_b32_e32 v74, 16, v70
	v_lshlrev_b32_e32 v77, 16, v71
	v_add_f32_e32 v66, v67, v66
	v_mul_f32_e32 v67, v75, v75
	v_mul_f32_e32 v72, v78, v78
	v_fmac_f32_e32 v67, v74, v74
	v_fmac_f32_e32 v72, v77, v77
	v_add_f32_e32 v67, v67, v72
	v_add_f32_e32 v66, v66, v67
	v_add_f32_e32 v66, v76, v66
	ds_bpermute_b32 v67, v153, v66
	v_lshl_add_u64 v[72:73], v[148:149], 0, s[24:25]
	global_store_dwordx4 v[72:73], v[68:71], off sc1
	s_waitcnt lgkmcnt(0)
	v_add_f32_e32 v66, v66, v67
	ds_bpermute_b32 v67, v124, v66
	s_and_saveexec_b64 s[24:25], s[6:7]
	s_cbranch_execz .LBB0_1035
	s_waitcnt lgkmcnt(0)
	v_add_f32_e32 v68, v66, v67
	v_lshl_add_u64 v[66:67], s[22:23], 2, v[122:123]
	s_lshl_b32 s96, s43, 2
	v_lshl_add_u64 v[66:67], v[66:67], 0, s[96:97]
	v_add_co_u32_e32 v66, vcc, 0x1000, v66
	s_nop 1
	v_addc_co_u32_e32 v67, vcc, 0, v67, vcc
	global_store_dword v[66:67], v68, off offset:2048 sc1
.LBB0_1035:
	s_or_b64 exec, exec, s[24:25]
	v_add_co_u32_e32 v66, vcc, s92, v148
	s_waitcnt vmcnt(3)
	v_lshlrev_b32_e32 v76, 16, v86
	s_waitcnt lgkmcnt(0)
	v_addc_co_u32_e32 v67, vcc, 0, v149, vcc
	global_load_dwordx4 v[70:73], v[66:67], off
	s_nop 0
	global_load_dwordx4 v[66:69], v[66:67], off offset:256
	v_and_b32_e32 v77, 0xffff0000, v86
	v_lshlrev_b32_e32 v78, 16, v87
	v_and_b32_e32 v79, 0xffff0000, v87
	v_lshlrev_b32_e32 v80, 16, v88
	v_and_b32_e32 v81, 0xffff0000, v88
	v_lshlrev_b32_e32 v86, 16, v89
	v_and_b32_e32 v87, 0xffff0000, v89
	v_lshl_add_u64 v[74:75], v[148:149], 0, s[94:95]
	v_pk_add_f32 v[64:65], v[64:65], v[78:79]
	v_pk_add_f32 v[62:63], v[62:63], v[76:77]
	v_pk_add_f32 v[76:77], v[60:61], v[86:87]
	v_pk_add_f32 v[60:61], v[58:59], v[80:81]
	v_cvt_pk_bf16_f32 v58, v62, v63
	v_cvt_pk_bf16_f32 v59, v64, v65
	s_waitcnt vmcnt(4)
	v_lshlrev_b32_e32 v88, 16, v82
	v_cvt_pk_bf16_f32 v60, v60, v61
	v_cvt_pk_bf16_f32 v61, v76, v77
	global_store_dwordx4 v[74:75], v[58:61], off sc1
	v_lshlrev_b32_e32 v62, 16, v58
	v_lshlrev_b32_e32 v63, 16, v59
	v_and_b32_e32 v58, 0xffff0000, v58
	v_and_b32_e32 v59, 0xffff0000, v59
	v_mul_f32_e32 v58, v58, v58
	v_mul_f32_e32 v59, v59, v59
	v_lshlrev_b32_e32 v64, 16, v60
	v_and_b32_e32 v60, 0xffff0000, v60
	v_lshlrev_b32_e32 v65, 16, v61
	v_and_b32_e32 v61, 0xffff0000, v61
	v_fmac_f32_e32 v58, v62, v62
	v_fmac_f32_e32 v59, v63, v63
	v_add_f32_e32 v58, v58, v59
	v_mul_f32_e32 v59, v60, v60
	v_mul_f32_e32 v60, v61, v61
	v_and_b32_e32 v89, 0xffff0000, v82
	v_lshlrev_b32_e32 v90, 16, v84
	v_and_b32_e32 v91, 0xffff0000, v84
	v_fmac_f32_e32 v59, v64, v64
	v_fmac_f32_e32 v60, v65, v65
	v_lshlrev_b32_e32 v82, 16, v83
	v_and_b32_e32 v83, 0xffff0000, v83
	v_lshlrev_b32_e32 v84, 16, v85
	v_and_b32_e32 v85, 0xffff0000, v85
	v_add_f32_e32 v59, v59, v60
	v_pk_add_f32 v[54:55], v[54:55], v[88:89]
	v_pk_add_f32 v[50:51], v[50:51], v[90:91]
	v_add_f32_e32 v60, v58, v59
	v_pk_add_f32 v[56:57], v[56:57], v[82:83]
	v_pk_add_f32 v[58:59], v[52:53], v[84:85]
	v_cvt_pk_bf16_f32 v52, v54, v55
	v_cvt_pk_bf16_f32 v53, v56, v57
	v_cvt_pk_bf16_f32 v54, v50, v51
	s_mov_b64 s[24:25], 0x80100
	v_and_b32_e32 v51, 0xffff0000, v52
	v_lshlrev_b32_e32 v50, 16, v52
	v_and_b32_e32 v57, 0xffff0000, v53
	v_mul_f32_e32 v51, v51, v51
	v_lshlrev_b32_e32 v56, 16, v53
	v_fmac_f32_e32 v51, v50, v50
	v_mul_f32_e32 v50, v57, v57
	v_cvt_pk_bf16_f32 v55, v58, v59
	v_and_b32_e32 v59, 0xffff0000, v54
	v_and_b32_e32 v62, 0xffff0000, v55
	v_fmac_f32_e32 v50, v56, v56
	v_lshlrev_b32_e32 v58, 16, v54
	v_lshlrev_b32_e32 v61, 16, v55
	v_add_f32_e32 v50, v51, v50
	v_mul_f32_e32 v51, v59, v59
	v_mul_f32_e32 v56, v62, v62
	v_fmac_f32_e32 v51, v58, v58
	v_fmac_f32_e32 v56, v61, v61
	v_add_f32_e32 v51, v51, v56
	v_add_f32_e32 v50, v50, v51
	v_add_f32_e32 v50, v60, v50
	ds_bpermute_b32 v51, v153, v50
	v_lshl_add_u64 v[56:57], v[148:149], 0, s[24:25]
	global_store_dwordx4 v[56:57], v[52:55], off sc1
	s_waitcnt lgkmcnt(0)
	v_add_f32_e32 v50, v50, v51
	ds_bpermute_b32 v51, v124, v50
	s_and_saveexec_b64 s[24:25], s[6:7]
	s_cbranch_execz .LBB0_1037
	s_waitcnt lgkmcnt(0)
	v_add_f32_e32 v52, v50, v51
	v_lshl_add_u64 v[50:51], s[22:23], 2, v[122:123]
	s_lshl_b32 s96, s43, 2
	v_lshl_add_u64 v[50:51], v[50:51], 0, s[96:97]
	v_add_co_u32_e32 v50, vcc, 0x4000, v50
	s_nop 1
	v_addc_co_u32_e32 v51, vcc, 0, v51, vcc
	global_store_dword v[50:51], v52, off sc1
;     __device__ __forceinline__ void operator()(const f32x4 (&acc)[2][2][4][2], const pg8::Unit& u, int wr, int wc, int fr_, int fq_, int tid) {
;     ...
;         const int row0 = u.pm * 256 + wr * 64 + fr, col0 = u.pn * 256 + wc * 32 + 8 * fq;
;         const size_t base = (size_t)row0 * DM + col0;
;         f32x4 cur[4], nxt[4];
;     ...
;         ER_LD(cur, 0);
; #pragma unroll
;         for (int g = 0; g < 8; ++g) {
;             const int ai = g >> 2, m = g & 3;
;             if (g < 7) ER_LD(nxt, g + 1);
;             const size_t off = base + (size_t)(ai * 128 + m * 16) * DM; float s = 0.f;
; #pragma unroll
;             for (int bj = 0; bj < 2; ++bj) {
;                 const f32x4 n0 = cur[2 * bj] + acc[ai][bj][m][0] * alpha, n1 = cur[2 * bj + 1] + acc[ai][bj][m][1] * alpha;
;                 const u32x4 w = pack8bf(n0, n1);
;                 *(u32x4*)(xb + off + bj * 128) = w;
;                 float q[8]; unpack8(w, q);
;                 s += ((q[0] * q[0] + q[1] * q[1]) + (q[2] * q[2] + q[3] * q[3])) + ((q[4] * q[4] + q[5] * q[5]) + (q[6] * q[6] + q[7] * q[7]));
;             }
;             s += __shfl_xor(s, 16); s += __shfl_xor(s, 32);
;             if (fq == 0) ssq[(size_t)(row0 + ai * 128 + m * 16) * 32 + u.pn * 4 + wc] = s;
; #pragma unroll
;             for (int j = 0; j < 4; ++j) cur[j] = nxt[j];
;         }
.LBB0_1037:
	s_or_b64 exec, exec, s[24:25]
	v_add_co_u32_e32 v50, vcc, s59, v148
	s_waitcnt vmcnt(3)
	v_lshlrev_b32_e32 v60, 16, v70
	s_waitcnt lgkmcnt(0)
	v_addc_co_u32_e32 v51, vcc, 0, v149, vcc
	global_load_dwordx4 v[54:57], v[50:51], off
	s_nop 0
	global_load_dwordx4 v[50:53], v[50:51], off offset:256
	v_and_b32_e32 v61, 0xffff0000, v70
	v_lshlrev_b32_e32 v62, 16, v71
	v_and_b32_e32 v63, 0xffff0000, v71
	v_lshlrev_b32_e32 v64, 16, v72
	v_and_b32_e32 v65, 0xffff0000, v72
	v_lshlrev_b32_e32 v70, 16, v73
	v_and_b32_e32 v71, 0xffff0000, v73
	v_lshl_add_u64 v[58:59], v[148:149], 0, s[68:69]
	v_pk_add_f32 v[48:49], v[48:49], v[62:63]
	v_pk_add_f32 v[46:47], v[46:47], v[60:61]
	v_pk_add_f32 v[60:61], v[44:45], v[70:71]
	v_pk_add_f32 v[44:45], v[42:43], v[64:65]
	v_cvt_pk_bf16_f32 v42, v46, v47
	v_cvt_pk_bf16_f32 v43, v48, v49
	s_waitcnt vmcnt(4)
	v_lshlrev_b32_e32 v72, 16, v66
	v_cvt_pk_bf16_f32 v44, v44, v45
	v_cvt_pk_bf16_f32 v45, v60, v61
	global_store_dwordx4 v[58:59], v[42:45], off sc1
	v_lshlrev_b32_e32 v46, 16, v42
	v_lshlrev_b32_e32 v47, 16, v43
	v_and_b32_e32 v42, 0xffff0000, v42
	v_and_b32_e32 v43, 0xffff0000, v43
	v_mul_f32_e32 v42, v42, v42
	v_mul_f32_e32 v43, v43, v43
	v_lshlrev_b32_e32 v48, 16, v44
	v_and_b32_e32 v44, 0xffff0000, v44
	v_lshlrev_b32_e32 v49, 16, v45
	v_and_b32_e32 v45, 0xffff0000, v45
	v_fmac_f32_e32 v42, v46, v46
	v_fmac_f32_e32 v43, v47, v47
	v_add_f32_e32 v42, v42, v43
	v_mul_f32_e32 v43, v44, v44
	v_mul_f32_e32 v44, v45, v45
	v_and_b32_e32 v73, 0xffff0000, v66
	v_lshlrev_b32_e32 v74, 16, v68
	v_and_b32_e32 v75, 0xffff0000, v68
	v_fmac_f32_e32 v43, v48, v48
	v_fmac_f32_e32 v44, v49, v49
	v_lshlrev_b32_e32 v66, 16, v67
	v_and_b32_e32 v67, 0xffff0000, v67
	v_lshlrev_b32_e32 v68, 16, v69
	v_and_b32_e32 v69, 0xffff0000, v69
	v_add_f32_e32 v43, v43, v44
	v_pk_add_f32 v[38:39], v[38:39], v[72:73]
	v_pk_add_f32 v[34:35], v[34:35], v[74:75]
	v_add_f32_e32 v44, v42, v43
	v_pk_add_f32 v[40:41], v[40:41], v[66:67]
	v_pk_add_f32 v[42:43], v[36:37], v[68:69]
	v_cvt_pk_bf16_f32 v36, v38, v39
	v_cvt_pk_bf16_f32 v37, v40, v41
	v_cvt_pk_bf16_f32 v38, v34, v35
	s_mov_b64 s[24:25], 0x90100
	v_and_b32_e32 v35, 0xffff0000, v36
	v_lshlrev_b32_e32 v34, 16, v36
	v_and_b32_e32 v41, 0xffff0000, v37
	v_mul_f32_e32 v35, v35, v35
	v_lshlrev_b32_e32 v40, 16, v37
	v_fmac_f32_e32 v35, v34, v34
	v_mul_f32_e32 v34, v41, v41
	v_cvt_pk_bf16_f32 v39, v42, v43
	v_and_b32_e32 v43, 0xffff0000, v38
	v_and_b32_e32 v46, 0xffff0000, v39
	v_fmac_f32_e32 v34, v40, v40
	v_lshlrev_b32_e32 v42, 16, v38
	v_lshlrev_b32_e32 v45, 16, v39
	v_add_f32_e32 v34, v35, v34
	v_mul_f32_e32 v35, v43, v43
	v_mul_f32_e32 v40, v46, v46
	v_fmac_f32_e32 v35, v42, v42
	v_fmac_f32_e32 v40, v45, v45
	v_add_f32_e32 v35, v35, v40
	v_add_f32_e32 v34, v34, v35
	v_add_f32_e32 v34, v44, v34
	ds_bpermute_b32 v35, v153, v34
	v_lshl_add_u64 v[40:41], v[148:149], 0, s[24:25]
	global_store_dwordx4 v[40:41], v[36:39], off sc1
	s_waitcnt lgkmcnt(0)
	v_add_f32_e32 v34, v34, v35
	ds_bpermute_b32 v35, v124, v34
	s_and_saveexec_b64 s[24:25], s[6:7]
	s_cbranch_execz .LBB0_1039
	s_waitcnt lgkmcnt(0)
	v_add_f32_e32 v36, v34, v35
	v_lshl_add_u64 v[34:35], s[22:23], 2, v[122:123]
	s_lshl_b32 s96, s43, 2
	v_lshl_add_u64 v[34:35], v[34:35], 0, s[96:97]
	v_add_co_u32_e32 v34, vcc, 0x4000, v34
	s_nop 1
	v_addc_co_u32_e32 v35, vcc, 0, v35, vcc
	global_store_dword v[34:35], v36, off offset:2048 sc1
;     __device__ __forceinline__ void operator()(const f32x4 (&acc)[2][2][4][2], const pg8::Unit& u, int wr, int wc, int fr_, int fq_, int tid) {
;     ...
;         const int row0 = u.pm * 256 + wr * 64 + fr, col0 = u.pn * 256 + wc * 32 + 8 * fq;
;         const size_t base = (size_t)row0 * DM + col0;
;         f32x4 cur[4], nxt[4];
;     ...
;         ER_LD(cur, 0);
; #pragma unroll
;         for (int g = 0; g < 8; ++g) {
;             const int ai = g >> 2, m = g & 3;
;             if (g < 7) ER_LD(nxt, g + 1);
;             const size_t off = base + (size_t)(ai * 128 + m * 16) * DM; float s = 0.f;
; #pragma unroll
;             for (int bj = 0; bj < 2; ++bj) {
;                 const f32x4 n0 = cur[2 * bj] + acc[ai][bj][m][0] * alpha, n1 = cur[2 * bj + 1] + acc[ai][bj][m][1] * alpha;
;                 const u32x4 w = pack8bf(n0, n1);
;                 *(u32x4*)(xb + off + bj * 128) = w;
;                 float q[8]; unpack8(w, q);
;                 s += ((q[0] * q[0] + q[1] * q[1]) + (q[2] * q[2] + q[3] * q[3])) + ((q[4] * q[4] + q[5] * q[5]) + (q[6] * q[6] + q[7] * q[7]));
;             }
;             s += __shfl_xor(s, 16); s += __shfl_xor(s, 32);
;             if (fq == 0) ssq[(size_t)(row0 + ai * 128 + m * 16) * 32 + u.pn * 4 + wc] = s;
; #pragma unroll
;             for (int j = 0; j < 4; ++j) cur[j] = nxt[j];
;         }
.LBB0_1039:
	s_or_b64 exec, exec, s[24:25]
	v_add_co_u32_e32 v34, vcc, s60, v148
	s_waitcnt vmcnt(3)
	v_lshlrev_b32_e32 v44, 16, v54
	s_waitcnt lgkmcnt(0)
	v_addc_co_u32_e32 v35, vcc, 0, v149, vcc
	global_load_dwordx4 v[38:41], v[34:35], off
	s_nop 0
	global_load_dwordx4 v[34:37], v[34:35], off offset:256
	v_and_b32_e32 v45, 0xffff0000, v54
	v_lshlrev_b32_e32 v46, 16, v55
	v_and_b32_e32 v47, 0xffff0000, v55
	v_lshlrev_b32_e32 v48, 16, v56
	v_and_b32_e32 v49, 0xffff0000, v56
	v_lshlrev_b32_e32 v54, 16, v57
	v_and_b32_e32 v55, 0xffff0000, v57
	v_lshl_add_u64 v[42:43], v[148:149], 0, s[70:71]
	v_pk_add_f32 v[32:33], v[32:33], v[46:47]
	v_pk_add_f32 v[30:31], v[30:31], v[44:45]
	v_pk_add_f32 v[44:45], v[28:29], v[54:55]
	v_pk_add_f32 v[28:29], v[26:27], v[48:49]
	v_cvt_pk_bf16_f32 v26, v30, v31
	v_cvt_pk_bf16_f32 v27, v32, v33
	s_waitcnt vmcnt(4)
	v_lshlrev_b32_e32 v56, 16, v50
	v_cvt_pk_bf16_f32 v28, v28, v29
	v_cvt_pk_bf16_f32 v29, v44, v45
	global_store_dwordx4 v[42:43], v[26:29], off sc1
	v_lshlrev_b32_e32 v30, 16, v26
	v_lshlrev_b32_e32 v31, 16, v27
	v_and_b32_e32 v26, 0xffff0000, v26
	v_and_b32_e32 v27, 0xffff0000, v27
	v_mul_f32_e32 v26, v26, v26
	v_mul_f32_e32 v27, v27, v27
	v_lshlrev_b32_e32 v32, 16, v28
	v_and_b32_e32 v28, 0xffff0000, v28
	v_lshlrev_b32_e32 v33, 16, v29
	v_and_b32_e32 v29, 0xffff0000, v29
	v_fmac_f32_e32 v26, v30, v30
	v_fmac_f32_e32 v27, v31, v31
	v_add_f32_e32 v26, v26, v27
	v_mul_f32_e32 v27, v28, v28
	v_mul_f32_e32 v28, v29, v29
	v_and_b32_e32 v57, 0xffff0000, v50
	v_lshlrev_b32_e32 v58, 16, v52
	v_and_b32_e32 v59, 0xffff0000, v52
	v_fmac_f32_e32 v27, v32, v32
	v_fmac_f32_e32 v28, v33, v33
	v_lshlrev_b32_e32 v50, 16, v51
	v_and_b32_e32 v51, 0xffff0000, v51
	v_lshlrev_b32_e32 v52, 16, v53
	v_and_b32_e32 v53, 0xffff0000, v53
	v_add_f32_e32 v27, v27, v28
	v_pk_add_f32 v[22:23], v[22:23], v[56:57]
	v_pk_add_f32 v[18:19], v[18:19], v[58:59]
	v_add_f32_e32 v28, v26, v27
	v_pk_add_f32 v[24:25], v[24:25], v[50:51]
	v_pk_add_f32 v[26:27], v[20:21], v[52:53]
	v_cvt_pk_bf16_f32 v20, v22, v23
	v_cvt_pk_bf16_f32 v21, v24, v25
	v_cvt_pk_bf16_f32 v22, v18, v19
	s_mov_b64 s[24:25], 0xa0100
	v_and_b32_e32 v19, 0xffff0000, v20
	v_lshlrev_b32_e32 v18, 16, v20
	v_and_b32_e32 v25, 0xffff0000, v21
	v_mul_f32_e32 v19, v19, v19
	v_lshlrev_b32_e32 v24, 16, v21
	v_fmac_f32_e32 v19, v18, v18
	v_mul_f32_e32 v18, v25, v25
	v_cvt_pk_bf16_f32 v23, v26, v27
	v_and_b32_e32 v27, 0xffff0000, v22
	v_and_b32_e32 v30, 0xffff0000, v23
	v_fmac_f32_e32 v18, v24, v24
	v_lshlrev_b32_e32 v26, 16, v22
	v_lshlrev_b32_e32 v29, 16, v23
	v_add_f32_e32 v18, v19, v18
	v_mul_f32_e32 v19, v27, v27
	v_mul_f32_e32 v24, v30, v30
	v_fmac_f32_e32 v19, v26, v26
	v_fmac_f32_e32 v24, v29, v29
	v_add_f32_e32 v19, v19, v24
	v_add_f32_e32 v18, v18, v19
	v_add_f32_e32 v18, v28, v18
	ds_bpermute_b32 v19, v153, v18
	v_lshl_add_u64 v[24:25], v[148:149], 0, s[24:25]
	global_store_dwordx4 v[24:25], v[20:23], off sc1
	s_waitcnt lgkmcnt(0)
	v_add_f32_e32 v18, v18, v19
	ds_bpermute_b32 v19, v124, v18
	s_and_saveexec_b64 s[24:25], s[6:7]
	s_cbranch_execz .LBB0_1041
	s_waitcnt lgkmcnt(0)
	v_add_f32_e32 v20, v18, v19
	v_lshl_add_u64 v[18:19], s[22:23], 2, v[122:123]
	s_lshl_b32 s96, s43, 2
	v_lshl_add_u64 v[18:19], v[18:19], 0, s[96:97]
	v_add_co_u32_e32 v18, vcc, 0x5000, v18
	s_nop 1
	v_addc_co_u32_e32 v19, vcc, 0, v19, vcc
	global_store_dword v[18:19], v20, off sc1
.LBB0_1041:
	s_or_b64 exec, exec, s[24:25]
	s_waitcnt vmcnt(3)
	v_lshlrev_b32_e32 v20, 16, v38
	v_and_b32_e32 v21, 0xffff0000, v38
	v_lshlrev_b32_e32 v22, 16, v39
	v_and_b32_e32 v23, 0xffff0000, v39
	v_lshlrev_b32_e32 v24, 16, v40
	v_and_b32_e32 v25, 0xffff0000, v40
	v_lshlrev_b32_e32 v26, 16, v41
	v_and_b32_e32 v27, 0xffff0000, v41
	s_waitcnt lgkmcnt(0)
	v_lshl_add_u64 v[18:19], v[148:149], 0, s[72:73]
	v_pk_add_f32 v[16:17], v[16:17], v[22:23]
	v_pk_add_f32 v[14:15], v[14:15], v[20:21]
	v_pk_add_f32 v[20:21], v[12:13], v[26:27]
	v_pk_add_f32 v[12:13], v[10:11], v[24:25]
	v_cvt_pk_bf16_f32 v10, v14, v15
	v_cvt_pk_bf16_f32 v11, v16, v17
	s_waitcnt vmcnt(2)
	v_lshlrev_b32_e32 v28, 16, v34
	v_cvt_pk_bf16_f32 v12, v12, v13
	v_cvt_pk_bf16_f32 v13, v20, v21
	global_store_dwordx4 v[18:19], v[10:13], off sc1
	v_lshlrev_b32_e32 v14, 16, v10
	v_lshlrev_b32_e32 v15, 16, v11
	v_and_b32_e32 v10, 0xffff0000, v10
	v_and_b32_e32 v11, 0xffff0000, v11
	v_mul_f32_e32 v10, v10, v10
	v_mul_f32_e32 v11, v11, v11
	v_lshlrev_b32_e32 v16, 16, v12
	v_and_b32_e32 v12, 0xffff0000, v12
	v_lshlrev_b32_e32 v17, 16, v13
	v_and_b32_e32 v13, 0xffff0000, v13
	v_fmac_f32_e32 v10, v14, v14
	v_fmac_f32_e32 v11, v15, v15
	v_add_f32_e32 v10, v10, v11
	v_mul_f32_e32 v11, v12, v12
	v_mul_f32_e32 v12, v13, v13
	v_and_b32_e32 v29, 0xffff0000, v34
	v_lshlrev_b32_e32 v32, 16, v36
	v_and_b32_e32 v33, 0xffff0000, v36
	v_fmac_f32_e32 v11, v16, v16
	v_fmac_f32_e32 v12, v17, v17
	v_lshlrev_b32_e32 v30, 16, v35
	v_and_b32_e32 v31, 0xffff0000, v35
	v_lshlrev_b32_e32 v34, 16, v37
	v_and_b32_e32 v35, 0xffff0000, v37
	v_add_f32_e32 v11, v11, v12
	v_pk_add_f32 v[6:7], v[6:7], v[28:29]
	v_pk_add_f32 v[2:3], v[2:3], v[32:33]
	v_add_f32_e32 v12, v10, v11
	v_pk_add_f32 v[8:9], v[8:9], v[30:31]
	v_pk_add_f32 v[10:11], v[4:5], v[34:35]
	v_cvt_pk_bf16_f32 v4, v6, v7
	v_cvt_pk_bf16_f32 v5, v8, v9
	v_cvt_pk_bf16_f32 v6, v2, v3
	s_mov_b64 s[24:25], 0xb0100
	v_and_b32_e32 v3, 0xffff0000, v4
	v_lshlrev_b32_e32 v2, 16, v4
	v_and_b32_e32 v9, 0xffff0000, v5
	v_mul_f32_e32 v3, v3, v3
	v_lshlrev_b32_e32 v8, 16, v5
	v_fmac_f32_e32 v3, v2, v2
	v_mul_f32_e32 v2, v9, v9
	v_cvt_pk_bf16_f32 v7, v10, v11
	v_and_b32_e32 v11, 0xffff0000, v6
	v_and_b32_e32 v14, 0xffff0000, v7
	v_fmac_f32_e32 v2, v8, v8
	v_lshlrev_b32_e32 v10, 16, v6
	v_lshlrev_b32_e32 v13, 16, v7
	v_add_f32_e32 v2, v3, v2
	v_mul_f32_e32 v3, v11, v11
	v_mul_f32_e32 v8, v14, v14
	v_fmac_f32_e32 v3, v10, v10
	v_fmac_f32_e32 v8, v13, v13
	v_add_f32_e32 v3, v3, v8
	v_add_f32_e32 v2, v2, v3
	v_add_f32_e32 v2, v12, v2
	ds_bpermute_b32 v3, v153, v2
	v_lshl_add_u64 v[8:9], v[148:149], 0, s[24:25]
	global_store_dwordx4 v[8:9], v[4:7], off sc1
	s_waitcnt lgkmcnt(0)
	v_add_f32_e32 v2, v2, v3
	ds_bpermute_b32 v3, v124, v2
	s_and_saveexec_b64 s[24:25], s[6:7]
	s_cbranch_execz .LBB0_1043
	s_waitcnt lgkmcnt(0)
	v_add_f32_e32 v4, v2, v3
	v_lshl_add_u64 v[2:3], s[22:23], 2, v[122:123]
	s_lshl_b32 s96, s43, 2
	v_lshl_add_u64 v[2:3], v[2:3], 0, s[96:97]
	v_add_co_u32_e32 v2, vcc, 0x5000, v2
	s_nop 1
	v_addc_co_u32_e32 v3, vcc, 0, v3, vcc
	global_store_dword v[2:3], v4, off offset:2048 sc1

;     __device__ __forceinline__ void operator()(const f32x4 (&acc)[2][2][4][2], const pg8::Unit& u, int wr, int wc, int fr_, int fq_, int tid) {
;     ...
;         const int row0 = u.pm * 256 + wr * 64 + fr, col0 = u.pn * 256 + wc * 32 + 8 * fq;
;         const size_t base = (size_t)row0 * DM + col0;
;         f32x4 cur[4], nxt[4];
;     ...
;         ER_LD(cur, 0);
; #pragma unroll
;         for (int g = 0; g < 8; ++g) {
;             const int ai = g >> 2, m = g & 3;
;             if (g < 7) ER_LD(nxt, g + 1);
;             const size_t off = base + (size_t)(ai * 128 + m * 16) * DM; float s = 0.f;
; #pragma unroll
;             for (int bj = 0; bj < 2; ++bj) {
;                 const f32x4 n0 = cur[2 * bj] + acc[ai][bj][m][0] * alpha, n1 = cur[2 * bj + 1] + acc[ai][bj][m][1] * alpha;
;                 const u32x4 w = pack8bf(n0, n1);
;                 *(u32x4*)(xb + off + bj * 128) = w;
;                 float q[8]; unpack8(w, q);
;                 s += ((q[0] * q[0] + q[1] * q[1]) + (q[2] * q[2] + q[3] * q[3])) + ((q[4] * q[4] + q[5] * q[5]) + (q[6] * q[6] + q[7] * q[7]));
;             }
;             s += __shfl_xor(s, 16); s += __shfl_xor(s, 32);
;             if (fq == 0) ssq[(size_t)(row0 + ai * 128 + m * 16) * 32 + u.pn * 4 + wc] = s;
; #pragma unroll
;             for (int j = 0; j < 4; ++j) cur[j] = nxt[j];
;         }
.LBB0_1227:
	s_lshl_b32 s6, s48, 8
	v_mov_b32_e32 v130, v1
	v_mov_b32_e32 v173, v150
	s_add_i32 s6, s6, s38
	v_cmp_lt_i32_e32 vcc, v203, v198
	v_add_u32_e32 v174, s6, v130
	s_lshl_b32 s6, s47, 8
	s_or_b32 s6, s6, s39
	v_ashrrev_i32_e32 v175, 31, v174
	v_lshl_add_u32 v130, v173, 3, s6
	v_lshlrev_b64 v[132:133], 12, v[174:175]
	v_ashrrev_i32_e32 v131, 31, v130
	v_lshl_add_u64 v[132:133], s[8:9], 0, v[132:133]
	v_lshl_add_u64 v[148:149], v[130:131], 1, v[132:133]
	global_load_dwordx4 v[154:157], v[148:149], off
	global_load_dwordx4 v[158:161], v[148:149], off offset:256
	v_cndmask_b32_e32 v130, v195, v203, vcc
	v_lshlrev_b32_e32 v153, 2, v130
	v_add_co_u32_e32 v130, vcc, s86, v148
	s_lshl_b32 s18, s47, 2
	s_nop 0
	v_addc_co_u32_e32 v131, vcc, 0, v149, vcc
	global_load_dwordx4 v[134:137], v[130:131], off
	s_nop 0
	global_load_dwordx4 v[130:133], v[130:131], off offset:256
	v_cmp_lt_i32_e32 vcc, v204, v198
	v_cmp_eq_u32_e64 s[6:7], 0, v173
	s_ashr_i32 s19, s18, 31
	s_waitcnt vmcnt(0)
	v_lshlrev_b32_e32 v176, 16, v154
	v_and_b32_e32 v177, 0xffff0000, v154
	v_lshlrev_b32_e32 v154, 16, v155
	v_and_b32_e32 v155, 0xffff0000, v155
	v_lshlrev_b32_e32 v178, 16, v156
	v_and_b32_e32 v179, 0xffff0000, v156
	v_lshlrev_b32_e32 v156, 16, v157
	v_and_b32_e32 v157, 0xffff0000, v157
	v_lshlrev_b32_e32 v182, 16, v160
	v_and_b32_e32 v183, 0xffff0000, v160
	v_lshlrev_b32_e32 v180, 16, v158
	v_and_b32_e32 v181, 0xffff0000, v158
	v_lshlrev_b32_e32 v158, 16, v159
	v_and_b32_e32 v159, 0xffff0000, v159
	v_lshlrev_b32_e32 v160, 16, v161
	v_and_b32_e32 v161, 0xffff0000, v161
	v_pk_fma_f32 v[128:129], v[128:129], 0.5, v[154:155] op_sel_hi:[1,0,1]
	v_pk_fma_f32 v[126:127], v[126:127], 0.5, v[176:177] op_sel_hi:[1,0,1]
	v_pk_fma_f32 v[124:125], v[124:125], 0.5, v[156:157] op_sel_hi:[1,0,1]
	v_pk_fma_f32 v[122:123], v[122:123], 0.5, v[178:179] op_sel_hi:[1,0,1]
	v_pk_fma_f32 v[156:157], v[114:115], 0.5, v[182:183] op_sel_hi:[1,0,1]
	v_cvt_pk_bf16_f32 v114, v126, v127
	v_cvt_pk_bf16_f32 v115, v128, v129
	v_pk_fma_f32 v[120:121], v[120:121], 0.5, v[158:159] op_sel_hi:[1,0,1]
	v_pk_fma_f32 v[118:119], v[118:119], 0.5, v[180:181] op_sel_hi:[1,0,1]
	v_pk_fma_f32 v[154:155], v[116:117], 0.5, v[160:161] op_sel_hi:[1,0,1]
	v_cvt_pk_bf16_f32 v116, v122, v123
	v_cvt_pk_bf16_f32 v117, v124, v125
	global_store_dwordx4 v[148:149], v[114:117], off sc1
	v_lshlrev_b32_e32 v122, 16, v114
	v_lshlrev_b32_e32 v123, 16, v115
	v_and_b32_e32 v114, 0xffff0000, v114
	v_and_b32_e32 v115, 0xffff0000, v115
	v_and_b32_e32 v125, 0xffff0000, v116
	v_and_b32_e32 v127, 0xffff0000, v117
	v_lshlrev_b32_e32 v124, 16, v116
	v_lshlrev_b32_e32 v126, 16, v117
	v_cvt_pk_bf16_f32 v116, v118, v119
	v_cvt_pk_bf16_f32 v117, v120, v121
	v_cvt_pk_bf16_f32 v118, v156, v157
	v_cvt_pk_bf16_f32 v119, v154, v155
	v_mul_f32_e32 v114, v114, v114
	v_mul_f32_e32 v115, v115, v115
	v_mul_f32_e32 v120, v125, v125
	v_mul_f32_e32 v121, v127, v127
	v_and_b32_e32 v127, 0xffff0000, v116
	v_and_b32_e32 v129, 0xffff0000, v117
	v_and_b32_e32 v155, 0xffff0000, v118
	v_and_b32_e32 v157, 0xffff0000, v119
	v_lshlrev_b32_e32 v125, 16, v116
	v_lshlrev_b32_e32 v128, 16, v117
	v_lshlrev_b32_e32 v154, 16, v118
	v_lshlrev_b32_e32 v156, 16, v119
	v_fmac_f32_e32 v114, v122, v122
	v_fmac_f32_e32 v115, v123, v123
	v_fmac_f32_e32 v120, v124, v124
	v_fmac_f32_e32 v121, v126, v126
	v_mul_f32_e32 v122, v127, v127
	v_mul_f32_e32 v123, v129, v129
	v_mul_f32_e32 v124, v155, v155
	v_mul_f32_e32 v126, v157, v157
	v_add_f32_e32 v114, v114, v115
	v_add_f32_e32 v115, v120, v121
	v_fmac_f32_e32 v122, v125, v125
	v_fmac_f32_e32 v123, v128, v128
	v_fmac_f32_e32 v124, v154, v154
	v_fmac_f32_e32 v126, v156, v156
	v_add_f32_e32 v114, v114, v115
	v_add_f32_e32 v115, v122, v123
	v_add_f32_e32 v120, v124, v126
	v_add_f32_e32 v115, v115, v120
	v_add_f32_e32 v114, v114, v115
	ds_bpermute_b32 v115, v153, v114
	v_cndmask_b32_e32 v120, v195, v204, vcc
	v_lshlrev_b32_e32 v124, 2, v120
	global_store_dwordx4 v[148:149], v[116:119], off offset:256 sc1
	s_waitcnt lgkmcnt(0)
	v_add_f32_e32 v114, v114, v115
	ds_bpermute_b32 v115, v124, v114
	v_lshlrev_b64 v[116:117], 7, v[174:175]
	v_lshl_add_u64 v[122:123], s[10:11], 0, v[116:117]
	s_and_saveexec_b64 s[20:21], s[6:7]
	s_cbranch_execz .LBB0_1229
	v_lshl_add_u64 v[116:117], s[18:19], 2, v[122:123]
	s_lshl_b32 s96, s37, 2
	v_lshl_add_u64 v[116:117], v[116:117], 0, s[96:97]
	s_waitcnt lgkmcnt(0)
	v_add_f32_e32 v114, v114, v115
	global_store_dword v[116:117], v114, off sc1
;     __device__ __forceinline__ void operator()(const f32x4 (&acc)[2][2][4][2], const pg8::Unit& u, int wr, int wc, int fr_, int fq_, int tid) {
;     ...
;         const int row0 = u.pm * 256 + wr * 64 + fr, col0 = u.pn * 256 + wc * 32 + 8 * fq;
;         const size_t base = (size_t)row0 * DM + col0;
;         f32x4 cur[4], nxt[4];
;     ...
;         ER_LD(cur, 0);
; #pragma unroll
;         for (int g = 0; g < 8; ++g) {
;             const int ai = g >> 2, m = g & 3;
;             if (g < 7) ER_LD(nxt, g + 1);
;             const size_t off = base + (size_t)(ai * 128 + m * 16) * DM; float s = 0.f;
; #pragma unroll
;             for (int bj = 0; bj < 2; ++bj) {
;                 const f32x4 n0 = cur[2 * bj] + acc[ai][bj][m][0] * alpha, n1 = cur[2 * bj + 1] + acc[ai][bj][m][1] * alpha;
;                 const u32x4 w = pack8bf(n0, n1);
;                 *(u32x4*)(xb + off + bj * 128) = w;
;                 float q[8]; unpack8(w, q);
;                 s += ((q[0] * q[0] + q[1] * q[1]) + (q[2] * q[2] + q[3] * q[3])) + ((q[4] * q[4] + q[5] * q[5]) + (q[6] * q[6] + q[7] * q[7]));
;             }
;             s += __shfl_xor(s, 16); s += __shfl_xor(s, 32);
;             if (fq == 0) ssq[(size_t)(row0 + ai * 128 + m * 16) * 32 + u.pn * 4 + wc] = s;
; #pragma unroll
;             for (int j = 0; j < 4; ++j) cur[j] = nxt[j];
;         }
.LBB0_1229:
	s_or_b64 exec, exec, s[20:21]
	v_add_co_u32_e32 v114, vcc, s89, v148
	s_mov_b64 s[20:21], 0x10000
	s_waitcnt lgkmcnt(0)
	v_addc_co_u32_e32 v115, vcc, 0, v149, vcc
	global_load_dwordx4 v[118:121], v[114:115], off
	s_nop 0
	global_load_dwordx4 v[114:117], v[114:115], off offset:256
	v_lshlrev_b32_e32 v128, 16, v134
	v_and_b32_e32 v129, 0xffff0000, v134
	v_lshlrev_b32_e32 v134, 16, v135
	v_and_b32_e32 v135, 0xffff0000, v135
	v_lshlrev_b32_e32 v154, 16, v136
	v_and_b32_e32 v155, 0xffff0000, v136
	v_lshlrev_b32_e32 v136, 16, v137
	v_and_b32_e32 v137, 0xffff0000, v137
	v_lshl_add_u64 v[126:127], v[148:149], 0, s[20:21]
	v_pk_fma_f32 v[112:113], v[112:113], 0.5, v[134:135] op_sel_hi:[1,0,1]
	v_pk_fma_f32 v[110:111], v[110:111], 0.5, v[128:129] op_sel_hi:[1,0,1]
	v_pk_fma_f32 v[128:129], v[108:109], 0.5, v[136:137] op_sel_hi:[1,0,1]
	v_pk_fma_f32 v[108:109], v[106:107], 0.5, v[154:155] op_sel_hi:[1,0,1]
	v_cvt_pk_bf16_f32 v106, v110, v111
	v_cvt_pk_bf16_f32 v107, v112, v113
	v_lshlrev_b32_e32 v156, 16, v130
	v_cvt_pk_bf16_f32 v108, v108, v109
	v_cvt_pk_bf16_f32 v109, v128, v129
	global_store_dwordx4 v[126:127], v[106:109], off sc1
	v_lshlrev_b32_e32 v110, 16, v106
	v_lshlrev_b32_e32 v111, 16, v107
	v_and_b32_e32 v106, 0xffff0000, v106
	v_and_b32_e32 v107, 0xffff0000, v107
	v_mul_f32_e32 v106, v106, v106
	v_mul_f32_e32 v107, v107, v107
	v_lshlrev_b32_e32 v112, 16, v108
	v_and_b32_e32 v108, 0xffff0000, v108
	v_lshlrev_b32_e32 v113, 16, v109
	v_and_b32_e32 v109, 0xffff0000, v109
	v_fmac_f32_e32 v106, v110, v110
	v_fmac_f32_e32 v107, v111, v111
	v_add_f32_e32 v106, v106, v107
	v_mul_f32_e32 v107, v108, v108
	v_mul_f32_e32 v108, v109, v109
	v_and_b32_e32 v157, 0xffff0000, v130
	v_lshlrev_b32_e32 v158, 16, v132
	v_and_b32_e32 v159, 0xffff0000, v132
	v_fmac_f32_e32 v107, v112, v112
	v_fmac_f32_e32 v108, v113, v113
	v_lshlrev_b32_e32 v130, 16, v131
	v_and_b32_e32 v131, 0xffff0000, v131
	v_lshlrev_b32_e32 v132, 16, v133
	v_and_b32_e32 v133, 0xffff0000, v133
	v_add_f32_e32 v107, v107, v108
	v_pk_fma_f32 v[102:103], v[102:103], 0.5, v[156:157] op_sel_hi:[1,0,1]
	v_pk_fma_f32 v[98:99], v[98:99], 0.5, v[158:159] op_sel_hi:[1,0,1]
	v_add_f32_e32 v108, v106, v107
	v_pk_fma_f32 v[104:105], v[104:105], 0.5, v[130:131] op_sel_hi:[1,0,1]
	v_pk_fma_f32 v[106:107], v[100:101], 0.5, v[132:133] op_sel_hi:[1,0,1]
	v_cvt_pk_bf16_f32 v100, v102, v103
	v_cvt_pk_bf16_f32 v101, v104, v105
	v_cvt_pk_bf16_f32 v102, v98, v99
	s_mov_b64 s[20:21], 0x10100
	v_and_b32_e32 v99, 0xffff0000, v100
	v_lshlrev_b32_e32 v98, 16, v100
	v_and_b32_e32 v105, 0xffff0000, v101
	v_mul_f32_e32 v99, v99, v99
	v_lshlrev_b32_e32 v104, 16, v101
	v_fmac_f32_e32 v99, v98, v98
	v_mul_f32_e32 v98, v105, v105
	v_cvt_pk_bf16_f32 v103, v106, v107
	v_and_b32_e32 v107, 0xffff0000, v102
	v_and_b32_e32 v110, 0xffff0000, v103
	v_fmac_f32_e32 v98, v104, v104
	v_lshlrev_b32_e32 v106, 16, v102
	v_lshlrev_b32_e32 v109, 16, v103
	v_add_f32_e32 v98, v99, v98
	v_mul_f32_e32 v99, v107, v107
	v_mul_f32_e32 v104, v110, v110
	v_fmac_f32_e32 v99, v106, v106
	v_fmac_f32_e32 v104, v109, v109
	v_add_f32_e32 v99, v99, v104
	v_add_f32_e32 v98, v98, v99
	v_add_f32_e32 v98, v108, v98
	ds_bpermute_b32 v99, v153, v98
	v_lshl_add_u64 v[104:105], v[148:149], 0, s[20:21]
	global_store_dwordx4 v[104:105], v[100:103], off sc1
	s_waitcnt lgkmcnt(0)
	v_add_f32_e32 v98, v98, v99
	ds_bpermute_b32 v99, v124, v98
	s_and_saveexec_b64 s[20:21], s[6:7]
	s_cbranch_execz .LBB0_1231
	s_waitcnt lgkmcnt(0)
	v_add_f32_e32 v100, v98, v99
	v_lshl_add_u64 v[98:99], s[18:19], 2, v[122:123]
	s_lshl_b32 s96, s37, 2
	v_lshl_add_u64 v[98:99], v[98:99], 0, s[96:97]
	global_store_dword v[98:99], v100, off offset:2048 sc1
.LBB0_1231:
	s_or_b64 exec, exec, s[20:21]
	v_add_co_u32_e32 v98, vcc, s90, v148
	s_waitcnt vmcnt(3)
	v_lshlrev_b32_e32 v108, 16, v118
	s_waitcnt lgkmcnt(0)
	v_addc_co_u32_e32 v99, vcc, 0, v149, vcc
	global_load_dwordx4 v[102:105], v[98:99], off
	s_nop 0
	global_load_dwordx4 v[98:101], v[98:99], off offset:256
	v_and_b32_e32 v109, 0xffff0000, v118
	v_lshlrev_b32_e32 v110, 16, v119
	v_and_b32_e32 v111, 0xffff0000, v119
	v_lshlrev_b32_e32 v112, 16, v120
	v_and_b32_e32 v113, 0xffff0000, v120
	v_lshlrev_b32_e32 v118, 16, v121
	v_and_b32_e32 v119, 0xffff0000, v121
	v_lshl_add_u64 v[106:107], v[148:149], 0, s[64:65]
	v_pk_fma_f32 v[96:97], v[96:97], 0.5, v[110:111] op_sel_hi:[1,0,1]
	v_pk_fma_f32 v[94:95], v[94:95], 0.5, v[108:109] op_sel_hi:[1,0,1]
	v_pk_fma_f32 v[108:109], v[92:93], 0.5, v[118:119] op_sel_hi:[1,0,1]
	v_pk_fma_f32 v[92:93], v[90:91], 0.5, v[112:113] op_sel_hi:[1,0,1]
	v_cvt_pk_bf16_f32 v90, v94, v95
	v_cvt_pk_bf16_f32 v91, v96, v97
	s_waitcnt vmcnt(4)
	v_lshlrev_b32_e32 v120, 16, v114
	v_cvt_pk_bf16_f32 v92, v92, v93
	v_cvt_pk_bf16_f32 v93, v108, v109
	global_store_dwordx4 v[106:107], v[90:93], off sc1
	v_lshlrev_b32_e32 v94, 16, v90
	v_lshlrev_b32_e32 v95, 16, v91
	v_and_b32_e32 v90, 0xffff0000, v90
	v_and_b32_e32 v91, 0xffff0000, v91
	v_mul_f32_e32 v90, v90, v90
	v_mul_f32_e32 v91, v91, v91
	v_lshlrev_b32_e32 v96, 16, v92
	v_and_b32_e32 v92, 0xffff0000, v92
	v_lshlrev_b32_e32 v97, 16, v93
	v_and_b32_e32 v93, 0xffff0000, v93
	v_fmac_f32_e32 v90, v94, v94
	v_fmac_f32_e32 v91, v95, v95
	v_add_f32_e32 v90, v90, v91
	v_mul_f32_e32 v91, v92, v92
	v_mul_f32_e32 v92, v93, v93
	v_and_b32_e32 v121, 0xffff0000, v114
	v_lshlrev_b32_e32 v126, 16, v116
	v_and_b32_e32 v127, 0xffff0000, v116
	v_fmac_f32_e32 v91, v96, v96
	v_fmac_f32_e32 v92, v97, v97
	v_lshlrev_b32_e32 v114, 16, v115
	v_and_b32_e32 v115, 0xffff0000, v115
	v_lshlrev_b32_e32 v116, 16, v117
	v_and_b32_e32 v117, 0xffff0000, v117
	v_add_f32_e32 v91, v91, v92
	v_pk_fma_f32 v[86:87], v[86:87], 0.5, v[120:121] op_sel_hi:[1,0,1]
	v_pk_fma_f32 v[82:83], v[82:83], 0.5, v[126:127] op_sel_hi:[1,0,1]
	v_add_f32_e32 v92, v90, v91
	v_pk_fma_f32 v[88:89], v[88:89], 0.5, v[114:115] op_sel_hi:[1,0,1]
	v_pk_fma_f32 v[90:91], v[84:85], 0.5, v[116:117] op_sel_hi:[1,0,1]
	v_cvt_pk_bf16_f32 v84, v86, v87
	v_cvt_pk_bf16_f32 v85, v88, v89
	v_cvt_pk_bf16_f32 v86, v82, v83
	s_mov_b64 s[20:21], 0x20100
	v_and_b32_e32 v83, 0xffff0000, v84
	v_lshlrev_b32_e32 v82, 16, v84
	v_and_b32_e32 v89, 0xffff0000, v85
	v_mul_f32_e32 v83, v83, v83
	v_lshlrev_b32_e32 v88, 16, v85
	v_fmac_f32_e32 v83, v82, v82
	v_mul_f32_e32 v82, v89, v89
	v_cvt_pk_bf16_f32 v87, v90, v91
	v_and_b32_e32 v91, 0xffff0000, v86
	v_and_b32_e32 v94, 0xffff0000, v87
	v_fmac_f32_e32 v82, v88, v88
	v_lshlrev_b32_e32 v90, 16, v86
	v_lshlrev_b32_e32 v93, 16, v87
	v_add_f32_e32 v82, v83, v82
	v_mul_f32_e32 v83, v91, v91
	v_mul_f32_e32 v88, v94, v94
	v_fmac_f32_e32 v83, v90, v90
	v_fmac_f32_e32 v88, v93, v93
	v_add_f32_e32 v83, v83, v88
	v_add_f32_e32 v82, v82, v83
	v_add_f32_e32 v82, v92, v82
	ds_bpermute_b32 v83, v153, v82
	v_lshl_add_u64 v[88:89], v[148:149], 0, s[20:21]
	global_store_dwordx4 v[88:89], v[84:87], off sc1
	s_waitcnt lgkmcnt(0)
	v_add_f32_e32 v82, v82, v83
	ds_bpermute_b32 v83, v124, v82
	s_and_saveexec_b64 s[20:21], s[6:7]
	s_cbranch_execz .LBB0_1233
;     __device__ __forceinline__ void operator()(const f32x4 (&acc)[2][2][4][2], const pg8::Unit& u, int wr, int wc, int fr_, int fq_, int tid) {
;     ...
;         const int row0 = u.pm * 256 + wr * 64 + fr, col0 = u.pn * 256 + wc * 32 + 8 * fq;
;         const size_t base = (size_t)row0 * DM + col0;
;         f32x4 cur[4], nxt[4];
;     ...
;         ER_LD(cur, 0);
; #pragma unroll
;         for (int g = 0; g < 8; ++g) {
;             const int ai = g >> 2, m = g & 3;
;             if (g < 7) ER_LD(nxt, g + 1);
;             const size_t off = base + (size_t)(ai * 128 + m * 16) * DM; float s = 0.f;
; #pragma unroll
;             for (int bj = 0; bj < 2; ++bj) {
;                 const f32x4 n0 = cur[2 * bj] + acc[ai][bj][m][0] * alpha, n1 = cur[2 * bj + 1] + acc[ai][bj][m][1] * alpha;
;                 const u32x4 w = pack8bf(n0, n1);
;                 *(u32x4*)(xb + off + bj * 128) = w;
;                 float q[8]; unpack8(w, q);
;                 s += ((q[0] * q[0] + q[1] * q[1]) + (q[2] * q[2] + q[3] * q[3])) + ((q[4] * q[4] + q[5] * q[5]) + (q[6] * q[6] + q[7] * q[7]));
;             }
;             s += __shfl_xor(s, 16); s += __shfl_xor(s, 32);
;             if (fq == 0) ssq[(size_t)(row0 + ai * 128 + m * 16) * 32 + u.pn * 4 + wc] = s;
; #pragma unroll
;             for (int j = 0; j < 4; ++j) cur[j] = nxt[j];
;         }
	s_waitcnt lgkmcnt(0)
	v_add_f32_e32 v84, v82, v83
	v_lshl_add_u64 v[82:83], s[18:19], 2, v[122:123]
	s_lshl_b32 s96, s37, 2
	v_lshl_add_u64 v[82:83], v[82:83], 0, s[96:97]
	v_add_co_u32_e32 v82, vcc, 0x1000, v82
	s_nop 1
	v_addc_co_u32_e32 v83, vcc, 0, v83, vcc
	global_store_dword v[82:83], v84, off sc1
.LBB0_1233:
	s_or_b64 exec, exec, s[20:21]
	v_add_co_u32_e32 v82, vcc, s91, v148
	s_waitcnt vmcnt(3)
	v_lshlrev_b32_e32 v92, 16, v102
	s_waitcnt lgkmcnt(0)
	v_addc_co_u32_e32 v83, vcc, 0, v149, vcc
	global_load_dwordx4 v[86:89], v[82:83], off
	s_nop 0
	global_load_dwordx4 v[82:85], v[82:83], off offset:256
	v_and_b32_e32 v93, 0xffff0000, v102
	v_lshlrev_b32_e32 v94, 16, v103
	v_and_b32_e32 v95, 0xffff0000, v103
	v_lshlrev_b32_e32 v96, 16, v104
	v_and_b32_e32 v97, 0xffff0000, v104
	v_lshlrev_b32_e32 v102, 16, v105
	v_and_b32_e32 v103, 0xffff0000, v105
	v_lshl_add_u64 v[90:91], v[148:149], 0, s[66:67]
	v_pk_fma_f32 v[80:81], v[80:81], 0.5, v[94:95] op_sel_hi:[1,0,1]
	v_pk_fma_f32 v[78:79], v[78:79], 0.5, v[92:93] op_sel_hi:[1,0,1]
	v_pk_fma_f32 v[92:93], v[76:77], 0.5, v[102:103] op_sel_hi:[1,0,1]
	v_pk_fma_f32 v[76:77], v[74:75], 0.5, v[96:97] op_sel_hi:[1,0,1]
	v_cvt_pk_bf16_f32 v74, v78, v79
	v_cvt_pk_bf16_f32 v75, v80, v81
	s_waitcnt vmcnt(4)
	v_lshlrev_b32_e32 v104, 16, v98
	v_cvt_pk_bf16_f32 v76, v76, v77
	v_cvt_pk_bf16_f32 v77, v92, v93
	global_store_dwordx4 v[90:91], v[74:77], off sc1
	v_lshlrev_b32_e32 v78, 16, v74
	v_lshlrev_b32_e32 v79, 16, v75
	v_and_b32_e32 v74, 0xffff0000, v74
	v_and_b32_e32 v75, 0xffff0000, v75
	v_mul_f32_e32 v74, v74, v74
	v_mul_f32_e32 v75, v75, v75
	v_lshlrev_b32_e32 v80, 16, v76
	v_and_b32_e32 v76, 0xffff0000, v76
	v_lshlrev_b32_e32 v81, 16, v77
	v_and_b32_e32 v77, 0xffff0000, v77
	v_fmac_f32_e32 v74, v78, v78
	v_fmac_f32_e32 v75, v79, v79
	v_add_f32_e32 v74, v74, v75
	v_mul_f32_e32 v75, v76, v76
	v_mul_f32_e32 v76, v77, v77
	v_and_b32_e32 v105, 0xffff0000, v98
	v_lshlrev_b32_e32 v106, 16, v100
	v_and_b32_e32 v107, 0xffff0000, v100
	v_fmac_f32_e32 v75, v80, v80
	v_fmac_f32_e32 v76, v81, v81
	v_lshlrev_b32_e32 v98, 16, v99
	v_and_b32_e32 v99, 0xffff0000, v99
	v_lshlrev_b32_e32 v100, 16, v101
	v_and_b32_e32 v101, 0xffff0000, v101
	v_add_f32_e32 v75, v75, v76
	v_pk_fma_f32 v[70:71], v[70:71], 0.5, v[104:105] op_sel_hi:[1,0,1]
	v_pk_fma_f32 v[66:67], v[66:67], 0.5, v[106:107] op_sel_hi:[1,0,1]
	v_add_f32_e32 v76, v74, v75
	v_pk_fma_f32 v[72:73], v[72:73], 0.5, v[98:99] op_sel_hi:[1,0,1]
	v_pk_fma_f32 v[74:75], v[68:69], 0.5, v[100:101] op_sel_hi:[1,0,1]
	v_cvt_pk_bf16_f32 v68, v70, v71
	v_cvt_pk_bf16_f32 v69, v72, v73
	v_cvt_pk_bf16_f32 v70, v66, v67
	s_mov_b64 s[20:21], 0x30100
	v_and_b32_e32 v67, 0xffff0000, v68
	v_lshlrev_b32_e32 v66, 16, v68
	v_and_b32_e32 v73, 0xffff0000, v69
	v_mul_f32_e32 v67, v67, v67
	v_lshlrev_b32_e32 v72, 16, v69
	v_fmac_f32_e32 v67, v66, v66
	v_mul_f32_e32 v66, v73, v73
	v_cvt_pk_bf16_f32 v71, v74, v75
	v_and_b32_e32 v75, 0xffff0000, v70
	v_and_b32_e32 v78, 0xffff0000, v71
	v_fmac_f32_e32 v66, v72, v72
	v_lshlrev_b32_e32 v74, 16, v70
	v_lshlrev_b32_e32 v77, 16, v71
	v_add_f32_e32 v66, v67, v66
	v_mul_f32_e32 v67, v75, v75
	v_mul_f32_e32 v72, v78, v78
	v_fmac_f32_e32 v67, v74, v74
	v_fmac_f32_e32 v72, v77, v77
	v_add_f32_e32 v67, v67, v72
	v_add_f32_e32 v66, v66, v67
	v_add_f32_e32 v66, v76, v66
	ds_bpermute_b32 v67, v153, v66
	v_lshl_add_u64 v[72:73], v[148:149], 0, s[20:21]
	global_store_dwordx4 v[72:73], v[68:71], off sc1
	s_waitcnt lgkmcnt(0)
	v_add_f32_e32 v66, v66, v67
	ds_bpermute_b32 v67, v124, v66
	s_and_saveexec_b64 s[20:21], s[6:7]
	s_cbranch_execz .LBB0_1235
	s_waitcnt lgkmcnt(0)
	v_add_f32_e32 v68, v66, v67
	v_lshl_add_u64 v[66:67], s[18:19], 2, v[122:123]
	s_lshl_b32 s96, s37, 2
	v_lshl_add_u64 v[66:67], v[66:67], 0, s[96:97]
	v_add_co_u32_e32 v66, vcc, 0x1000, v66
	s_nop 1
	v_addc_co_u32_e32 v67, vcc, 0, v67, vcc
	global_store_dword v[66:67], v68, off offset:2048 sc1
.LBB0_1235:
	s_or_b64 exec, exec, s[20:21]
	v_add_co_u32_e32 v66, vcc, s92, v148
	s_waitcnt vmcnt(3)
	v_lshlrev_b32_e32 v76, 16, v86
	s_waitcnt lgkmcnt(0)
	v_addc_co_u32_e32 v67, vcc, 0, v149, vcc
	global_load_dwordx4 v[70:73], v[66:67], off
	s_nop 0
	global_load_dwordx4 v[66:69], v[66:67], off offset:256
	v_and_b32_e32 v77, 0xffff0000, v86
	v_lshlrev_b32_e32 v78, 16, v87
	v_and_b32_e32 v79, 0xffff0000, v87
	v_lshlrev_b32_e32 v80, 16, v88
	v_and_b32_e32 v81, 0xffff0000, v88
	v_lshlrev_b32_e32 v86, 16, v89
	v_and_b32_e32 v87, 0xffff0000, v89
	v_lshl_add_u64 v[74:75], v[148:149], 0, s[94:95]
	v_pk_fma_f32 v[64:65], v[64:65], 0.5, v[78:79] op_sel_hi:[1,0,1]
	v_pk_fma_f32 v[62:63], v[62:63], 0.5, v[76:77] op_sel_hi:[1,0,1]
	v_pk_fma_f32 v[76:77], v[60:61], 0.5, v[86:87] op_sel_hi:[1,0,1]
	v_pk_fma_f32 v[60:61], v[58:59], 0.5, v[80:81] op_sel_hi:[1,0,1]
	v_cvt_pk_bf16_f32 v58, v62, v63
	v_cvt_pk_bf16_f32 v59, v64, v65
	s_waitcnt vmcnt(4)
;     __device__ __forceinline__ void operator()(const f32x4 (&acc)[2][2][4][2], const pg8::Unit& u, int wr, int wc, int fr_, int fq_, int tid) {
;     ...
;         const int row0 = u.pm * 256 + wr * 64 + fr, col0 = u.pn * 256 + wc * 32 + 8 * fq;
;         const size_t base = (size_t)row0 * DM + col0;
;         f32x4 cur[4], nxt[4];
;     ...
;         ER_LD(cur, 0);
; #pragma unroll
;         for (int g = 0; g < 8; ++g) {
;             const int ai = g >> 2, m = g & 3;
;             if (g < 7) ER_LD(nxt, g + 1);
;             const size_t off = base + (size_t)(ai * 128 + m * 16) * DM; float s = 0.f;
; #pragma unroll
;             for (int bj = 0; bj < 2; ++bj) {
;                 const f32x4 n0 = cur[2 * bj] + acc[ai][bj][m][0] * alpha, n1 = cur[2 * bj + 1] + acc[ai][bj][m][1] * alpha;
;                 const u32x4 w = pack8bf(n0, n1);
;                 *(u32x4*)(xb + off + bj * 128) = w;
;                 float q[8]; unpack8(w, q);
;                 s += ((q[0] * q[0] + q[1] * q[1]) + (q[2] * q[2] + q[3] * q[3])) + ((q[4] * q[4] + q[5] * q[5]) + (q[6] * q[6] + q[7] * q[7]));
;             }
;             s += __shfl_xor(s, 16); s += __shfl_xor(s, 32);
;             if (fq == 0) ssq[(size_t)(row0 + ai * 128 + m * 16) * 32 + u.pn * 4 + wc] = s;
; #pragma unroll
;             for (int j = 0; j < 4; ++j) cur[j] = nxt[j];
;         }
	v_lshlrev_b32_e32 v88, 16, v82
	v_cvt_pk_bf16_f32 v60, v60, v61
	v_cvt_pk_bf16_f32 v61, v76, v77
	global_store_dwordx4 v[74:75], v[58:61], off sc1
	v_lshlrev_b32_e32 v62, 16, v58
	v_lshlrev_b32_e32 v63, 16, v59
	v_and_b32_e32 v58, 0xffff0000, v58
	v_and_b32_e32 v59, 0xffff0000, v59
	v_mul_f32_e32 v58, v58, v58
	v_mul_f32_e32 v59, v59, v59
	v_lshlrev_b32_e32 v64, 16, v60
	v_and_b32_e32 v60, 0xffff0000, v60
	v_lshlrev_b32_e32 v65, 16, v61
	v_and_b32_e32 v61, 0xffff0000, v61
	v_fmac_f32_e32 v58, v62, v62
	v_fmac_f32_e32 v59, v63, v63
	v_add_f32_e32 v58, v58, v59
	v_mul_f32_e32 v59, v60, v60
	v_mul_f32_e32 v60, v61, v61
	v_and_b32_e32 v89, 0xffff0000, v82
	v_lshlrev_b32_e32 v90, 16, v84
	v_and_b32_e32 v91, 0xffff0000, v84
	v_fmac_f32_e32 v59, v64, v64
	v_fmac_f32_e32 v60, v65, v65
	v_lshlrev_b32_e32 v82, 16, v83
	v_and_b32_e32 v83, 0xffff0000, v83
	v_lshlrev_b32_e32 v84, 16, v85
	v_and_b32_e32 v85, 0xffff0000, v85
	v_add_f32_e32 v59, v59, v60
	v_pk_fma_f32 v[54:55], v[54:55], 0.5, v[88:89] op_sel_hi:[1,0,1]
	v_pk_fma_f32 v[50:51], v[50:51], 0.5, v[90:91] op_sel_hi:[1,0,1]
	v_add_f32_e32 v60, v58, v59
	v_pk_fma_f32 v[56:57], v[56:57], 0.5, v[82:83] op_sel_hi:[1,0,1]
	v_pk_fma_f32 v[58:59], v[52:53], 0.5, v[84:85] op_sel_hi:[1,0,1]
	v_cvt_pk_bf16_f32 v52, v54, v55
	v_cvt_pk_bf16_f32 v53, v56, v57
	v_cvt_pk_bf16_f32 v54, v50, v51
	s_mov_b64 s[20:21], 0x80100
	v_and_b32_e32 v51, 0xffff0000, v52
	v_lshlrev_b32_e32 v50, 16, v52
	v_and_b32_e32 v57, 0xffff0000, v53
	v_mul_f32_e32 v51, v51, v51
	v_lshlrev_b32_e32 v56, 16, v53
	v_fmac_f32_e32 v51, v50, v50
	v_mul_f32_e32 v50, v57, v57
	v_cvt_pk_bf16_f32 v55, v58, v59
	v_and_b32_e32 v59, 0xffff0000, v54
	v_and_b32_e32 v62, 0xffff0000, v55
	v_fmac_f32_e32 v50, v56, v56
	v_lshlrev_b32_e32 v58, 16, v54
	v_lshlrev_b32_e32 v61, 16, v55
	v_add_f32_e32 v50, v51, v50
	v_mul_f32_e32 v51, v59, v59
	v_mul_f32_e32 v56, v62, v62
	v_fmac_f32_e32 v51, v58, v58
	v_fmac_f32_e32 v56, v61, v61
	v_add_f32_e32 v51, v51, v56
	v_add_f32_e32 v50, v50, v51
	v_add_f32_e32 v50, v60, v50
	ds_bpermute_b32 v51, v153, v50
	v_lshl_add_u64 v[56:57], v[148:149], 0, s[20:21]
	global_store_dwordx4 v[56:57], v[52:55], off sc1
	s_waitcnt lgkmcnt(0)
	v_add_f32_e32 v50, v50, v51
	ds_bpermute_b32 v51, v124, v50
	s_and_saveexec_b64 s[20:21], s[6:7]
	s_cbranch_execz .LBB0_1237
	s_waitcnt lgkmcnt(0)
	v_add_f32_e32 v52, v50, v51
	v_lshl_add_u64 v[50:51], s[18:19], 2, v[122:123]
	s_lshl_b32 s96, s37, 2
	v_lshl_add_u64 v[50:51], v[50:51], 0, s[96:97]
	v_add_co_u32_e32 v50, vcc, 0x4000, v50
	s_nop 1
	v_addc_co_u32_e32 v51, vcc, 0, v51, vcc
	global_store_dword v[50:51], v52, off sc1
.LBB0_1237:
	s_or_b64 exec, exec, s[20:21]
	v_add_co_u32_e32 v50, vcc, s59, v148
	s_waitcnt vmcnt(3)
	v_lshlrev_b32_e32 v60, 16, v70
	s_waitcnt lgkmcnt(0)
	v_addc_co_u32_e32 v51, vcc, 0, v149, vcc
	global_load_dwordx4 v[54:57], v[50:51], off
	s_nop 0
	global_load_dwordx4 v[50:53], v[50:51], off offset:256
	v_and_b32_e32 v61, 0xffff0000, v70
	v_lshlrev_b32_e32 v62, 16, v71
	v_and_b32_e32 v63, 0xffff0000, v71
	v_lshlrev_b32_e32 v64, 16, v72
	v_and_b32_e32 v65, 0xffff0000, v72
	v_lshlrev_b32_e32 v70, 16, v73
	v_and_b32_e32 v71, 0xffff0000, v73
	v_lshl_add_u64 v[58:59], v[148:149], 0, s[68:69]
	v_pk_fma_f32 v[48:49], v[48:49], 0.5, v[62:63] op_sel_hi:[1,0,1]
	v_pk_fma_f32 v[46:47], v[46:47], 0.5, v[60:61] op_sel_hi:[1,0,1]
	v_pk_fma_f32 v[60:61], v[44:45], 0.5, v[70:71] op_sel_hi:[1,0,1]
	v_pk_fma_f32 v[44:45], v[42:43], 0.5, v[64:65] op_sel_hi:[1,0,1]
	v_cvt_pk_bf16_f32 v42, v46, v47
	v_cvt_pk_bf16_f32 v43, v48, v49
	s_waitcnt vmcnt(4)
	v_lshlrev_b32_e32 v72, 16, v66
	v_cvt_pk_bf16_f32 v44, v44, v45
	v_cvt_pk_bf16_f32 v45, v60, v61
	global_store_dwordx4 v[58:59], v[42:45], off sc1
	v_lshlrev_b32_e32 v46, 16, v42
	v_lshlrev_b32_e32 v47, 16, v43
	v_and_b32_e32 v42, 0xffff0000, v42
	v_and_b32_e32 v43, 0xffff0000, v43
	v_mul_f32_e32 v42, v42, v42
	v_mul_f32_e32 v43, v43, v43
	v_lshlrev_b32_e32 v48, 16, v44
	v_and_b32_e32 v44, 0xffff0000, v44
	v_lshlrev_b32_e32 v49, 16, v45
	v_and_b32_e32 v45, 0xffff0000, v45
	v_fmac_f32_e32 v42, v46, v46
	v_fmac_f32_e32 v43, v47, v47
	v_add_f32_e32 v42, v42, v43
	v_mul_f32_e32 v43, v44, v44
	v_mul_f32_e32 v44, v45, v45
	v_and_b32_e32 v73, 0xffff0000, v66
	v_lshlrev_b32_e32 v74, 16, v68
	v_and_b32_e32 v75, 0xffff0000, v68
	v_fmac_f32_e32 v43, v48, v48
	v_fmac_f32_e32 v44, v49, v49
	v_lshlrev_b32_e32 v66, 16, v67
	v_and_b32_e32 v67, 0xffff0000, v67
	v_lshlrev_b32_e32 v68, 16, v69
	v_and_b32_e32 v69, 0xffff0000, v69
	v_add_f32_e32 v43, v43, v44
	v_pk_fma_f32 v[38:39], v[38:39], 0.5, v[72:73] op_sel_hi:[1,0,1]
	v_pk_fma_f32 v[34:35], v[34:35], 0.5, v[74:75] op_sel_hi:[1,0,1]
	v_add_f32_e32 v44, v42, v43
	v_pk_fma_f32 v[40:41], v[40:41], 0.5, v[66:67] op_sel_hi:[1,0,1]
	v_pk_fma_f32 v[42:43], v[36:37], 0.5, v[68:69] op_sel_hi:[1,0,1]
	v_cvt_pk_bf16_f32 v36, v38, v39
	v_cvt_pk_bf16_f32 v37, v40, v41
	v_cvt_pk_bf16_f32 v38, v34, v35
	s_mov_b64 s[20:21], 0x90100
	v_and_b32_e32 v35, 0xffff0000, v36
	v_lshlrev_b32_e32 v34, 16, v36
	v_and_b32_e32 v41, 0xffff0000, v37
	v_mul_f32_e32 v35, v35, v35
	v_lshlrev_b32_e32 v40, 16, v37
	v_fmac_f32_e32 v35, v34, v34
	v_mul_f32_e32 v34, v41, v41
	v_cvt_pk_bf16_f32 v39, v42, v43
	v_and_b32_e32 v43, 0xffff0000, v38
	v_and_b32_e32 v46, 0xffff0000, v39
	v_fmac_f32_e32 v34, v40, v40
	v_lshlrev_b32_e32 v42, 16, v38
	v_lshlrev_b32_e32 v45, 16, v39
	v_add_f32_e32 v34, v35, v34
	v_mul_f32_e32 v35, v43, v43
	v_mul_f32_e32 v40, v46, v46
	v_fmac_f32_e32 v35, v42, v42
	v_fmac_f32_e32 v40, v45, v45
	v_add_f32_e32 v35, v35, v40
	v_add_f32_e32 v34, v34, v35
	v_add_f32_e32 v34, v44, v34
	ds_bpermute_b32 v35, v153, v34
	v_lshl_add_u64 v[40:41], v[148:149], 0, s[20:21]
	global_store_dwordx4 v[40:41], v[36:39], off sc1
	s_waitcnt lgkmcnt(0)
	v_add_f32_e32 v34, v34, v35
	ds_bpermute_b32 v35, v124, v34
	s_and_saveexec_b64 s[20:21], s[6:7]
	s_cbranch_execz .LBB0_1239
	s_waitcnt lgkmcnt(0)
	v_add_f32_e32 v36, v34, v35
	v_lshl_add_u64 v[34:35], s[18:19], 2, v[122:123]
	s_lshl_b32 s96, s37, 2
	v_lshl_add_u64 v[34:35], v[34:35], 0, s[96:97]
	v_add_co_u32_e32 v34, vcc, 0x4000, v34
	s_nop 1
	v_addc_co_u32_e32 v35, vcc, 0, v35, vcc
	global_store_dword v[34:35], v36, off offset:2048 sc1
;     __device__ __forceinline__ void operator()(const f32x4 (&acc)[2][2][4][2], const pg8::Unit& u, int wr, int wc, int fr_, int fq_, int tid) {
;     ...
;         for (int g = 0; g < 8; ++g) {
;             const int ai = g >> 2, m = g & 3;
;             if (g < 7) ER_LD(nxt, g + 1);
;             const size_t off = base + (size_t)(ai * 128 + m * 16) * DM; float s = 0.f;
; #pragma unroll
;             for (int bj = 0; bj < 2; ++bj) {
;                 const f32x4 n0 = cur[2 * bj] + acc[ai][bj][m][0] * alpha, n1 = cur[2 * bj + 1] + acc[ai][bj][m][1] * alpha;
;                 const u32x4 w = pack8bf(n0, n1);
;                 *(u32x4*)(xb + off + bj * 128) = w;
;                 float q[8]; unpack8(w, q);
;                 s += ((q[0] * q[0] + q[1] * q[1]) + (q[2] * q[2] + q[3] * q[3])) + ((q[4] * q[4] + q[5] * q[5]) + (q[6] * q[6] + q[7] * q[7]));
;             }
;             s += __shfl_xor(s, 16); s += __shfl_xor(s, 32);
;             if (fq == 0) ssq[(size_t)(row0 + ai * 128 + m * 16) * 32 + u.pn * 4 + wc] = s;
; #pragma unroll
;             for (int j = 0; j < 4; ++j) cur[j] = nxt[j];
.LBB0_1239:
	s_or_b64 exec, exec, s[20:21]
	v_add_co_u32_e32 v34, vcc, s60, v148
	s_waitcnt vmcnt(3)
	v_lshlrev_b32_e32 v44, 16, v54
	s_waitcnt lgkmcnt(0)
	v_addc_co_u32_e32 v35, vcc, 0, v149, vcc
	global_load_dwordx4 v[38:41], v[34:35], off
	s_nop 0
	global_load_dwordx4 v[34:37], v[34:35], off offset:256
	v_and_b32_e32 v45, 0xffff0000, v54
	v_lshlrev_b32_e32 v46, 16, v55
	v_and_b32_e32 v47, 0xffff0000, v55
	v_lshlrev_b32_e32 v48, 16, v56
	v_and_b32_e32 v49, 0xffff0000, v56
	v_lshlrev_b32_e32 v54, 16, v57
	v_and_b32_e32 v55, 0xffff0000, v57
	v_lshl_add_u64 v[42:43], v[148:149], 0, s[70:71]
	v_pk_fma_f32 v[32:33], v[32:33], 0.5, v[46:47] op_sel_hi:[1,0,1]
	v_pk_fma_f32 v[30:31], v[30:31], 0.5, v[44:45] op_sel_hi:[1,0,1]
	v_pk_fma_f32 v[44:45], v[28:29], 0.5, v[54:55] op_sel_hi:[1,0,1]
	v_pk_fma_f32 v[28:29], v[26:27], 0.5, v[48:49] op_sel_hi:[1,0,1]
	v_cvt_pk_bf16_f32 v26, v30, v31
	v_cvt_pk_bf16_f32 v27, v32, v33
	s_waitcnt vmcnt(4)
	v_lshlrev_b32_e32 v56, 16, v50
	v_cvt_pk_bf16_f32 v28, v28, v29
	v_cvt_pk_bf16_f32 v29, v44, v45
	global_store_dwordx4 v[42:43], v[26:29], off sc1
	v_lshlrev_b32_e32 v30, 16, v26
	v_lshlrev_b32_e32 v31, 16, v27
	v_and_b32_e32 v26, 0xffff0000, v26
	v_and_b32_e32 v27, 0xffff0000, v27
	v_mul_f32_e32 v26, v26, v26
	v_mul_f32_e32 v27, v27, v27
	v_lshlrev_b32_e32 v32, 16, v28
	v_and_b32_e32 v28, 0xffff0000, v28
	v_lshlrev_b32_e32 v33, 16, v29
	v_and_b32_e32 v29, 0xffff0000, v29
	v_fmac_f32_e32 v26, v30, v30
	v_fmac_f32_e32 v27, v31, v31
	v_add_f32_e32 v26, v26, v27
	v_mul_f32_e32 v27, v28, v28
	v_mul_f32_e32 v28, v29, v29
	v_and_b32_e32 v57, 0xffff0000, v50
	v_lshlrev_b32_e32 v58, 16, v52
	v_and_b32_e32 v59, 0xffff0000, v52
	v_fmac_f32_e32 v27, v32, v32
	v_fmac_f32_e32 v28, v33, v33
	v_lshlrev_b32_e32 v50, 16, v51
	v_and_b32_e32 v51, 0xffff0000, v51
	v_lshlrev_b32_e32 v52, 16, v53
	v_and_b32_e32 v53, 0xffff0000, v53
	v_add_f32_e32 v27, v27, v28
	v_pk_fma_f32 v[22:23], v[22:23], 0.5, v[56:57] op_sel_hi:[1,0,1]
	v_pk_fma_f32 v[18:19], v[18:19], 0.5, v[58:59] op_sel_hi:[1,0,1]
	v_add_f32_e32 v28, v26, v27
	v_pk_fma_f32 v[24:25], v[24:25], 0.5, v[50:51] op_sel_hi:[1,0,1]
	v_pk_fma_f32 v[26:27], v[20:21], 0.5, v[52:53] op_sel_hi:[1,0,1]
	v_cvt_pk_bf16_f32 v20, v22, v23
	v_cvt_pk_bf16_f32 v21, v24, v25
	v_cvt_pk_bf16_f32 v22, v18, v19
	s_mov_b64 s[20:21], 0xa0100
	v_and_b32_e32 v19, 0xffff0000, v20
	v_lshlrev_b32_e32 v18, 16, v20
	v_and_b32_e32 v25, 0xffff0000, v21
	v_mul_f32_e32 v19, v19, v19
	v_lshlrev_b32_e32 v24, 16, v21
	v_fmac_f32_e32 v19, v18, v18
	v_mul_f32_e32 v18, v25, v25
	v_cvt_pk_bf16_f32 v23, v26, v27
	v_and_b32_e32 v27, 0xffff0000, v22
	v_and_b32_e32 v30, 0xffff0000, v23
	v_fmac_f32_e32 v18, v24, v24
	v_lshlrev_b32_e32 v26, 16, v22
	v_lshlrev_b32_e32 v29, 16, v23
	v_add_f32_e32 v18, v19, v18
	v_mul_f32_e32 v19, v27, v27
	v_mul_f32_e32 v24, v30, v30
	v_fmac_f32_e32 v19, v26, v26
	v_fmac_f32_e32 v24, v29, v29
	v_add_f32_e32 v19, v19, v24
	v_add_f32_e32 v18, v18, v19
	v_add_f32_e32 v18, v28, v18
	ds_bpermute_b32 v19, v153, v18
	v_lshl_add_u64 v[24:25], v[148:149], 0, s[20:21]
	global_store_dwordx4 v[24:25], v[20:23], off sc1
	s_waitcnt lgkmcnt(0)
	v_add_f32_e32 v18, v18, v19
	ds_bpermute_b32 v19, v124, v18
	s_and_saveexec_b64 s[20:21], s[6:7]
	s_cbranch_execz .LBB0_1241
	s_waitcnt lgkmcnt(0)
	v_add_f32_e32 v20, v18, v19
	v_lshl_add_u64 v[18:19], s[18:19], 2, v[122:123]
	s_lshl_b32 s96, s37, 2
	v_lshl_add_u64 v[18:19], v[18:19], 0, s[96:97]
	v_add_co_u32_e32 v18, vcc, 0x5000, v18
	s_nop 1
	v_addc_co_u32_e32 v19, vcc, 0, v19, vcc
	global_store_dword v[18:19], v20, off sc1
.LBB0_1241:
	s_or_b64 exec, exec, s[20:21]
	s_waitcnt vmcnt(3)
	v_lshlrev_b32_e32 v20, 16, v38
	v_and_b32_e32 v21, 0xffff0000, v38
	v_lshlrev_b32_e32 v22, 16, v39
	v_and_b32_e32 v23, 0xffff0000, v39
	v_lshlrev_b32_e32 v24, 16, v40
	v_and_b32_e32 v25, 0xffff0000, v40
	v_lshlrev_b32_e32 v26, 16, v41
	v_and_b32_e32 v27, 0xffff0000, v41
	s_waitcnt lgkmcnt(0)
	v_lshl_add_u64 v[18:19], v[148:149], 0, s[72:73]
	v_pk_fma_f32 v[16:17], v[16:17], 0.5, v[22:23] op_sel_hi:[1,0,1]
	v_pk_fma_f32 v[14:15], v[14:15], 0.5, v[20:21] op_sel_hi:[1,0,1]
	v_pk_fma_f32 v[20:21], v[12:13], 0.5, v[26:27] op_sel_hi:[1,0,1]
	v_pk_fma_f32 v[12:13], v[10:11], 0.5, v[24:25] op_sel_hi:[1,0,1]
	v_cvt_pk_bf16_f32 v10, v14, v15
	v_cvt_pk_bf16_f32 v11, v16, v17
	s_waitcnt vmcnt(2)
	v_lshlrev_b32_e32 v28, 16, v34
	v_cvt_pk_bf16_f32 v12, v12, v13
	v_cvt_pk_bf16_f32 v13, v20, v21
	global_store_dwordx4 v[18:19], v[10:13], off sc1
	v_lshlrev_b32_e32 v14, 16, v10
	v_lshlrev_b32_e32 v15, 16, v11
	v_and_b32_e32 v10, 0xffff0000, v10
	v_and_b32_e32 v11, 0xffff0000, v11
	v_mul_f32_e32 v10, v10, v10
	v_mul_f32_e32 v11, v11, v11
	v_lshlrev_b32_e32 v16, 16, v12
	v_and_b32_e32 v12, 0xffff0000, v12
	v_lshlrev_b32_e32 v17, 16, v13
	v_and_b32_e32 v13, 0xffff0000, v13
	v_fmac_f32_e32 v10, v14, v14
	v_fmac_f32_e32 v11, v15, v15
	v_add_f32_e32 v10, v10, v11
	v_mul_f32_e32 v11, v12, v12
	v_mul_f32_e32 v12, v13, v13
	v_and_b32_e32 v29, 0xffff0000, v34
	v_lshlrev_b32_e32 v32, 16, v36
	v_and_b32_e32 v33, 0xffff0000, v36
	v_fmac_f32_e32 v11, v16, v16
	v_fmac_f32_e32 v12, v17, v17
	v_lshlrev_b32_e32 v30, 16, v35
	v_and_b32_e32 v31, 0xffff0000, v35
	v_lshlrev_b32_e32 v34, 16, v37
	v_and_b32_e32 v35, 0xffff0000, v37
	v_add_f32_e32 v11, v11, v12
	v_pk_fma_f32 v[6:7], v[6:7], 0.5, v[28:29] op_sel_hi:[1,0,1]
	v_pk_fma_f32 v[2:3], v[2:3], 0.5, v[32:33] op_sel_hi:[1,0,1]
	v_add_f32_e32 v12, v10, v11
	v_pk_fma_f32 v[8:9], v[8:9], 0.5, v[30:31] op_sel_hi:[1,0,1]
	v_pk_fma_f32 v[10:11], v[4:5], 0.5, v[34:35] op_sel_hi:[1,0,1]
	v_cvt_pk_bf16_f32 v4, v6, v7
	v_cvt_pk_bf16_f32 v5, v8, v9
	v_cvt_pk_bf16_f32 v6, v2, v3
	s_mov_b64 s[20:21], 0xb0100
	v_and_b32_e32 v3, 0xffff0000, v4
	v_lshlrev_b32_e32 v2, 16, v4
	v_and_b32_e32 v9, 0xffff0000, v5
	v_mul_f32_e32 v3, v3, v3
	v_lshlrev_b32_e32 v8, 16, v5
	v_fmac_f32_e32 v3, v2, v2
	v_mul_f32_e32 v2, v9, v9
	v_cvt_pk_bf16_f32 v7, v10, v11
	v_and_b32_e32 v11, 0xffff0000, v6
	v_and_b32_e32 v14, 0xffff0000, v7
	v_fmac_f32_e32 v2, v8, v8
	v_lshlrev_b32_e32 v10, 16, v6
	v_lshlrev_b32_e32 v13, 16, v7
	v_add_f32_e32 v2, v3, v2
	v_mul_f32_e32 v3, v11, v11
	v_mul_f32_e32 v8, v14, v14
	v_fmac_f32_e32 v3, v10, v10
	v_fmac_f32_e32 v8, v13, v13
	v_add_f32_e32 v3, v3, v8
	v_add_f32_e32 v2, v2, v3
	v_add_f32_e32 v2, v12, v2
	ds_bpermute_b32 v3, v153, v2
	v_lshl_add_u64 v[8:9], v[148:149], 0, s[20:21]
	global_store_dwordx4 v[8:9], v[4:7], off sc1
	s_waitcnt lgkmcnt(0)
	v_add_f32_e32 v2, v2, v3
	ds_bpermute_b32 v3, v124, v2
	s_and_saveexec_b64 s[20:21], s[6:7]
	s_cbranch_execz .LBB0_1243
	s_waitcnt lgkmcnt(0)
	v_add_f32_e32 v4, v2, v3
	v_lshl_add_u64 v[2:3], s[18:19], 2, v[122:123]
	s_lshl_b32 s96, s37, 2
	v_lshl_add_u64 v[2:3], v[2:3], 0, s[96:97]
	v_add_co_u32_e32 v2, vcc, 0x5000, v2
	s_nop 1
	v_addc_co_u32_e32 v3, vcc, 0, v3, vcc
	global_store_dword v[2:3], v4, off offset:2048 sc1
